# static priority raise: one s_setprio 1 before the step loop for workgroups >= 256 (second resident per CU), all other s_setprio replaced by s_nop 0
# baseline (speedup 1.0000x reference)
; #define LAS __attribute__((address_space(3)))
; __global__ void __launch_bounds__(256, 2) mega_kernel(Params p) {
;   __shared__ __attribute__((aligned(16))) char smem[SMEM_BYTES];
;   __shared__ uint4 xb_words;
;   cg::grid_group grid = cg::this_grid();
;   if (threadIdx.x == 0) xb_words = make_uint4(0u, 0u, 0u, 0u);
;   __syncthreads();
;   const XcdBarrier xb = xcd_barrier_post((unsigned*)(p.ws + OFF_BAR), (volatile LAS unsigned*)&xb_words);
;   phase_prep(p, smem);
;   grid.sync();
; #pragma unroll 1
;   for (int step = 0; step < 2 + NCHUNK * 17; ++step) {
.LBB1_178:
	s_or_b64 exec, exec, s[0:1]
	s_mul_i32 s0, s79, s78
	s_lshl_b32 s56, s78, 2
	s_lshl_b32 s57, s78, 8
	s_mul_i32 s58, s0, s3
	s_add_u32 s0, s76, 0x1c140200
	s_addc_u32 s1, s77, 0
	v_writelane_b32 v254, s0, 34
	v_exp_f32_e32 v173, 0xbf549a78
	v_exp_f32_e32 v252, 0xbfd49a78
	v_writelane_b32 v254, s1, 35
	s_add_u32 s0, s76, 0x1c140400
	s_addc_u32 s1, s77, 0
	v_writelane_b32 v254, s0, 36
	v_exp_f32_e32 v253, 0xc01f73da
	v_exp_f32_e32 v192, 0xc0549a78
	v_writelane_b32 v254, s1, 37
	s_add_u32 s0, s76, 0x1c140500
	s_addc_u32 s1, s77, 0
	v_writelane_b32 v254, s0, 38
	v_exp_f32_e32 v195, 0xc084e08b
	v_exp_f32_e32 v178, 0xc09f73da
	v_writelane_b32 v254, s1, 39
	s_add_u32 s0, s76, 0x1c140600
	s_addc_u32 s1, s77, 0
	v_writelane_b32 v254, s0, 40
	v_exp_f32_e32 v179, 0xc0ba0729
	v_exp_f32_e32 v180, 0xc0d49a78
	v_writelane_b32 v254, s1, 41
	s_add_u32 s0, s76, 0x1c140700
	s_addc_u32 s1, s77, 0
	v_writelane_b32 v254, s0, 42
	v_exp_f32_e32 v181, 0xc0ef2dc7
	v_exp_f32_e32 v182, 0xc104e08b
	v_writelane_b32 v254, s1, 43
	s_add_u32 s0, s76, 0x1c140800
	s_addc_u32 s1, s77, 0
	s_add_u32 s62, s76, 0x1c140900
	s_addc_u32 s63, s77, 0
	s_add_u32 s64, s76, 0x1c140a00
	s_addc_u32 s65, s77, 0
	s_add_u32 s66, s76, 0x1c140b00
	s_addc_u32 s67, s77, 0
	s_add_u32 s68, s76, 0x1c140c00
	s_addc_u32 s69, s77, 0
	s_add_u32 s70, s76, 0x1c140d00
	s_addc_u32 s71, s77, 0
	s_add_u32 s72, s76, 0x1c140e00
	s_addc_u32 s73, s77, 0
	s_add_u32 s80, s76, 0x1c140f00
	s_addc_u32 s81, s77, 0
	s_add_u32 s82, s76, 0x1c141000
	s_addc_u32 s83, s77, 0
	s_add_u32 s84, s76, 0x1c141100
	s_addc_u32 s85, s77, 0
	s_add_u32 s86, s76, 0x1c141200
	s_addc_u32 s87, s77, 0
	s_add_u32 s88, s76, 0x1c141300
	s_addc_u32 s89, s77, 0
	v_writelane_b32 v254, s0, 44
	s_cmp_eq_u32 s2, 15
	v_exp_f32_e32 v183, 0xc1122a32
	v_writelane_b32 v254, s1, 45
	s_cselect_b64 s[0:1], -1, 0
	v_writelane_b32 v254, s0, 46
	s_cmp_eq_u32 s2, 14
	v_exp_f32_e32 v184, 0xc11f73da
	v_writelane_b32 v254, s1, 47
	s_cselect_b64 s[0:1], -1, 0
	v_writelane_b32 v254, s0, 48
	s_cmp_eq_u32 s2, 13
	v_exp_f32_e32 v185, 0xc12cbd82
	v_writelane_b32 v254, s1, 49
	s_cselect_b64 s[0:1], -1, 0
	v_writelane_b32 v254, s0, 50
	s_cmp_eq_u32 s2, 12
	v_exp_f32_e32 v186, 0xc13a0729
	v_writelane_b32 v254, s1, 51
	s_cselect_b64 s[0:1], -1, 0
	v_writelane_b32 v254, s0, 52
	s_cmp_eq_u32 s2, 11
	v_exp_f32_e32 v187, 0xc14750d0
	v_writelane_b32 v254, s1, 53
	s_cselect_b64 s[0:1], -1, 0
	v_writelane_b32 v254, s0, 54
	s_cmp_eq_u32 s2, 10
	v_mbcnt_lo_u32_b32 v0, -1, 0
	v_writelane_b32 v254, s1, 55
	s_cselect_b64 s[0:1], -1, 0
	v_writelane_b32 v254, s0, 56
	s_cmp_eq_u32 s2, 9
	v_mbcnt_hi_u32_b32 v193, -1, v0
	v_writelane_b32 v254, s1, 57
	s_cselect_b64 s[0:1], -1, 0
	v_writelane_b32 v254, s0, 58
	s_cmp_eq_u32 s2, 8
	v_and_b32_e32 v0, 64, v193
	v_writelane_b32 v254, s1, 59
	s_cselect_b64 s[0:1], -1, 0
	v_writelane_b32 v254, s0, 60
	s_cmp_eq_u32 s2, 7
	v_mov_b32_e32 v1, 0
	v_writelane_b32 v254, s1, 61
	s_cselect_b64 s[0:1], -1, 0
	v_writelane_b32 v254, s0, 62
	s_cmp_eq_u32 s2, 6
	s_movk_i32 s91, 0x48
	v_writelane_b32 v254, s1, 63
	s_cselect_b64 s[0:1], -1, 0
	v_writelane_b32 v255, s0, 0
	s_cmp_eq_u32 s2, 5
	s_mov_b32 s90, 0xfffffc0
	v_writelane_b32 v255, s1, 1
	s_cselect_b64 s[0:1], -1, 0
	v_writelane_b32 v255, s0, 2
	s_cmp_eq_u32 s2, 4
	s_movk_i32 s4, 0x90
	v_writelane_b32 v255, s1, 3
	s_cselect_b64 s[0:1], -1, 0
	v_writelane_b32 v255, s0, 4
	s_cmp_eq_u32 s2, 3
	s_movk_i32 s5, 0x210
	v_writelane_b32 v255, s1, 5
	s_cselect_b64 s[0:1], -1, 0
	v_writelane_b32 v255, s0, 6
	s_cmp_eq_u32 s2, 2
	s_movk_i32 s60, 0xf800
	v_writelane_b32 v255, s1, 7
	s_cselect_b64 s[0:1], -1, 0
	v_writelane_b32 v255, s0, 8
	s_cmp_eq_u32 s2, 1
	v_mov_b32_e32 v188, 0x358637bd
	v_writelane_b32 v255, s1, 9
	s_cselect_b64 s[0:1], -1, 0
	v_writelane_b32 v255, s0, 10
	s_cmp_eq_u32 s2, 0
	v_mov_b32_e32 v189, 0x12200
	v_writelane_b32 v255, s1, 11
	s_cselect_b64 s[0:1], -1, 0
	v_writelane_b32 v255, s0, 12
	v_mov_b32_e32 v190, 0x12204
	v_mov_b32_e32 v191, 1
	v_writelane_b32 v255, s1, 13
	s_lshl_b32 s0, s2, 8
	s_add_u32 s0, s20, s0
	s_addc_u32 s1, s21, 0
	s_add_u32 s2, s0, 0x1400
	s_addc_u32 s3, s1, 0
	v_writelane_b32 v255, s2, 14
	s_add_u32 s0, s0, 0x2400
	s_addc_u32 s1, s1, 0
	v_writelane_b32 v255, s3, 15
	v_writelane_b32 v255, s0, 16
	v_add_u32_e32 v194, 64, v0
	v_xor_b32_e32 v196, 16, v193
	v_writelane_b32 v255, s1, 17
	s_add_u32 s0, s76, 0x1c143400
	s_addc_u32 s1, s77, 0
	v_writelane_b32 v255, s0, 18
	v_xor_b32_e32 v197, 8, v193
	v_xor_b32_e32 v198, 4, v193
	v_writelane_b32 v255, s1, 19
	s_add_u32 s0, s76, 0x1c143500
	s_addc_u32 s1, s77, 0
	v_writelane_b32 v255, s0, 20
	s_lshl_b32 s59, s78, 17
	s_lshl_b32 s95, s78, 7
	v_writelane_b32 v255, s1, 21
	s_lshl_b32 s0, s78, 19
	v_writelane_b32 v255, s0, 22
	v_writelane_b32 v255, s92, 23
	v_writelane_b32 v255, s56, 24
	v_writelane_b32 v255, s57, 25
	v_writelane_b32 v255, s58, 26
	v_xor_b32_e32 v199, 2, v193
	v_xor_b32_e32 v200, 1, v193
	v_mov_b32_e32 v201, 0x12000
	v_mov_b32_e32 v202, 0xff800000
	v_mov_b32_e32 v203, 0xc0
	v_mov_b32_e32 v204, 0x12080
	v_mov_b32_e32 v205, 0x12100
	v_mov_b32_e32 v206, 0x12180
	v_mov_b32_e32 v207, 0x3e0293ee
	s_mov_b32 s38, 0x20000
	s_mov_b32 s39, 0x800000
	s_mov_b32 s96, 0x19140000
	s_mov_b32 s97, 0x2980000
	s_movk_i32 s3, 0x110
	s_mov_b32 s7, 0xff800000
	s_movk_i32 s33, 0x41
	s_mov_b32 s6, -1
	s_mov_b32 s1, 0
	s_mov_b64 s[8:9], 0x80
	s_mov_b64 s[10:11], 0x18000
	v_writelane_b32 v255, s59, 27
	s_cmp_ge_u32 s92, 0x100
	s_cbranch_scc0 .Lprio_done
	s_setprio 1
.Lprio_done:
	s_barrier
	s_branch .LBB1_181

; DI int TID() { int t = (int)__builtin_amdgcn_workitem_id_x(); asm volatile("" : "+v"(t)); return t; }
; #define BLOAD(A_, B_, kt) do { _Pragma("unroll") for (int i = 0; i < 4; ++i) { \
;     A_[i] = *(const u32x4*)((const char*)Ap + (aoff + (unsigned)(32 * i * lda + (kt) * 64) * 2u)); B_[i] = *(const u32x4*)((const char*)Wt + (woff + (unsigned)(32 * i * K + (kt) * 64) * 2u)); } } while (0)
; #define BLOAD(A_, B_, kt) do { _Pragma("unroll") for (int i = 0; i < 4; ++i) { \
;     A_[i] = *(const u32x4*)((const char*)Ap + (aoff + (unsigned)(32 * i * lda + (kt) * 64) * 2u)); B_[i] = *(const u32x4*)((const char*)Wt + (woff + (unsigned)(32 * i * K + (kt) * 64) * 2u)); } } while (0)
; #define BSTORE(A_, B_, buf) do { _Pragma("unroll") for (int i = 0; i < 4; ++i) { \
;     *(u32x4*)&As[(buf) * GBUF + (srow + 32 * i) * LDT + sc8] = A_[i]; \
;     *(u32x4*)&Bs[(buf) * GBUF + (srow + 32 * i) * LDT + sc8] = B_[i]; } } while (0)
; template <int NK>
; DI void gemm_run(PF& pf, const u16* __restrict__ Ap, int lda, const u16* __restrict__ Wt, f32x16 (&acc)[2][2], char* smem) {
;   constexpr int K = NK * 64;
;   const int tid = TID(), lane = tid & 63, w = tid >> 6, wm = w >> 1, wn = w & 1, r32 = lane & 31, hi = lane >> 5;
;   u16* As = (u16*)smem; u16* Bs = As + 128 * LDT;
;   const int srow = tid >> 3, sc8 = (tid & 7) * 8;
;   constexpr int nk = NK;
;   const unsigned aoff = (unsigned)(srow * lda + sc8) * 2u, woff = (unsigned)(srow * K + sc8) * 2u;
;     ...
;   __builtin_amdgcn_s_setprio(0);
;   __syncthreads();
;   BSTORE(pf.a0, pf.b0, 0);
;   BLOAD(pf.a0, pf.b0, 2);
;   __syncthreads();
; DI void tile_ffn2(const Params& p, int l, const Chunk& ck, int tile, int next, PF& pf, char* smem) {
;   float* Cs = (float*)smem;
;   const int tid = TID(); const int mi = tile & (MTN - 1), ni = tile >> MTS; const int m0 = mi * 128, n0 = ni * 128;
;   f32x16 acc[2][2]; zero_acc(acc);
;   { const u16* Ap; const u16* Wt; ffn2_ptrs(p, l, tile, Ap, Wt); gemm_run<64>(pf, Ap, 4096, Wt, acc, smem); }
;   if (next >= 0) { const u16* An; const u16* Wn; ffn2_ptrs(p, l, next, An, Wn); gemm_issue(pf, An, 4096, Wn, 4096); }
;   acc_to_cs(acc, Cs);
.LBB1_206:
	s_add_i32 s25, s26, s78
	s_cmpk_gt_i32 s25, 0x1ff
	s_cselect_b64 s[28:29], -1, 0
	s_cmpk_lt_i32 s25, 0x200
	s_cselect_b32 s0, s25, -1
	s_and_b32 s16, s41, 0x3f80000
	s_and_b32 s36, s26, 0xffffff80
	s_add_i32 s26, s26, s36
	s_lshl_b32 s36, s36, 1
	s_lshl_b32 s16, s16, 1
	s_add_u32 vcc_lo, s17, s16
	v_mov_b32_e32 v0, v172
	s_addc_u32 vcc_hi, s27, 0
	s_ashr_i32 s37, s36, 31
	s_lshl_b64 s[30:31], s[36:37], 6
	s_add_u32 s30, s34, s30
	s_addc_u32 s31, s40, s31
	s_nop 0
	s_waitcnt lgkmcnt(0)
	s_lshr_b32 s16, s16, 7
	s_add_u32 s42, s17, s16
	s_addc_u32 s43, s27, 0
	v_and_b32_e32 v174, 63, v172
	v_lshrrev_b32_e32 v175, 6, v172
	v_bfe_u32 v176, v174, 4, 2
	v_lshrrev_b32_e32 v177, 1, v176
	v_xor_b32_e32 v176, v176, v177
	v_and_b32_e32 v176, 1, v176
	v_lshl_or_b32 v176, v176, 1, v177
	v_xor_b32_e32 v176, v176, v174
	v_and_b32_e32 v176, 3, v176
	v_lshlrev_b32_e32 v176, 4, v176
	v_lshrrev_b32_e32 v177, 2, v174
	v_lshl_add_u32 v137, v175, 5, v177
	v_lshl_add_u32 v137, v137, 6, v176
	v_mov_b32_e32 v150, v137
	v_lshl_add_u32 v151, v175, 6, v177
	v_lshl_add_u32 v151, v151, 6, v176
	v_mov_b32_e32 v152, v151
	v_mov_b32_e32 v153, v151
	v_mov_b32_e32 v154, v151
	v_readfirstlane_b32 s16, v175
	s_lshl_b32 s0, s16, 12
	s_lshl_b32 s16, s16, 11
	s_add_u32 s0, s0, 0x2000
	v_bfe_u32 v176, v174, 2, 2
	v_lshrrev_b32_e32 v177, 1, v176
	v_xor_b32_e32 v176, v176, v177
	v_and_b32_e32 v176, 1, v176
	v_lshl_or_b32 v176, v176, 1, v177
	v_lshrrev_b32_e32 v177, 4, v174
	v_xor_b32_e32 v176, v176, v177
	v_lshlrev_b32_e32 v176, 4, v176
	v_and_b32_e32 v174, 15, v174
	v_lshl_add_u32 v174, v174, 6, v176
	v_lshrrev_b32_e32 v176, 1, v175
	v_and_b32_e32 v177, 1, v175
	v_lshl_add_u32 v126, v176, 12, v174
	v_lshl_add_u32 v128, v177, 12, v174
	v_add_u32_e32 v128, 0x2000, v128
	s_barrier
	v_mov_b32_e32 v2, 0
	v_mov_b32_e32 v3, 0
	v_mov_b32_e32 v4, 0
	v_mov_b32_e32 v5, 0
	v_mov_b32_e32 v6, 0
	v_mov_b32_e32 v7, 0
	v_mov_b32_e32 v8, 0
	v_mov_b32_e32 v9, 0
	v_mov_b32_e32 v10, 0
	v_mov_b32_e32 v11, 0
	v_mov_b32_e32 v12, 0
	v_mov_b32_e32 v13, 0
	v_mov_b32_e32 v14, 0
	v_mov_b32_e32 v15, 0
	v_mov_b32_e32 v16, 0
	v_mov_b32_e32 v17, 0
	v_mov_b32_e32 v18, 0
	v_mov_b32_e32 v19, 0
	v_mov_b32_e32 v20, 0
	v_mov_b32_e32 v21, 0
	v_mov_b32_e32 v22, 0
	v_mov_b32_e32 v23, 0
	v_mov_b32_e32 v24, 0
	v_mov_b32_e32 v25, 0
	v_mov_b32_e32 v26, 0
	v_mov_b32_e32 v27, 0
	v_mov_b32_e32 v28, 0
	v_mov_b32_e32 v29, 0
	v_mov_b32_e32 v30, 0
	v_mov_b32_e32 v31, 0
	v_mov_b32_e32 v32, 0
	v_mov_b32_e32 v33, 0
	v_mov_b32_e32 v34, 0
	v_mov_b32_e32 v35, 0
	v_mov_b32_e32 v36, 0
	v_mov_b32_e32 v37, 0
	v_mov_b32_e32 v38, 0
	v_mov_b32_e32 v39, 0
	v_mov_b32_e32 v40, 0
	v_mov_b32_e32 v41, 0
	v_mov_b32_e32 v42, 0
	v_mov_b32_e32 v43, 0
	v_mov_b32_e32 v44, 0
	v_mov_b32_e32 v45, 0
	v_mov_b32_e32 v46, 0
	v_mov_b32_e32 v47, 0
	v_mov_b32_e32 v48, 0
	v_mov_b32_e32 v49, 0
	v_mov_b32_e32 v50, 0
	v_mov_b32_e32 v51, 0
	v_mov_b32_e32 v52, 0
	v_mov_b32_e32 v53, 0
	v_mov_b32_e32 v54, 0
	v_mov_b32_e32 v55, 0
	v_mov_b32_e32 v56, 0
	v_mov_b32_e32 v57, 0
	v_mov_b32_e32 v58, 0
	v_mov_b32_e32 v59, 0
	v_mov_b32_e32 v60, 0
	v_mov_b32_e32 v61, 0
	v_mov_b32_e32 v62, 0
	v_mov_b32_e32 v63, 0
	v_mov_b32_e32 v64, 0
	v_mov_b32_e32 v65, 0
	v_mov_b32_e32 v74, 0
	v_mov_b32_e32 v75, 0
	v_mov_b32_e32 v76, 0
	v_mov_b32_e32 v77, 0
	v_mov_b32_e32 v78, 0
	v_mov_b32_e32 v79, 0
	v_mov_b32_e32 v80, 0
	v_mov_b32_e32 v81, 0
	v_mov_b32_e32 v82, 0
	v_mov_b32_e32 v83, 0
	v_mov_b32_e32 v84, 0
	v_mov_b32_e32 v85, 0
	v_mov_b32_e32 v86, 0
	v_mov_b32_e32 v87, 0
	v_mov_b32_e32 v88, 0
	v_mov_b32_e32 v89, 0
	v_mov_b32_e32 v90, 0
	v_mov_b32_e32 v91, 0
	v_mov_b32_e32 v92, 0
	v_mov_b32_e32 v93, 0
	v_mov_b32_e32 v94, 0
	v_mov_b32_e32 v95, 0
	v_mov_b32_e32 v96, 0
	v_mov_b32_e32 v97, 0
	v_mov_b32_e32 v98, 0
	v_mov_b32_e32 v99, 0
	v_mov_b32_e32 v100, 0
	v_mov_b32_e32 v101, 0
	v_mov_b32_e32 v102, 0
	v_mov_b32_e32 v103, 0
	v_mov_b32_e32 v104, 0
	v_mov_b32_e32 v105, 0
	v_mov_b32_e32 v106, 0
	v_mov_b32_e32 v107, 0
	v_mov_b32_e32 v108, 0
	v_mov_b32_e32 v109, 0
	v_mov_b32_e32 v110, 0
	v_mov_b32_e32 v111, 0
	v_mov_b32_e32 v112, 0
	v_mov_b32_e32 v113, 0
	v_mov_b32_e32 v114, 0
	v_mov_b32_e32 v115, 0
	v_mov_b32_e32 v116, 0
	v_mov_b32_e32 v117, 0
	v_mov_b32_e32 v118, 0
	v_mov_b32_e32 v119, 0
	v_mov_b32_e32 v120, 0
	v_mov_b32_e32 v121, 0
	v_mov_b32_e32 v208, 0
	v_mov_b32_e32 v209, 0
	v_mov_b32_e32 v210, 0
	v_mov_b32_e32 v211, 0
	v_mov_b32_e32 v212, 0
	v_mov_b32_e32 v213, 0
	v_mov_b32_e32 v214, 0
	v_mov_b32_e32 v215, 0
	v_mov_b32_e32 v216, 0
	v_mov_b32_e32 v217, 0
	v_mov_b32_e32 v218, 0
	v_mov_b32_e32 v219, 0
	v_mov_b32_e32 v220, 0
	v_mov_b32_e32 v221, 0
	v_mov_b32_e32 v222, 0
	v_mov_b32_e32 v223, 0
	s_add_u32 m0, s16, 0x0
	s_nop 0
	global_load_lds_dwordx4 v137, s[42:43]
	global_load_lds_dwordx4 v150, s[42:43] offset:1024
	s_add_u32 m0, s0, 0x0
	s_nop 0
	global_load_lds_dwordx4 v151, s[30:31]
	global_load_lds_dwordx4 v152, s[30:31] offset:1024
	global_load_lds_dwordx4 v153, s[30:31] offset:2048
	global_load_lds_dwordx4 v154, s[30:31] offset:3072
	s_add_u32 m0, s16, 0x6000
	s_add_u32 s42, s42, 0x100000
	s_addc_u32 s43, s43, 0
	global_load_lds_dwordx4 v137, s[42:43]
	global_load_lds_dwordx4 v150, s[42:43] offset:1024
	s_add_u32 m0, s0, 0x6000
	s_add_u32 s30, s30, 0x10000
	s_addc_u32 s31, s31, 0
	global_load_lds_dwordx4 v151, s[30:31]
	global_load_lds_dwordx4 v152, s[30:31] offset:1024
	global_load_lds_dwordx4 v153, s[30:31] offset:2048
	global_load_lds_dwordx4 v154, s[30:31] offset:3072
	s_mov_b32 s46, 42

; DI int TID() { int t = (int)__builtin_amdgcn_workitem_id_x(); asm volatile("" : "+v"(t)); return t; }
; #define BLOAD(A_, B_, kt) do { _Pragma("unroll") for (int i = 0; i < 4; ++i) { \
;     A_[i] = *(const u32x4*)((const char*)Ap + (aoff + (unsigned)(32 * i * lda + (kt) * 64) * 2u)); B_[i] = *(const u32x4*)((const char*)Wt + (woff + (unsigned)(32 * i * K + (kt) * 64) * 2u)); } } while (0)
; DI RowSS rowss_load(const float* ps, int m0) { const int tid = TID(); const float* q = ps + (size_t)(m0 + (tid >> 1)) * 16 + (tid & 1) * 8; RowSS r; r.a = *(const f32x4*)q; r.b = *(const f32x4*)(q + 4); return r; }
; #define BLOAD(A_, B_, kt) do { _Pragma("unroll") for (int i = 0; i < 4; ++i) { \
;     A_[i] = *(const u32x4*)((const char*)Ap + (aoff + (unsigned)(32 * i * lda + (kt) * 64) * 2u)); B_[i] = *(const u32x4*)((const char*)Wt + (woff + (unsigned)(32 * i * K + (kt) * 64) * 2u)); } } while (0)
; template <int NK>
; DI void gemm_run(PF& pf, const u16* __restrict__ Ap, int lda, const u16* __restrict__ Wt, f32x16 (&acc)[2][2], char* smem) {
;   constexpr int K = NK * 64;
;   const int tid = TID(), lane = tid & 63, w = tid >> 6, wm = w >> 1, wn = w & 1, r32 = lane & 31, hi = lane >> 5;
;   u16* As = (u16*)smem; u16* Bs = As + 128 * LDT;
;   const int srow = tid >> 3, sc8 = (tid & 7) * 8;
;   constexpr int nk = NK;
;   const unsigned aoff = (unsigned)(srow * lda + sc8) * 2u, woff = (unsigned)(srow * K + sc8) * 2u;
;     ...
;   __builtin_amdgcn_s_setprio(0);
;   __syncthreads();
;   BSTORE(pf.a0, pf.b0, 0);
;   BLOAD(pf.a0, pf.b0, 2);
;   __syncthreads();
; DI void tile_ffn1(const Params& p, int l, const Chunk& ck, int tile, int next, PF& pf, char* smem) {
;   float* Cs = (float*)smem; float* rinv_s = (float*)(smem + SMEM_CS);
;   const int tid = TID(); const int mi = tile & (MTN - 1), ni = tile >> MTS; const int m0 = mi * 128, n0 = ni * 128;
;   f32x16 acc[2][2]; zero_acc(acc);
;   const RowSS rss = rowss_load((const float*)(p.ws + OFF_PSMID), m0);
;   { const u16* Ap; const u16* Wt; ffn1_ptrs(p, l, tile, Ap, Wt); gemm_run<16>(pf, Ap, 1024, Wt, acc, smem); }
;   if (next >= 0) { const u16* An; const u16* Wn; ffn1_ptrs(p, l, next, An, Wn); gemm_issue(pf, An, 1024, Wn, 1024); }
.LBB1_246:
	s_mov_b32 s26, s16
	s_add_i32 s16, s16, s78
	s_cmpk_gt_i32 s16, 0x7ff
	s_cselect_b64 s[24:25], -1, 0
	s_cmpk_lt_i32 s16, 0x800
	v_mov_b32_e32 v148, v172
	v_mov_b32_e32 v0, v172
	s_cselect_b32 s0, s16, -1
	s_and_b32 s41, s40, 0x3f80
	s_and_b32 s27, s35, 0xfe0000
	v_ashrrev_i32_e32 v2, 1, v0
	v_add_u32_e32 v2, s41, v2
	v_ashrrev_i32_e32 v3, 31, v2
	v_lshlrev_b64 v[2:3], 6, v[2:3]
	v_lshlrev_b32_e32 v0, 5, v0
	v_lshl_add_u64 v[2:3], s[20:21], 0, v[2:3]
	v_and_b32_e32 v0, 32, v0
	v_lshl_add_u64 v[2:3], v[2:3], 0, v[0:1]
	global_load_dwordx4 v[66:69], v[2:3], off offset:16
	global_load_dwordx4 v[70:73], v[2:3], off
	s_and_b32 s26, s26, 0xffffff80
	s_lshl_b32 s26, s26, 1
	s_lshr_b32 s27, s27, 4
	s_add_u32 s28, s17, s27
	s_addc_u32 s29, s34, 0
	s_ashr_i32 s27, s26, 31
	s_lshl_b64 s[30:31], s[26:27], 6
	s_add_u32 s30, s36, s30
	s_addc_u32 s31, s37, s31
	s_nop 0
	s_waitcnt lgkmcnt(0)
	s_mov_b32 s0, 0
	v_and_b32_e32 v149, 63, v172
	v_lshrrev_b32_e32 v151, 6, v172
	v_bfe_u32 v152, v149, 4, 2
	v_lshrrev_b32_e32 v153, 1, v152
	v_xor_b32_e32 v152, v152, v153
	v_and_b32_e32 v152, 1, v152
	v_lshl_or_b32 v152, v152, 1, v153
	v_xor_b32_e32 v152, v152, v149
	v_and_b32_e32 v152, 3, v152
	v_lshlrev_b32_e32 v152, 4, v152
	v_lshrrev_b32_e32 v153, 2, v149
	v_lshl_add_u32 v142, v151, 5, v153
	v_lshl_add_u32 v142, v142, 6, v152
	v_mov_b32_e32 v143, v142
	v_lshl_add_u32 v144, v151, 6, v153
	v_lshl_add_u32 v144, v144, 6, v152
	v_mov_b32_e32 v145, v144
	v_mov_b32_e32 v146, v144
	v_mov_b32_e32 v147, v144
	v_readfirstlane_b32 s42, v151
	s_lshl_b32 s43, s42, 12
	s_lshl_b32 s42, s42, 11
	s_add_u32 s43, s43, 0x2000
	v_bfe_u32 v152, v149, 2, 2
	v_lshrrev_b32_e32 v153, 1, v152
	v_xor_b32_e32 v152, v152, v153
	v_and_b32_e32 v152, 1, v152
	v_lshl_or_b32 v152, v152, 1, v153
	v_lshrrev_b32_e32 v153, 4, v149
	v_xor_b32_e32 v152, v152, v153
	v_lshlrev_b32_e32 v152, 4, v152
	v_and_b32_e32 v149, 15, v149
	v_lshl_add_u32 v149, v149, 6, v152
	v_lshrrev_b32_e32 v152, 1, v151
	v_and_b32_e32 v153, 1, v151
	v_lshl_add_u32 v138, v152, 12, v149
	v_lshl_add_u32 v140, v153, 12, v149
	v_add_u32_e32 v140, 0x2000, v140
	s_barrier
	v_mov_b32_e32 v2, 0
	v_mov_b32_e32 v3, 0
	v_mov_b32_e32 v4, 0
	v_mov_b32_e32 v5, 0
	v_mov_b32_e32 v6, 0
	v_mov_b32_e32 v7, 0
	v_mov_b32_e32 v8, 0
	v_mov_b32_e32 v9, 0
	v_mov_b32_e32 v10, 0
	v_mov_b32_e32 v11, 0
	v_mov_b32_e32 v12, 0
	v_mov_b32_e32 v13, 0
	v_mov_b32_e32 v14, 0
	v_mov_b32_e32 v15, 0
	v_mov_b32_e32 v16, 0
	v_mov_b32_e32 v17, 0
	v_mov_b32_e32 v18, 0
	v_mov_b32_e32 v19, 0
	v_mov_b32_e32 v20, 0
	v_mov_b32_e32 v21, 0
	v_mov_b32_e32 v22, 0
	v_mov_b32_e32 v23, 0
	v_mov_b32_e32 v24, 0
	v_mov_b32_e32 v25, 0
	v_mov_b32_e32 v26, 0
	v_mov_b32_e32 v27, 0
	v_mov_b32_e32 v28, 0
	v_mov_b32_e32 v29, 0
	v_mov_b32_e32 v30, 0
	v_mov_b32_e32 v31, 0
	v_mov_b32_e32 v32, 0
	v_mov_b32_e32 v33, 0
	v_mov_b32_e32 v34, 0
	v_mov_b32_e32 v35, 0
	v_mov_b32_e32 v36, 0
	v_mov_b32_e32 v37, 0
	v_mov_b32_e32 v38, 0
	v_mov_b32_e32 v39, 0
	v_mov_b32_e32 v40, 0
	v_mov_b32_e32 v41, 0
	v_mov_b32_e32 v42, 0
	v_mov_b32_e32 v43, 0
	v_mov_b32_e32 v44, 0
	v_mov_b32_e32 v45, 0
	v_mov_b32_e32 v46, 0
	v_mov_b32_e32 v47, 0
	v_mov_b32_e32 v48, 0
	v_mov_b32_e32 v49, 0
	v_mov_b32_e32 v50, 0
	v_mov_b32_e32 v51, 0
	v_mov_b32_e32 v52, 0
	v_mov_b32_e32 v53, 0
	v_mov_b32_e32 v54, 0
	v_mov_b32_e32 v55, 0
	v_mov_b32_e32 v56, 0
	v_mov_b32_e32 v57, 0
	v_mov_b32_e32 v58, 0
	v_mov_b32_e32 v59, 0
	v_mov_b32_e32 v60, 0
	v_mov_b32_e32 v61, 0
	v_mov_b32_e32 v62, 0
	v_mov_b32_e32 v63, 0
	v_mov_b32_e32 v64, 0
	v_mov_b32_e32 v65, 0
	v_mov_b32_e32 v74, 0
	v_mov_b32_e32 v75, 0
	v_mov_b32_e32 v76, 0
	v_mov_b32_e32 v77, 0
	v_mov_b32_e32 v78, 0
	v_mov_b32_e32 v79, 0
	v_mov_b32_e32 v80, 0
	v_mov_b32_e32 v81, 0
	v_mov_b32_e32 v82, 0
	v_mov_b32_e32 v83, 0
	v_mov_b32_e32 v84, 0
	v_mov_b32_e32 v85, 0
	v_mov_b32_e32 v86, 0
	v_mov_b32_e32 v87, 0
	v_mov_b32_e32 v88, 0
	v_mov_b32_e32 v89, 0
	v_mov_b32_e32 v90, 0
	v_mov_b32_e32 v91, 0
	v_mov_b32_e32 v92, 0
	v_mov_b32_e32 v93, 0
	v_mov_b32_e32 v94, 0
	v_mov_b32_e32 v95, 0
	v_mov_b32_e32 v96, 0
	v_mov_b32_e32 v97, 0
	v_mov_b32_e32 v98, 0
	v_mov_b32_e32 v99, 0
	v_mov_b32_e32 v100, 0
	v_mov_b32_e32 v101, 0
	v_mov_b32_e32 v102, 0
	v_mov_b32_e32 v103, 0
	v_mov_b32_e32 v104, 0
	v_mov_b32_e32 v105, 0
	v_mov_b32_e32 v106, 0
	v_mov_b32_e32 v107, 0
	v_mov_b32_e32 v108, 0
	v_mov_b32_e32 v109, 0
	v_mov_b32_e32 v110, 0
	v_mov_b32_e32 v111, 0
	v_mov_b32_e32 v112, 0
	v_mov_b32_e32 v113, 0
	v_mov_b32_e32 v114, 0
	v_mov_b32_e32 v115, 0
	v_mov_b32_e32 v116, 0
	v_mov_b32_e32 v117, 0
	v_mov_b32_e32 v118, 0
	v_mov_b32_e32 v119, 0
	v_mov_b32_e32 v120, 0
	v_mov_b32_e32 v121, 0
	v_mov_b32_e32 v122, 0
	v_mov_b32_e32 v123, 0
	v_mov_b32_e32 v124, 0
	v_mov_b32_e32 v125, 0
	v_mov_b32_e32 v126, 0
	v_mov_b32_e32 v127, 0
	v_mov_b32_e32 v128, 0
	v_mov_b32_e32 v129, 0
	v_mov_b32_e32 v130, 0
	v_mov_b32_e32 v131, 0
	v_mov_b32_e32 v132, 0
	v_mov_b32_e32 v133, 0
	v_mov_b32_e32 v134, 0
	v_mov_b32_e32 v135, 0
	v_mov_b32_e32 v136, 0
	v_mov_b32_e32 v137, 0
	s_add_u32 m0, s42, 0x0
	s_nop 0
	global_load_lds_dwordx4 v142, s[28:29]
	global_load_lds_dwordx4 v143, s[28:29] offset:1024
	s_add_u32 m0, s43, 0x0
	s_nop 0
	global_load_lds_dwordx4 v144, s[30:31]
	global_load_lds_dwordx4 v145, s[30:31] offset:1024
	global_load_lds_dwordx4 v146, s[30:31] offset:2048
	global_load_lds_dwordx4 v147, s[30:31] offset:3072
	s_add_u32 m0, s42, 0x6000
	s_add_u32 s28, s28, 0x100000
	s_addc_u32 s29, s29, 0
	global_load_lds_dwordx4 v142, s[28:29]
	global_load_lds_dwordx4 v143, s[28:29] offset:1024
	s_add_u32 m0, s43, 0x6000
	s_add_u32 s30, s30, 0x40000
	s_addc_u32 s31, s31, 0
	global_load_lds_dwordx4 v144, s[30:31]
	global_load_lds_dwordx4 v145, s[30:31] offset:1024
	global_load_lds_dwordx4 v146, s[30:31] offset:2048
	global_load_lds_dwordx4 v147, s[30:31] offset:3072
	s_mov_b32 s46, 10

; DI int TID() { int t = (int)__builtin_amdgcn_workitem_id_x(); asm volatile("" : "+v"(t)); return t; }
; #define BLOAD(A_, B_, kt) do { _Pragma("unroll") for (int i = 0; i < 4; ++i) { \
;     A_[i] = *(const u32x4*)((const char*)Ap + (aoff + (unsigned)(32 * i * lda + (kt) * 64) * 2u)); B_[i] = *(const u32x4*)((const char*)Wt + (woff + (unsigned)(32 * i * K + (kt) * 64) * 2u)); } } while (0)
; #define BLOAD(A_, B_, kt) do { _Pragma("unroll") for (int i = 0; i < 4; ++i) { \
;     A_[i] = *(const u32x4*)((const char*)Ap + (aoff + (unsigned)(32 * i * lda + (kt) * 64) * 2u)); B_[i] = *(const u32x4*)((const char*)Wt + (woff + (unsigned)(32 * i * K + (kt) * 64) * 2u)); } } while (0)
; #define BSTORE(A_, B_, buf) do { _Pragma("unroll") for (int i = 0; i < 4; ++i) { \
;     *(u32x4*)&As[(buf) * GBUF + (srow + 32 * i) * LDT + sc8] = A_[i]; \
;     *(u32x4*)&Bs[(buf) * GBUF + (srow + 32 * i) * LDT + sc8] = B_[i]; } } while (0)
; template <int NK>
; DI void gemm_run(PF& pf, const u16* __restrict__ Ap, int lda, const u16* __restrict__ Wt, f32x16 (&acc)[2][2], char* smem) {
;   constexpr int K = NK * 64;
;   const int tid = TID(), lane = tid & 63, w = tid >> 6, wm = w >> 1, wn = w & 1, r32 = lane & 31, hi = lane >> 5;
;   u16* As = (u16*)smem; u16* Bs = As + 128 * LDT;
;   const int srow = tid >> 3, sc8 = (tid & 7) * 8;
;   constexpr int nk = NK;
;   const unsigned aoff = (unsigned)(srow * lda + sc8) * 2u, woff = (unsigned)(srow * K + sc8) * 2u;
;     ...
;   __builtin_amdgcn_s_setprio(0);
;   __syncthreads();
;   BSTORE(pf.a0, pf.b0, 0);
;   BLOAD(pf.a0, pf.b0, 2);
;   __syncthreads();
; DI void tile_outproj(const Params& p, int l, const Chunk& ck, int tile, int next, PF& pf, char* smem) {
;   float* Cs = (float*)smem;
;   const int tid = TID(); const int mi = tile & (MTN - 1), ni = tile >> MTS; const int m0 = mi * 128, n0 = ni * 128;
;   f32x16 acc[2][2]; zero_acc(acc);
;   { const u16* Ap; const u16* Wt; outproj_ptrs(p, l, tile, Ap, Wt); gemm_run<16>(pf, Ap, 1024, Wt, acc, smem); }
;   if (next >= 0) { const u16* An; const u16* Wn; outproj_ptrs(p, l, next, An, Wn); gemm_issue(pf, An, 1024, Wn, 1024); }
;   acc_to_cs(acc, Cs);
.LBB1_255:
	s_add_i32 s41, s35, s78
	s_cmpk_gt_i32 s41, 0x1ff
	s_cselect_b64 s[24:25], -1, 0
	s_cmpk_lt_i32 s41, 0x200
	s_cselect_b32 s0, s41, -1
	s_and_b32 s27, s34, 0xfe0000
	s_and_b32 s26, s35, 0xffffff80
	s_lshl_b32 s26, s26, 1
	s_lshr_b32 s27, s27, 4
	s_add_u32 s28, s16, s27
	v_mov_b32_e32 v0, v172
	s_addc_u32 s29, s17, 0
	s_ashr_i32 s27, s26, 31
	s_lshl_b64 s[30:31], s[26:27], 6
	s_add_u32 s30, s36, s30
	s_addc_u32 s31, s37, s31
	s_nop 0
	s_waitcnt lgkmcnt(0)
	v_and_b32_e32 v150, 63, v172
	v_lshrrev_b32_e32 v151, 6, v172
	v_bfe_u32 v152, v150, 4, 2
	v_lshrrev_b32_e32 v153, 1, v152
	v_xor_b32_e32 v152, v152, v153
	v_and_b32_e32 v152, 1, v152
	v_lshl_or_b32 v152, v152, 1, v153
	v_xor_b32_e32 v152, v152, v150
	v_and_b32_e32 v152, 3, v152
	v_lshlrev_b32_e32 v152, 4, v152
	v_lshrrev_b32_e32 v153, 2, v150
	v_lshl_add_u32 v143, v151, 5, v153
	v_lshl_add_u32 v143, v143, 6, v152
	v_mov_b32_e32 v144, v143
	v_lshl_add_u32 v145, v151, 6, v153
	v_lshl_add_u32 v145, v145, 6, v152
	v_mov_b32_e32 v146, v145
	v_mov_b32_e32 v147, v145
	v_mov_b32_e32 v148, v145
	v_readfirstlane_b32 s42, v151
	s_lshl_b32 s43, s42, 12
	s_lshl_b32 s42, s42, 11
	s_add_u32 s43, s43, 0x2000
	v_bfe_u32 v152, v150, 2, 2
	v_lshrrev_b32_e32 v153, 1, v152
	v_xor_b32_e32 v152, v152, v153
	v_and_b32_e32 v152, 1, v152
	v_lshl_or_b32 v152, v152, 1, v153
	v_lshrrev_b32_e32 v153, 4, v150
	v_xor_b32_e32 v152, v152, v153
	v_lshlrev_b32_e32 v152, 4, v152
	v_and_b32_e32 v150, 15, v150
	v_lshl_add_u32 v150, v150, 6, v152
	v_lshrrev_b32_e32 v152, 1, v151
	v_and_b32_e32 v153, 1, v151
	v_lshl_add_u32 v126, v152, 12, v150
	v_lshl_add_u32 v128, v153, 12, v150
	v_add_u32_e32 v128, 0x2000, v128
	s_barrier
	v_mov_b32_e32 v2, 0
	v_mov_b32_e32 v3, 0
	v_mov_b32_e32 v4, 0
	v_mov_b32_e32 v5, 0
	v_mov_b32_e32 v6, 0
	v_mov_b32_e32 v7, 0
	v_mov_b32_e32 v8, 0
	v_mov_b32_e32 v9, 0
	v_mov_b32_e32 v10, 0
	v_mov_b32_e32 v11, 0
	v_mov_b32_e32 v12, 0
	v_mov_b32_e32 v13, 0
	v_mov_b32_e32 v14, 0
	v_mov_b32_e32 v15, 0
	v_mov_b32_e32 v16, 0
	v_mov_b32_e32 v17, 0
	v_mov_b32_e32 v18, 0
	v_mov_b32_e32 v19, 0
	v_mov_b32_e32 v20, 0
	v_mov_b32_e32 v21, 0
	v_mov_b32_e32 v22, 0
	v_mov_b32_e32 v23, 0
	v_mov_b32_e32 v24, 0
	v_mov_b32_e32 v25, 0
	v_mov_b32_e32 v26, 0
	v_mov_b32_e32 v27, 0
	v_mov_b32_e32 v28, 0
	v_mov_b32_e32 v29, 0
	v_mov_b32_e32 v30, 0
	v_mov_b32_e32 v31, 0
	v_mov_b32_e32 v32, 0
	v_mov_b32_e32 v33, 0
	v_mov_b32_e32 v34, 0
	v_mov_b32_e32 v35, 0
	v_mov_b32_e32 v36, 0
	v_mov_b32_e32 v37, 0
	v_mov_b32_e32 v38, 0
	v_mov_b32_e32 v39, 0
	v_mov_b32_e32 v40, 0
	v_mov_b32_e32 v41, 0
	v_mov_b32_e32 v42, 0
	v_mov_b32_e32 v43, 0
	v_mov_b32_e32 v44, 0
	v_mov_b32_e32 v45, 0
	v_mov_b32_e32 v46, 0
	v_mov_b32_e32 v47, 0
	v_mov_b32_e32 v48, 0
	v_mov_b32_e32 v49, 0
	v_mov_b32_e32 v50, 0
	v_mov_b32_e32 v51, 0
	v_mov_b32_e32 v52, 0
	v_mov_b32_e32 v53, 0
	v_mov_b32_e32 v54, 0
	v_mov_b32_e32 v55, 0
	v_mov_b32_e32 v56, 0
	v_mov_b32_e32 v57, 0
	v_mov_b32_e32 v58, 0
	v_mov_b32_e32 v59, 0
	v_mov_b32_e32 v60, 0
	v_mov_b32_e32 v61, 0
	v_mov_b32_e32 v62, 0
	v_mov_b32_e32 v63, 0
	v_mov_b32_e32 v64, 0
	v_mov_b32_e32 v65, 0
	v_mov_b32_e32 v74, 0
	v_mov_b32_e32 v75, 0
	v_mov_b32_e32 v76, 0
	v_mov_b32_e32 v77, 0
	v_mov_b32_e32 v78, 0
	v_mov_b32_e32 v79, 0
	v_mov_b32_e32 v80, 0
	v_mov_b32_e32 v81, 0
	v_mov_b32_e32 v82, 0
	v_mov_b32_e32 v83, 0
	v_mov_b32_e32 v84, 0
	v_mov_b32_e32 v85, 0
	v_mov_b32_e32 v86, 0
	v_mov_b32_e32 v87, 0
	v_mov_b32_e32 v88, 0
	v_mov_b32_e32 v89, 0
	v_mov_b32_e32 v90, 0
	v_mov_b32_e32 v91, 0
	v_mov_b32_e32 v92, 0
	v_mov_b32_e32 v93, 0
	v_mov_b32_e32 v94, 0
	v_mov_b32_e32 v95, 0
	v_mov_b32_e32 v96, 0
	v_mov_b32_e32 v97, 0
	v_mov_b32_e32 v98, 0
	v_mov_b32_e32 v99, 0
	v_mov_b32_e32 v100, 0
	v_mov_b32_e32 v101, 0
	v_mov_b32_e32 v102, 0
	v_mov_b32_e32 v103, 0
	v_mov_b32_e32 v104, 0
	v_mov_b32_e32 v105, 0
	v_mov_b32_e32 v106, 0
	v_mov_b32_e32 v107, 0
	v_mov_b32_e32 v108, 0
	v_mov_b32_e32 v109, 0
	v_mov_b32_e32 v110, 0
	v_mov_b32_e32 v111, 0
	v_mov_b32_e32 v112, 0
	v_mov_b32_e32 v113, 0
	v_mov_b32_e32 v114, 0
	v_mov_b32_e32 v115, 0
	v_mov_b32_e32 v116, 0
	v_mov_b32_e32 v117, 0
	v_mov_b32_e32 v118, 0
	v_mov_b32_e32 v119, 0
	v_mov_b32_e32 v120, 0
	v_mov_b32_e32 v121, 0
	v_mov_b32_e32 v208, 0
	v_mov_b32_e32 v209, 0
	v_mov_b32_e32 v210, 0
	v_mov_b32_e32 v211, 0
	v_mov_b32_e32 v212, 0
	v_mov_b32_e32 v213, 0
	v_mov_b32_e32 v214, 0
	v_mov_b32_e32 v215, 0
	v_mov_b32_e32 v216, 0
	v_mov_b32_e32 v217, 0
	v_mov_b32_e32 v218, 0
	v_mov_b32_e32 v219, 0
	v_mov_b32_e32 v220, 0
	v_mov_b32_e32 v221, 0
	v_mov_b32_e32 v222, 0
	v_mov_b32_e32 v223, 0
	s_add_u32 m0, s42, 0x0
	s_nop 0
	global_load_lds_dwordx4 v143, s[28:29]
	global_load_lds_dwordx4 v144, s[28:29] offset:1024
	s_add_u32 m0, s43, 0x0
	s_nop 0
	global_load_lds_dwordx4 v145, s[30:31]
	global_load_lds_dwordx4 v146, s[30:31] offset:1024
	global_load_lds_dwordx4 v147, s[30:31] offset:2048
	global_load_lds_dwordx4 v148, s[30:31] offset:3072
	s_add_u32 m0, s42, 0x6000
	s_add_u32 s28, s28, 0x100000
	s_addc_u32 s29, s29, 0
	global_load_lds_dwordx4 v143, s[28:29]
	global_load_lds_dwordx4 v144, s[28:29] offset:1024
	s_add_u32 m0, s43, 0x6000
	s_add_u32 s30, s30, 0x10000
	s_addc_u32 s31, s31, 0
	global_load_lds_dwordx4 v145, s[30:31]
	global_load_lds_dwordx4 v146, s[30:31] offset:1024
	global_load_lds_dwordx4 v147, s[30:31] offset:2048
	global_load_lds_dwordx4 v148, s[30:31] offset:3072
	s_mov_b32 s46, 10

; #define MFMA(a, b, c) __builtin_amdgcn_mfma_f32_32x32x16_bf16((a), (b), (c), 0, 0, 0)
; DI int crow(int r, int hi) { return (r & 3) + 8 * (r >> 2) + 4 * hi; }
; DI float xhalf_max(float x) { const auto rr = __builtin_amdgcn_permlane32_swap(__float_as_uint(x), __float_as_uint(x), false, false); return fmaxf(__uint_as_float(rr[0]), __uint_as_float(rr[1])); }
; template <int DQK, int DV, bool BAND> ...
;     ...
;     for (int sub = 0; sub < 2; ++sub) {
;       const int k0 = kt * 64 + sub * 32;
;       if (BAND) { if (k0 > qw0 + 95 || k0 + 31 < qw0 - 64) continue; }
;       f32x16 pacc;
; #pragma unroll
;       for (int r = 0; r < 16; ++r) pacc[r] = 0.f;
;       __builtin_amdgcn_s_setprio(1);
; #pragma unroll
;       for (int d0 = 0; d0 < ND0; ++d0) { const bf16x8 kf = *(const bf16x8*)&Ks[(sub * 32 + r32) * KLD + d0 * 16 + hi * 8]; pacc = MFMA(kf, qf[d0], pacc); }
;       __builtin_amdgcn_s_setprio(0);
;       float mx = -INFINITY;
;       if (BAND) {
; #pragma unroll
;         for (int r = 0; r < 16; ++r) { const int rel = k0 + crow(r, hi) - qi; const int a = rel < 0 ? -rel : rel;
;           const float s = (a <= 64) ? pacc[r] - bias_step * (float)a : -INFINITY; pacc[r] = s; mx = fmaxf(mx, s); }
;       } else {
; #pragma unroll
;         for (int r = 0; r < 16; ++r) mx = fmaxf(mx, pacc[r]);
;       }
;       mx = xhalf_max(mx);
;       if (__builtin_amdgcn_ballot_w64(mx > m_run + 8.f) != 0ull) {
;         const float m_new = fmaxf(m_run, mx); const float m_use = (m_new == -INFINITY) ? 0.f : m_new;
;         const float alpha = __builtin_amdgcn_exp2f(m_run - m_use);
;         l_run *= alpha; m_run = m_new;
;         if (hi == 0) sc[r32] = alpha;
;         __builtin_amdgcn_fence(__ATOMIC_RELEASE, "wavefront");
;         __builtin_amdgcn_wave_barrier();
; #pragma unroll
;         for (int g4 = 0; g4 < 4; ++g4) { const f32x4 a4 = *(const f32x4*)&sc[8 * g4 + 4 * hi];
; #pragma unroll
;           for (int cb = 0; cb < NCB; ++cb)
; #pragma unroll
;             for (int j = 0; j < 4; ++j) o[cb][4 * g4 + j] *= a4[j]; }
;         __builtin_amdgcn_wave_barrier();
;       }
.LBB1_287:
	s_nop 0
	v_or_b32_e32 v66, s0, v149
	v_mad_u32_u24 v174, v66, s3, v0
	ds_read_b128 v[66:69], v174
	ds_read_b128 v[222:225], v174 offset:32
	s_waitcnt lgkmcnt(1)
	v_mfma_f32_32x32x16_bf16 v[66:81], v[66:69], v[82:85], 0
	s_waitcnt lgkmcnt(0)
	v_mfma_f32_32x32x16_bf16 v[66:81], v[222:225], v[86:89], v[66:81]
	ds_read_b128 v[222:225], v174 offset:64
	s_waitcnt lgkmcnt(0)
	v_mfma_f32_32x32x16_bf16 v[66:81], v[222:225], v[90:93], v[66:81]
	ds_read_b128 v[222:225], v174 offset:96
	s_waitcnt lgkmcnt(0)
	v_mfma_f32_32x32x16_bf16 v[66:81], v[222:225], v[94:97], v[66:81]
	ds_read_b128 v[222:225], v174 offset:128
	s_waitcnt lgkmcnt(0)
	v_mfma_f32_32x32x16_bf16 v[66:81], v[222:225], v[98:101], v[66:81]
	ds_read_b128 v[222:225], v174 offset:160
	s_waitcnt lgkmcnt(0)
	v_mfma_f32_32x32x16_bf16 v[66:81], v[222:225], v[102:105], v[66:81]
	ds_read_b128 v[222:225], v174 offset:192
	s_waitcnt lgkmcnt(0)
	v_mfma_f32_32x32x16_bf16 v[66:81], v[222:225], v[106:109], v[66:81]
	ds_read_b128 v[222:225], v174 offset:224
	s_waitcnt lgkmcnt(0)
	v_mfma_f32_32x32x16_bf16 v[66:81], v[222:225], v[110:113], v[66:81]
	s_nop 0
	s_nop 10
	v_max3_f32 v174, v66, s7, v67
	v_max3_f32 v174, v174, v68, v69
	v_max3_f32 v174, v174, v70, v71
	v_max3_f32 v174, v174, v72, v73
	v_max3_f32 v174, v174, v74, v75
	v_max3_f32 v174, v174, v76, v77
	v_max3_f32 v174, v174, v78, v79
	v_max3_f32 v174, v174, v80, v81
	v_mov_b32_e32 v175, v174
	s_nop 1
	v_permlane32_swap_b32_e32 v174, v175
	v_max_f32_e32 v175, v175, v175
	v_max_f32_e32 v174, v174, v174
	v_max_f32_e32 v219, v174, v175
	v_add_f32_e32 v174, 0x41000000, v220
	v_cmp_gt_f32_e32 vcc, v219, v174
	s_cbranch_vccz .LBB1_291
	v_max_f32_e32 v174, v219, v219
	v_max_f32_e32 v175, v220, v220
	v_max_f32_e32 v219, v175, v174
	v_cmp_neq_f32_e32 vcc, s7, v219
	s_nop 1
	v_cndmask_b32_e32 v174, 0, v219, vcc
	v_sub_f32_e32 v174, v220, v174
	v_exp_f32_e32 v220, v174
	s_and_saveexec_b64 s[24:25], s[36:37]
	ds_write_b32 v208, v220 offset:34816
	s_or_b64 exec, exec, s[24:25]
	v_mul_f32_e32 v210, v210, v220
	ds_read_b128 v[220:223], v147 offset:34816
	ds_read_b128 v[224:227], v147 offset:34848
	ds_read_b128 v[228:231], v147 offset:34880
	ds_read_b128 v[232:235], v147 offset:34912
	s_waitcnt lgkmcnt(3)
	v_pk_mul_f32 v[52:53], v[52:53], v[222:223]
	s_waitcnt lgkmcnt(2)
	v_pk_mul_f32 v[56:57], v[56:57], v[226:227]
	s_waitcnt lgkmcnt(1)
	v_pk_mul_f32 v[60:61], v[60:61], v[230:231]
	s_waitcnt lgkmcnt(0)
	v_pk_mul_f32 v[64:65], v[64:65], v[234:235]
	v_pk_mul_f32 v[62:63], v[62:63], v[232:233]
	v_pk_mul_f32 v[58:59], v[58:59], v[228:229]
	v_pk_mul_f32 v[54:55], v[54:55], v[224:225]
	v_pk_mul_f32 v[50:51], v[50:51], v[220:221]
	v_pk_mul_f32 v[48:49], v[48:49], v[234:235]
	v_pk_mul_f32 v[44:45], v[44:45], v[230:231]
	v_pk_mul_f32 v[40:41], v[40:41], v[226:227]
	v_pk_mul_f32 v[36:37], v[36:37], v[222:223]
	v_pk_mul_f32 v[46:47], v[46:47], v[232:233]
	v_pk_mul_f32 v[42:43], v[42:43], v[228:229]
	v_pk_mul_f32 v[38:39], v[38:39], v[224:225]
	v_pk_mul_f32 v[34:35], v[34:35], v[220:221]
	v_pk_mul_f32 v[32:33], v[32:33], v[234:235]
	v_pk_mul_f32 v[28:29], v[28:29], v[230:231]
	v_pk_mul_f32 v[24:25], v[24:25], v[226:227]
	v_pk_mul_f32 v[20:21], v[20:21], v[222:223]
	v_pk_mul_f32 v[30:31], v[30:31], v[232:233]
	v_pk_mul_f32 v[26:27], v[26:27], v[228:229]
	v_pk_mul_f32 v[22:23], v[22:23], v[224:225]
	v_pk_mul_f32 v[18:19], v[18:19], v[220:221]
	v_pk_mul_f32 v[16:17], v[16:17], v[234:235]
	v_pk_mul_f32 v[12:13], v[12:13], v[230:231]
	v_pk_mul_f32 v[8:9], v[8:9], v[226:227]
	v_pk_mul_f32 v[4:5], v[4:5], v[222:223]
	v_pk_mul_f32 v[14:15], v[14:15], v[232:233]
	v_pk_mul_f32 v[10:11], v[10:11], v[228:229]
	v_pk_mul_f32 v[6:7], v[6:7], v[224:225]
	v_pk_mul_f32 v[2:3], v[2:3], v[220:221]
	s_branch .LBB1_292

; #define MFMA(a, b, c) __builtin_amdgcn_mfma_f32_32x32x16_bf16((a), (b), (c), 0, 0, 0)
; DI unsigned pk2(float a, float b) { f2_t v = {a, b}; bf2_t r = __builtin_convertvector(v, bf2_t); return __builtin_bit_cast(unsigned, r); }
; DI float xhalf_sum(float x) { const auto rr = __builtin_amdgcn_permlane32_swap(__float_as_uint(x), __float_as_uint(x), false, false); return __uint_as_float(rr[0]) + __uint_as_float(rr[1]); }
; template <int DQK, int DV, bool BAND> ...
;     ...
;       const float m_ref = (m_run == -INFINITY) ? 0.f : m_run;
;       float rs = 0.f;
; #pragma unroll
;       for (int r = 0; r < 16; ++r) { const float pe = __builtin_amdgcn_exp2f(pacc[r] - m_ref); pacc[r] = pe; rs += pe; }
;       l_run += xhalf_sum(rs);
;       __builtin_amdgcn_s_setprio(1);
; #pragma unroll
;       for (int s = 0; s < 2; ++s) {
;         const u32x4 pu = {pk2(pacc[8 * s], pacc[8 * s + 1]), pk2(pacc[8 * s + 2], pacc[8 * s + 3]), pk2(pacc[8 * s + 4], pacc[8 * s + 5]), pk2(pacc[8 * s + 6], pacc[8 * s + 7])};
;         const bf16x8 pa = __builtin_bit_cast(bf16x8, pu);
; #pragma unroll
;         for (int cb = 0; cb < NCB; ++cb) {
;           const u32x2 lo = *(const u32x2*)&Vs[(cb * 32 + r32) * VLD + sub * 32 + 16 * s + 4 * hi];
;           const u32x2 h8 = *(const u32x2*)&Vs[(cb * 32 + r32) * VLD + sub * 32 + 16 * s + 4 * hi + 8];
;           const u32x4 vu = {lo[0], lo[1], h8[0], h8[1]};
;           o[cb] = MFMA(pa, __builtin_bit_cast(bf16x8, vu), o[cb]);
;         }
;       }
;       __builtin_amdgcn_s_setprio(0);
;     }
.LBB1_292:
	v_cmp_neq_f32_e32 vcc, s7, v219
	s_xor_b64 s[24:25], s[22:23], -1
	s_nop 0
	v_cndmask_b32_e32 v174, 0, v219, vcc
	v_sub_f32_e32 v66, v66, v174
	v_exp_f32_e32 v66, v66
	v_sub_f32_e32 v67, v67, v174
	v_exp_f32_e32 v67, v67
	v_sub_f32_e32 v68, v68, v174
	v_exp_f32_e32 v68, v68
	v_sub_f32_e32 v69, v69, v174
	v_exp_f32_e32 v69, v69
	v_sub_f32_e32 v70, v70, v174
	v_add_f32_e32 v175, 0, v66
	v_exp_f32_e32 v70, v70
	v_sub_f32_e32 v71, v71, v174
	v_add_f32_e32 v175, v67, v175
	v_exp_f32_e32 v71, v71
	v_sub_f32_e32 v72, v72, v174
	v_add_f32_e32 v175, v68, v175
	v_exp_f32_e32 v72, v72
	v_sub_f32_e32 v73, v73, v174
	v_add_f32_e32 v175, v69, v175
	v_exp_f32_e32 v73, v73
	v_sub_f32_e32 v74, v74, v174
	v_add_f32_e32 v175, v70, v175
	v_exp_f32_e32 v176, v74
	v_sub_f32_e32 v74, v75, v174
	v_add_f32_e32 v175, v71, v175
	v_exp_f32_e32 v177, v74
	v_sub_f32_e32 v74, v76, v174
	v_add_f32_e32 v175, v72, v175
	v_exp_f32_e32 v220, v74
	v_sub_f32_e32 v74, v77, v174
	v_add_f32_e32 v175, v73, v175
	v_exp_f32_e32 v221, v74
	v_sub_f32_e32 v75, v78, v174
	v_add_f32_e32 v74, v176, v175
	v_exp_f32_e32 v78, v75
	v_sub_f32_e32 v75, v79, v174
	v_add_f32_e32 v74, v177, v74
	v_exp_f32_e32 v79, v75
	v_sub_f32_e32 v75, v80, v174
	v_add_f32_e32 v74, v220, v74
	v_exp_f32_e32 v80, v75
	v_sub_f32_e32 v75, v81, v174
	v_add_f32_e32 v74, v221, v74
	v_exp_f32_e32 v81, v75
	v_add_f32_e32 v74, v78, v74
	v_add_f32_e32 v74, v79, v74
	v_add_f32_e32 v74, v80, v74
	v_add_f32_e32 v74, v81, v74
	v_mov_b32_e32 v75, v74
	s_nop 1
	v_permlane32_swap_b32_e32 v74, v75
	v_add_f32_e32 v174, v74, v75
	s_nop 0
	v_or_b32_e32 v74, s0, v153
	v_lshl_add_u32 v175, v74, 1, v209
	v_cvt_pk_bf16_f32 v66, v66, v67
	v_cvt_pk_bf16_f32 v67, v68, v69
	v_cvt_pk_bf16_f32 v68, v70, v71
	v_cvt_pk_bf16_f32 v69, v72, v73
	v_add_u32_e32 v74, 0x4000, v175
	ds_read2_b64 v[70:73], v74 offset0:128 offset1:130
	ds_read2_b64 v[74:77], v74 offset0:132 offset1:134
	v_add_u32_e32 v222, 0x5000, v175
	s_waitcnt lgkmcnt(1)
	v_mfma_f32_32x32x16_bf16 v[50:65], v[66:69], v[70:73], v[50:65]
	ds_read2_b64 v[70:73], v222 offset0:160 offset1:162
	v_add_u32_e32 v223, 0x6000, v175
	v_add_u32_e32 v175, 0x7000, v175
	v_add_f32_e32 v210, v210, v174
	s_waitcnt lgkmcnt(0)
	v_mfma_f32_32x32x16_bf16 v[34:49], v[66:69], v[70:73], v[34:49]
	ds_read2_b64 v[70:73], v223 offset0:192 offset1:194
	s_waitcnt lgkmcnt(0)
	v_mfma_f32_32x32x16_bf16 v[18:33], v[66:69], v[70:73], v[18:33]
	ds_read2_b64 v[70:73], v175 offset0:224 offset1:226
	s_waitcnt lgkmcnt(0)
	v_mfma_f32_32x32x16_bf16 v[2:17], v[66:69], v[70:73], v[2:17]
	v_cvt_pk_bf16_f32 v66, v176, v177
	v_cvt_pk_bf16_f32 v67, v220, v221
	v_cvt_pk_bf16_f32 v68, v78, v79
	v_cvt_pk_bf16_f32 v69, v80, v81
	ds_read2_b64 v[70:73], v222 offset0:164 offset1:166
	s_waitcnt lgkmcnt(0)
	v_mfma_f32_32x32x16_bf16 v[34:49], v[66:69], v[70:73], v[34:49]
	ds_read2_b64 v[70:73], v223 offset0:196 offset1:198
	s_waitcnt lgkmcnt(0)
	v_mfma_f32_32x32x16_bf16 v[18:33], v[66:69], v[70:73], v[18:33]
	ds_read2_b64 v[70:73], v175 offset0:228 offset1:230
	v_mfma_f32_32x32x16_bf16 v[50:65], v[66:69], v[74:77], v[50:65]
	s_waitcnt lgkmcnt(0)
	v_mfma_f32_32x32x16_bf16 v[2:17], v[66:69], v[70:73], v[2:17]
	s_nop 0
	s_mov_b32 s0, 32
	s_mov_b64 s[22:23], 0
	s_and_b64 vcc, exec, s[24:25]
	s_cbranch_vccnz .LBB1_294
	v_mov_b32_e32 v220, v219
	s_branch .LBB1_287

; #define MFMA(a, b, c) __builtin_amdgcn_mfma_f32_32x32x16_bf16((a), (b), (c), 0, 0, 0)
; DI unsigned pk2(float a, float b) { f2_t v = {a, b}; bf2_t r = __builtin_convertvector(v, bf2_t); return __builtin_bit_cast(unsigned, r); }
; DI float xhalf_sum(float x) { const auto rr = __builtin_amdgcn_permlane32_swap(__float_as_uint(x), __float_as_uint(x), false, false); return __uint_as_float(rr[0]) + __uint_as_float(rr[1]); }
; template <int DQK, int DV, bool BAND> ...
;     ...
;       const float m_ref = (m_run == -INFINITY) ? 0.f : m_run;
;       float rs = 0.f;
; #pragma unroll
;       for (int r = 0; r < 16; ++r) { const float pe = __builtin_amdgcn_exp2f(pacc[r] - m_ref); pacc[r] = pe; rs += pe; }
;       l_run += xhalf_sum(rs);
;       __builtin_amdgcn_s_setprio(1);
; #pragma unroll
;       for (int s = 0; s < 2; ++s) {
;         const u32x4 pu = {pk2(pacc[8 * s], pacc[8 * s + 1]), pk2(pacc[8 * s + 2], pacc[8 * s + 3]), pk2(pacc[8 * s + 4], pacc[8 * s + 5]), pk2(pacc[8 * s + 6], pacc[8 * s + 7])};
;         const bf16x8 pa = __builtin_bit_cast(bf16x8, pu);
; #pragma unroll
;         for (int cb = 0; cb < NCB; ++cb) {
;           const u32x2 lo = *(const u32x2*)&Vs[(cb * 32 + r32) * VLD + sub * 32 + 16 * s + 4 * hi];
;           const u32x2 h8 = *(const u32x2*)&Vs[(cb * 32 + r32) * VLD + sub * 32 + 16 * s + 4 * hi + 8];
;           const u32x4 vu = {lo[0], lo[1], h8[0], h8[1]};
;           o[cb] = MFMA(pa, __builtin_bit_cast(bf16x8, vu), o[cb]);
;         }
;       }
;       __builtin_amdgcn_s_setprio(0);
;     }
.LBB1_306:
	v_cmp_neq_f32_e32 vcc, s7, v75
	s_nop 1
	v_cndmask_b32_e32 v167, 0, v75, vcc
	v_sub_f32_e32 v66, v66, v167
	v_exp_f32_e32 v66, v66
	v_sub_f32_e32 v67, v67, v167
	v_exp_f32_e32 v67, v67
	v_sub_f32_e32 v68, v68, v167
	v_exp_f32_e32 v68, v68
	v_sub_f32_e32 v69, v69, v167
	v_exp_f32_e32 v69, v69
	v_sub_f32_e32 v70, v70, v167
	v_add_f32_e32 v174, 0, v66
	v_exp_f32_e32 v70, v70
	v_sub_f32_e32 v71, v71, v167
	v_add_f32_e32 v174, v67, v174
	v_exp_f32_e32 v71, v71
	v_sub_f32_e32 v72, v72, v167
	v_add_f32_e32 v174, v68, v174
	v_exp_f32_e32 v72, v72
	v_sub_f32_e32 v73, v73, v167
	v_add_f32_e32 v174, v69, v174
	v_exp_f32_e32 v73, v73
	v_sub_f32_e32 v74, v74, v167
	v_add_f32_e32 v174, v70, v174
	v_exp_f32_e32 v74, v74
	v_sub_f32_e32 v175, v228, v167
	v_add_f32_e32 v174, v71, v174
	v_exp_f32_e32 v175, v175
	v_sub_f32_e32 v76, v76, v167
	v_add_f32_e32 v174, v72, v174
	v_exp_f32_e32 v176, v76
	v_sub_f32_e32 v76, v77, v167
	v_add_f32_e32 v174, v73, v174
	v_exp_f32_e32 v177, v76
	v_sub_f32_e32 v77, v78, v167
	v_add_f32_e32 v76, v74, v174
	v_exp_f32_e32 v174, v77
	v_sub_f32_e32 v77, v79, v167
	v_add_f32_e32 v76, v175, v76
	v_exp_f32_e32 v228, v77
	v_sub_f32_e32 v77, v80, v167
	v_add_f32_e32 v76, v176, v76
	v_exp_f32_e32 v80, v77
	v_sub_f32_e32 v77, v81, v167
	v_add_f32_e32 v76, v177, v76
	v_exp_f32_e32 v81, v77
	v_add_f32_e32 v76, v174, v76
	v_add_f32_e32 v76, v228, v76
	v_add_f32_e32 v76, v80, v76
	v_add_f32_e32 v76, v81, v76
	v_mov_b32_e32 v77, v76
	s_nop 1
	v_permlane32_swap_b32_e32 v76, v77
	v_add_f32_e32 v167, v76, v77
	s_nop 0
	v_or_b32_e32 v76, s61, v216
	v_lshl_add_u32 v229, v76, 1, v219
	v_cvt_pk_bf16_f32 v66, v66, v67
	v_cvt_pk_bf16_f32 v67, v68, v69
	v_cvt_pk_bf16_f32 v68, v70, v71
	v_cvt_pk_bf16_f32 v69, v72, v73
	v_add_u32_e32 v76, 0x4000, v229
	ds_read2_b64 v[70:73], v76 offset0:128 offset1:130
	ds_read2_b64 v[76:79], v76 offset0:132 offset1:134
	v_add_u32_e32 v230, 0x5000, v229
	s_waitcnt lgkmcnt(1)
	v_mfma_f32_32x32x16_bf16 v[50:65], v[66:69], v[70:73], v[50:65]
	ds_read2_b64 v[70:73], v230 offset0:160 offset1:162
	v_add_u32_e32 v231, 0x6000, v229
	v_add_u32_e32 v229, 0x7000, v229
	v_add_f32_e32 v166, v166, v167
	s_waitcnt lgkmcnt(0)
	v_mfma_f32_32x32x16_bf16 v[34:49], v[66:69], v[70:73], v[34:49]
	ds_read2_b64 v[70:73], v231 offset0:192 offset1:194
	s_waitcnt lgkmcnt(0)
	v_mfma_f32_32x32x16_bf16 v[18:33], v[66:69], v[70:73], v[18:33]
	ds_read2_b64 v[70:73], v229 offset0:224 offset1:226
	s_waitcnt lgkmcnt(0)
	v_mfma_f32_32x32x16_bf16 v[2:17], v[66:69], v[70:73], v[2:17]
	v_cvt_pk_bf16_f32 v66, v74, v175
	v_cvt_pk_bf16_f32 v67, v176, v177
	v_cvt_pk_bf16_f32 v68, v174, v228
	v_cvt_pk_bf16_f32 v69, v80, v81
	ds_read2_b64 v[70:73], v230 offset0:164 offset1:166
	s_waitcnt lgkmcnt(0)
	v_mfma_f32_32x32x16_bf16 v[34:49], v[66:69], v[70:73], v[34:49]
	ds_read2_b64 v[70:73], v231 offset0:196 offset1:198
	s_waitcnt lgkmcnt(0)
	v_mfma_f32_32x32x16_bf16 v[18:33], v[66:69], v[70:73], v[18:33]
	ds_read2_b64 v[70:73], v229 offset0:228 offset1:230
	v_mfma_f32_32x32x16_bf16 v[50:65], v[66:69], v[76:79], v[50:65]
	s_waitcnt lgkmcnt(0)
	v_mfma_f32_32x32x16_bf16 v[2:17], v[66:69], v[70:73], v[2:17]
	s_nop 0
	v_mov_b32_e32 v167, v75

; #define MFMA(a, b, c) __builtin_amdgcn_mfma_f32_32x32x16_bf16((a), (b), (c), 0, 0, 0)
; DI int crow(int r, int hi) { return (r & 3) + 8 * (r >> 2) + 4 * hi; }
; DI float xhalf_max(float x) { const auto rr = __builtin_amdgcn_permlane32_swap(__float_as_uint(x), __float_as_uint(x), false, false); return fmaxf(__uint_as_float(rr[0]), __uint_as_float(rr[1])); }
; template <int DQK, int DV, bool BAND> ...
;     ...
;     for (int sub = 0; sub < 2; ++sub) {
;       const int k0 = kt * 64 + sub * 32;
;       if (BAND) { if (k0 > qw0 + 95 || k0 + 31 < qw0 - 64) continue; }
;       f32x16 pacc;
; #pragma unroll
;       for (int r = 0; r < 16; ++r) pacc[r] = 0.f;
;       __builtin_amdgcn_s_setprio(1);
; #pragma unroll
;       for (int d0 = 0; d0 < ND0; ++d0) { const bf16x8 kf = *(const bf16x8*)&Ks[(sub * 32 + r32) * KLD + d0 * 16 + hi * 8]; pacc = MFMA(kf, qf[d0], pacc); }
;       __builtin_amdgcn_s_setprio(0);
;       float mx = -INFINITY;
;       if (BAND) {
; #pragma unroll
;         for (int r = 0; r < 16; ++r) { const int rel = k0 + crow(r, hi) - qi; const int a = rel < 0 ? -rel : rel;
;           const float s = (a <= 64) ? pacc[r] - bias_step * (float)a : -INFINITY; pacc[r] = s; mx = fmaxf(mx, s); }
;       } else {
; #pragma unroll
;         for (int r = 0; r < 16; ++r) mx = fmaxf(mx, pacc[r]);
;       }
;       mx = xhalf_max(mx);
;       if (__builtin_amdgcn_ballot_w64(mx > m_run + 8.f) != 0ull) {
;         const float m_new = fmaxf(m_run, mx); const float m_use = (m_new == -INFINITY) ? 0.f : m_new;
;         const float alpha = __builtin_amdgcn_exp2f(m_run - m_use);
;         l_run *= alpha; m_run = m_new;
;         if (hi == 0) sc[r32] = alpha;
.LBB1_308:
	s_or_b32 s30, s61, s0
	s_or_b32 s28, s30, 31
	v_cmp_le_i32_e32 vcc, s30, v214
	v_cmp_ge_i32_e64 s[40:41], s28, v215
	s_and_b64 s[40:41], vcc, s[40:41]
	s_and_saveexec_b64 s[28:29], s[40:41]
	s_cbranch_execz .LBB1_307
	s_nop 0
	v_or_b32_e32 v66, s61, v170
	v_mad_u32_u24 v174, v66, s3, v0
	ds_read_b128 v[66:69], v174
	ds_read_b128 v[228:231], v174 offset:32
	s_waitcnt lgkmcnt(1)
	v_mfma_f32_32x32x16_bf16 v[66:81], v[66:69], v[82:85], 0
	s_waitcnt lgkmcnt(0)
	v_mfma_f32_32x32x16_bf16 v[66:81], v[228:231], v[86:89], v[66:81]
	ds_read_b128 v[228:231], v174 offset:64
	s_waitcnt lgkmcnt(0)
	v_mfma_f32_32x32x16_bf16 v[66:81], v[228:231], v[90:93], v[66:81]
	ds_read_b128 v[228:231], v174 offset:96
	s_waitcnt lgkmcnt(0)
	v_mfma_f32_32x32x16_bf16 v[66:81], v[228:231], v[94:97], v[66:81]
	ds_read_b128 v[228:231], v174 offset:128
	s_waitcnt lgkmcnt(0)
	v_mfma_f32_32x32x16_bf16 v[66:81], v[228:231], v[98:101], v[66:81]
	ds_read_b128 v[228:231], v174 offset:160
	s_waitcnt lgkmcnt(0)
	v_mfma_f32_32x32x16_bf16 v[66:81], v[228:231], v[102:105], v[66:81]
	ds_read_b128 v[228:231], v174 offset:192
	s_waitcnt lgkmcnt(0)
	v_mfma_f32_32x32x16_bf16 v[66:81], v[228:231], v[106:109], v[66:81]
	ds_read_b128 v[228:231], v174 offset:224
	s_waitcnt lgkmcnt(0)
	v_mfma_f32_32x32x16_bf16 v[66:81], v[228:231], v[110:113], v[66:81]
	s_nop 0
	v_add_u32_e32 v174, s30, v217
	v_sub_u32_e32 v175, 0, v174
	v_max_i32_e32 v175, v174, v175
	v_cmp_gt_u32_e32 vcc, s33, v175
	v_cvt_f32_u32_e32 v175, v175
	v_not_b32_e32 v176, v174
	v_sub_u32_e32 v177, -2, v174
	s_nop 3
	v_fma_f32 v66, -v213, v175, v66
	v_add_u32_e32 v175, 1, v174
	v_max_i32_e32 v175, v175, v176
	v_cndmask_b32_e32 v66, v202, v66, vcc
	v_cmp_gt_u32_e32 vcc, s33, v175
	v_cvt_f32_u32_e32 v175, v175
	v_add_u32_e32 v176, 2, v174
	v_max_i32_e32 v176, v176, v177
	v_sub_u32_e32 v177, -3, v174
	v_fma_f32 v67, -v213, v175, v67
	v_cndmask_b32_e32 v67, v202, v67, vcc
	v_cmp_gt_u32_e32 vcc, s33, v176
	v_cvt_f32_u32_e32 v176, v176
	v_max3_f32 v175, v66, s7, v67
	v_fma_f32 v68, -v213, v176, v68
	v_add_u32_e32 v176, 3, v174
	v_max_i32_e32 v176, v176, v177
	v_cndmask_b32_e32 v68, v202, v68, vcc
	v_cmp_gt_u32_e32 vcc, s33, v176
	v_cvt_f32_u32_e32 v176, v176
	v_sub_u32_e32 v177, -8, v174
	v_fma_f32 v69, -v213, v176, v69
	v_add_u32_e32 v176, 8, v174
	v_max_i32_e32 v176, v176, v177
	v_cndmask_b32_e32 v69, v202, v69, vcc
	v_cmp_gt_u32_e32 vcc, s33, v176
	v_cvt_f32_u32_e32 v176, v176
	v_sub_u32_e32 v177, -9, v174
	v_max3_f32 v175, v175, v68, v69
	v_fma_f32 v70, -v213, v176, v70
	v_add_u32_e32 v176, 9, v174
	v_max_i32_e32 v176, v176, v177
	v_cndmask_b32_e32 v70, v202, v70, vcc
	v_cmp_gt_u32_e32 vcc, s33, v176
	v_cvt_f32_u32_e32 v176, v176
	v_sub_u32_e32 v177, -10, v174
	v_fma_f32 v71, -v213, v176, v71
	v_add_u32_e32 v176, 10, v174
	v_max_i32_e32 v176, v176, v177
	v_cndmask_b32_e32 v71, v202, v71, vcc
	v_cmp_gt_u32_e32 vcc, s33, v176
	v_cvt_f32_u32_e32 v176, v176
	v_sub_u32_e32 v177, -11, v174
	v_max3_f32 v175, v175, v70, v71
	v_fma_f32 v72, -v213, v176, v72
	v_add_u32_e32 v176, 11, v174
	v_max_i32_e32 v176, v176, v177
	v_cndmask_b32_e32 v72, v202, v72, vcc
	v_cmp_gt_u32_e32 vcc, s33, v176
	v_cvt_f32_u32_e32 v176, v176
	v_sub_u32_e32 v177, -16, v174
	v_fma_f32 v73, -v213, v176, v73
	v_add_u32_e32 v176, 16, v174
	v_max_i32_e32 v176, v176, v177
	v_cndmask_b32_e32 v73, v202, v73, vcc
	v_cmp_gt_u32_e32 vcc, s33, v176
	v_cvt_f32_u32_e32 v176, v176
	v_sub_u32_e32 v177, 0xffffffef, v174
	v_max3_f32 v175, v175, v72, v73
	v_fma_f32 v74, -v213, v176, v74
	v_add_u32_e32 v176, 17, v174
	v_max_i32_e32 v176, v176, v177
	v_cndmask_b32_e32 v74, v202, v74, vcc
	v_cmp_gt_u32_e32 vcc, s33, v176
	v_cvt_f32_u32_e32 v176, v176
	v_fma_f32 v75, -v213, v176, v75
	v_cndmask_b32_e32 v228, v202, v75, vcc
	v_max3_f32 v75, v175, v74, v228
	v_add_u32_e32 v175, 18, v174
	v_sub_u32_e32 v176, 0xffffffee, v174
	v_max_i32_e32 v175, v175, v176
	v_cmp_gt_u32_e32 vcc, s33, v175
	v_cvt_f32_u32_e32 v175, v175
	v_sub_u32_e32 v176, 0xffffffed, v174
	v_fma_f32 v76, -v213, v175, v76
	v_add_u32_e32 v175, 19, v174
	v_max_i32_e32 v175, v175, v176
	v_cndmask_b32_e32 v76, v202, v76, vcc
	v_cmp_gt_u32_e32 vcc, s33, v175
	v_cvt_f32_u32_e32 v175, v175
	v_sub_u32_e32 v176, 0xffffffe8, v174
	v_fma_f32 v77, -v213, v175, v77
	v_add_u32_e32 v175, 24, v174
	v_max_i32_e32 v175, v175, v176
	v_cndmask_b32_e32 v77, v202, v77, vcc
	v_cmp_gt_u32_e32 vcc, s33, v175
	v_cvt_f32_u32_e32 v175, v175
	v_sub_u32_e32 v176, 0xffffffe7, v174
	v_max3_f32 v75, v75, v76, v77
	v_fma_f32 v78, -v213, v175, v78
	v_add_u32_e32 v175, 25, v174
	v_max_i32_e32 v175, v175, v176
	v_cndmask_b32_e32 v78, v202, v78, vcc
	v_cmp_gt_u32_e32 vcc, s33, v175
	v_cvt_f32_u32_e32 v175, v175
	v_sub_u32_e32 v176, 0xffffffe6, v174
	v_fma_f32 v79, -v213, v175, v79
	v_add_u32_e32 v175, 26, v174
	v_max_i32_e32 v175, v175, v176
	v_cndmask_b32_e32 v79, v202, v79, vcc
	v_cmp_gt_u32_e32 vcc, s33, v175
	v_cvt_f32_u32_e32 v175, v175
	v_max3_f32 v75, v75, v78, v79
	v_fma_f32 v80, -v213, v175, v80
	v_add_u32_e32 v175, 27, v174
	v_sub_u32_e32 v174, 0xffffffe5, v174
	v_max_i32_e32 v174, v175, v174
	v_cndmask_b32_e32 v80, v202, v80, vcc
	v_cmp_gt_u32_e32 vcc, s33, v174
	v_cvt_f32_u32_e32 v174, v174
	v_fma_f32 v81, -v213, v174, v81
	v_cndmask_b32_e32 v81, v202, v81, vcc
	v_max3_f32 v75, v75, v80, v81
	v_mov_b32_e32 v174, v75
	s_nop 1
	v_permlane32_swap_b32_e32 v75, v174
	v_max_f32_e32 v174, v174, v174
	v_max_f32_e32 v75, v75, v75
	v_max_f32_e32 v75, v75, v174
	v_add_f32_e32 v174, 0x41000000, v167
	v_cmp_gt_f32_e32 vcc, v75, v174
	s_cbranch_vccz .LBB1_312
	v_max_f32_e32 v75, v75, v75
	v_max_f32_e32 v174, v167, v167
	v_max_f32_e32 v75, v174, v75
	v_cmp_neq_f32_e32 vcc, s7, v75
	s_nop 1
	v_cndmask_b32_e32 v174, 0, v75, vcc
	v_sub_f32_e32 v167, v167, v174
	v_exp_f32_e32 v167, v167
	s_and_saveexec_b64 s[30:31], s[36:37]
	s_cbranch_execz .LBB1_305
	ds_write_b32 v208, v167 offset:34816
	s_branch .LBB1_305

; DI int TID() { int t = (int)__builtin_amdgcn_workitem_id_x(); asm volatile("" : "+v"(t)); return t; }
; #define BLOAD(A_, B_, kt) do { _Pragma("unroll") for (int i = 0; i < 4; ++i) { \
;     A_[i] = *(const u32x4*)((const char*)Ap + (aoff + (unsigned)(32 * i * lda + (kt) * 64) * 2u)); B_[i] = *(const u32x4*)((const char*)Wt + (woff + (unsigned)(32 * i * K + (kt) * 64) * 2u)); } } while (0)
; #define BLOAD(A_, B_, kt) do { _Pragma("unroll") for (int i = 0; i < 4; ++i) { \
;     A_[i] = *(const u32x4*)((const char*)Ap + (aoff + (unsigned)(32 * i * lda + (kt) * 64) * 2u)); B_[i] = *(const u32x4*)((const char*)Wt + (woff + (unsigned)(32 * i * K + (kt) * 64) * 2u)); } } while (0)
; #define BSTORE(A_, B_, buf) do { _Pragma("unroll") for (int i = 0; i < 4; ++i) { \
;     *(u32x4*)&As[(buf) * GBUF + (srow + 32 * i) * LDT + sc8] = A_[i]; \
;     *(u32x4*)&Bs[(buf) * GBUF + (srow + 32 * i) * LDT + sc8] = B_[i]; } } while (0)
; template <bool ROWNORM, int NK>
; DI void gemm_main_bf(const u16* __restrict__ Ap, int lda, const u16* __restrict__ Wt, f32x16 (&acc)[2][2], char* smem, float* rinv_s) {
;   constexpr int K = NK * 64;
;   const int tid = TID(), lane = tid & 63, w = tid >> 6, wm = w >> 1, wn = w & 1, r32 = lane & 31, hi = lane >> 5;
;   u16* As = (u16*)smem; u16* Bs = As + 128 * LDT;
;   const int srow = tid >> 3, sc8 = (tid & 7) * 8;
;   float ss[4] = {0.f, 0.f, 0.f, 0.f};
;   u32x4 a0[4], b0[4], a1[4], b1[4];
;   constexpr int nk = NK;
;   const unsigned aoff = (unsigned)(srow * lda + sc8) * 2u, woff = (unsigned)(srow * K + sc8) * 2u;
;     ...
;   __builtin_amdgcn_s_setprio(0);
;   BLOAD(a0, b0, 0); BLOAD(a1, b1, 1);
;   __syncthreads();
;   BSTORE(a0, b0, 0);
;   BLOAD(a0, b0, 2);
;   __syncthreads();
.LBB1_343:
	s_add_i32 s40, s79, -8
	s_lshl_b32 s0, s52, 9
	s_add_u32 s36, s42, s0
	s_mov_b32 s41, s1
	s_addc_u32 s37, s43, 0
	s_lshl_b64 s[34:35], s[40:41], 16
	v_mov_b32_e32 v34, v172
	s_add_u32 vcc_lo, s74, s34
	s_addc_u32 vcc_hi, s75, s35
	v_and_b32_e32 v133, 7, v34
	v_ashrrev_i32_e32 v0, 3, v34
	v_lshlrev_b32_e32 v2, 4, v133
	v_lshl_or_b32 v140, v0, 9, v2
	s_nop 0
	global_load_dwordx4 v[18:21], v140, s[36:37]
	global_load_dwordx4 v[22:25], v140, vcc
	v_add_u32_e32 v2, 0x4000, v140
	global_load_dwordx4 v[26:29], v2, s[36:37]
	global_load_dwordx4 v[30:33], v2, vcc
	v_add_u32_e32 v2, 0x8000, v140
	global_load_dwordx4 v[10:13], v2, s[36:37]
	s_waitcnt lgkmcnt(0)
	global_load_dwordx4 v[14:17], v2, vcc
	v_add_u32_e32 v6, 0xc000, v140
	global_load_dwordx4 v[2:5], v6, s[36:37]
	s_nop 0
	global_load_dwordx4 v[6:9], v6, vcc
	s_nop 0
	global_load_dwordx4 v[90:93], v140, s[36:37] offset:128
	global_load_dwordx4 v[94:97], v140, vcc offset:128
	v_add_u32_e32 v35, 0x4080, v140
	global_load_dwordx4 v[82:85], v35, s[36:37]
	global_load_dwordx4 v[86:89], v35, vcc
	v_add_u32_e32 v35, 0x8080, v140
	global_load_dwordx4 v[74:77], v35, s[36:37]
	global_load_dwordx4 v[78:81], v35, vcc
	v_add_u32_e32 v35, 0xc080, v140
	global_load_dwordx4 v[66:69], v35, s[36:37]
	global_load_dwordx4 v[70:73], v35, vcc
	v_lshlrev_b32_e32 v35, 3, v133
	s_barrier
	s_waitcnt vmcnt(15)
	v_and_b32_e32 v37, 0xffff0000, v18
	v_lshlrev_b32_e32 v36, 16, v18
	v_mul_f32_e32 v134, v37, v37
	v_lshlrev_b32_e32 v38, 16, v19
	v_fmac_f32_e32 v134, v36, v36
	v_and_b32_e32 v39, 0xffff0000, v19
	v_fmac_f32_e32 v134, v38, v38
	v_lshlrev_b32_e32 v40, 16, v20
	v_fmac_f32_e32 v134, v39, v39
	v_and_b32_e32 v41, 0xffff0000, v20
	v_fmac_f32_e32 v134, v40, v40
	v_lshlrev_b32_e32 v42, 16, v21
	v_fmac_f32_e32 v134, v41, v41
	v_and_b32_e32 v43, 0xffff0000, v21
	v_fmac_f32_e32 v134, v42, v42
	v_mul_lo_u32 v36, v0, s91
	v_fmac_f32_e32 v134, v43, v43
	v_add_lshl_u32 v138, v36, v35, 1
	ds_write_b128 v138, v[18:21]
	s_waitcnt vmcnt(14)
	ds_write_b128 v138, v[22:25] offset:18432
	s_waitcnt vmcnt(13)
	v_and_b32_e32 v19, 0xffff0000, v26
	v_lshlrev_b32_e32 v18, 16, v26
	v_mul_f32_e32 v135, v19, v19
	s_waitcnt vmcnt(11)
	v_and_b32_e32 v19, 0xffff0000, v10
	v_lshlrev_b32_e32 v20, 16, v27
	v_fmac_f32_e32 v135, v18, v18
	v_lshlrev_b32_e32 v18, 16, v10
	v_mul_f32_e32 v136, v19, v19
	v_and_b32_e32 v21, 0xffff0000, v27
	v_fmac_f32_e32 v135, v20, v20
	v_lshlrev_b32_e32 v20, 16, v11
	v_fmac_f32_e32 v136, v18, v18
	v_lshlrev_b32_e32 v22, 16, v28
	v_fmac_f32_e32 v135, v21, v21
	v_and_b32_e32 v21, 0xffff0000, v11
	v_fmac_f32_e32 v136, v20, v20
	v_and_b32_e32 v23, 0xffff0000, v28
	v_fmac_f32_e32 v135, v22, v22
	v_lshlrev_b32_e32 v22, 16, v12
	v_fmac_f32_e32 v136, v21, v21
	v_lshlrev_b32_e32 v24, 16, v29
	v_fmac_f32_e32 v135, v23, v23
	v_and_b32_e32 v23, 0xffff0000, v12
	v_fmac_f32_e32 v136, v22, v22
	v_and_b32_e32 v25, 0xffff0000, v29
	v_fmac_f32_e32 v135, v24, v24
	v_lshlrev_b32_e32 v24, 16, v13
	v_fmac_f32_e32 v136, v23, v23
	v_fmac_f32_e32 v135, v25, v25
	v_and_b32_e32 v25, 0xffff0000, v13
	v_fmac_f32_e32 v136, v24, v24
	v_fmac_f32_e32 v136, v25, v25
	ds_write_b128 v138, v[26:29] offset:4608
	ds_write_b128 v138, v[30:33] offset:23040
	ds_write_b128 v138, v[10:13] offset:9216
	s_waitcnt vmcnt(10)
	ds_write_b128 v138, v[14:17] offset:27648
	s_waitcnt vmcnt(9)
	v_and_b32_e32 v11, 0xffff0000, v2
	v_lshlrev_b32_e32 v10, 16, v2
	v_mul_f32_e32 v137, v11, v11
	v_lshlrev_b32_e32 v12, 16, v3
	v_fmac_f32_e32 v137, v10, v10
	v_and_b32_e32 v13, 0xffff0000, v3
	v_fmac_f32_e32 v137, v12, v12
	v_lshlrev_b32_e32 v14, 16, v4
	v_fmac_f32_e32 v137, v13, v13
	v_and_b32_e32 v15, 0xffff0000, v4
	v_fmac_f32_e32 v137, v14, v14
	v_lshlrev_b32_e32 v16, 16, v5
	v_fmac_f32_e32 v137, v15, v15
	v_and_b32_e32 v17, 0xffff0000, v5
	v_fmac_f32_e32 v137, v16, v16
	v_fmac_f32_e32 v137, v17, v17
	ds_write_b128 v138, v[2:5] offset:13824
	s_waitcnt vmcnt(8)
	ds_write_b128 v138, v[6:9] offset:32256
	v_add_u32_e32 v2, 0x4100, v140
	global_load_dwordx4 v[122:125], v140, s[36:37] offset:256
	global_load_dwordx4 v[126:129], v140, vcc offset:256
	global_load_dwordx4 v[114:117], v2, s[36:37]
	global_load_dwordx4 v[118:121], v2, vcc
	v_add_u32_e32 v2, 0x8100, v140
	global_load_dwordx4 v[106:109], v2, s[36:37]
	global_load_dwordx4 v[110:113], v2, vcc
	v_add_u32_e32 v2, 0xc100, v140
	global_load_dwordx4 v[98:101], v2, s[36:37]
	global_load_dwordx4 v[102:105], v2, vcc
	v_and_b32_e32 v2, 31, v34
	v_lshrrev_b32_e32 v3, 1, v34
	v_and_b32_e32 v4, 0x5f, v34
	v_and_or_b32 v2, v3, s90, v2
	v_mul_u32_u24_e32 v7, 0x48, v4
	v_add_u32_e32 v139, 0x1200, v138
	s_waitcnt lgkmcnt(0)
	s_barrier
; #define BLOAD(A_, B_, kt) do { _Pragma("unroll") for (int i = 0; i < 4; ++i) { \
;     A_[i] = *(const u32x4*)((const char*)Ap + (aoff + (unsigned)(32 * i * lda + (kt) * 64) * 2u)); B_[i] = *(const u32x4*)((const char*)Wt + (woff + (unsigned)(32 * i * K + (kt) * 64) * 2u)); } } while (0)
; #define BLOAD(A_, B_, kt) do { _Pragma("unroll") for (int i = 0; i < 4; ++i) { \
;     A_[i] = *(const u32x4*)((const char*)Ap + (aoff + (unsigned)(32 * i * lda + (kt) * 64) * 2u)); B_[i] = *(const u32x4*)((const char*)Wt + (woff + (unsigned)(32 * i * K + (kt) * 64) * 2u)); } } while (0)
; #define BSTORE(A_, B_, buf) do { _Pragma("unroll") for (int i = 0; i < 4; ++i) { \
;     *(u32x4*)&As[(buf) * GBUF + (srow + 32 * i) * LDT + sc8] = A_[i]; \
;     *(u32x4*)&Bs[(buf) * GBUF + (srow + 32 * i) * LDT + sc8] = B_[i]; } } while (0)
; template <bool ROWNORM, int NK>
; DI void gemm_main_bf(const u16* __restrict__ Ap, int lda, const u16* __restrict__ Wt, f32x16 (&acc)[2][2], char* smem, float* rinv_s) {
;     ...
; #pragma unroll
;   for (int kt = 0; kt < nk; kt += 2) {
;     BCOMP(0);
;     BSTORE(a1, b1, 1);
;     if (kt + 3 < nk) BLOAD(a1, b1, kt + 3);
;     __syncthreads();
;     BCOMP(1);
;     if (kt + 2 < nk) { BSTORE(a0, b0, 0); if (kt + 4 < nk) BLOAD(a0, b0, kt + 4); }
	s_nop 0
	v_and_b32_e32 v6, 16, v3
	v_mad_u64_u32 v[130:131], s[34:35], v2, s4, v[6:7]
	ds_read_b128 v[2:5], v130
	ds_read_b128 v[22:25], v130 offset:4608
	v_lshl_add_u32 v131, v7, 1, v6
	ds_read_b128 v[6:9], v131 offset:18432
	ds_read_b128 v[18:21], v131 offset:23040
	ds_read_b128 v[142:145], v130 offset:32
	ds_read_b128 v[154:157], v131 offset:18464
	ds_read_b128 v[158:161], v131 offset:23072
	s_waitcnt lgkmcnt(4)
	v_mfma_f32_32x32x16_bf16 v[34:49], v[2:5], v[6:9], 0
	s_waitcnt lgkmcnt(3)
	v_mfma_f32_32x32x16_bf16 v[50:65], v[2:5], v[18:21], 0
	s_waitcnt lgkmcnt(1)
	v_mfma_f32_32x32x16_bf16 v[34:49], v[142:145], v[154:157], v[34:49]
	s_waitcnt lgkmcnt(0)
	v_mfma_f32_32x32x16_bf16 v[50:65], v[142:145], v[158:161], v[50:65]
	ds_read_b128 v[142:145], v130 offset:4640
	v_mfma_f32_32x32x16_bf16 v[2:17], v[22:25], v[6:9], 0
	v_mfma_f32_32x32x16_bf16 v[18:33], v[22:25], v[18:21], 0
	s_waitcnt lgkmcnt(0)
	v_mfma_f32_32x32x16_bf16 v[2:17], v[142:145], v[154:157], v[2:17]
	v_mfma_f32_32x32x16_bf16 v[18:33], v[142:145], v[158:161], v[18:33]
	ds_read_b128 v[142:145], v130 offset:64
	ds_read_b128 v[154:157], v131 offset:18496
	ds_read_b128 v[158:161], v131 offset:23104
	s_waitcnt lgkmcnt(1)
	v_mfma_f32_32x32x16_bf16 v[34:49], v[142:145], v[154:157], v[34:49]
	s_waitcnt lgkmcnt(0)
	v_mfma_f32_32x32x16_bf16 v[50:65], v[142:145], v[158:161], v[50:65]
	ds_read_b128 v[142:145], v130 offset:4672
	s_waitcnt lgkmcnt(0)
	v_mfma_f32_32x32x16_bf16 v[2:17], v[142:145], v[154:157], v[2:17]
	v_mfma_f32_32x32x16_bf16 v[18:33], v[142:145], v[158:161], v[18:33]
	ds_read_b128 v[142:145], v130 offset:96
	ds_read_b128 v[154:157], v131 offset:18528
	ds_read_b128 v[158:161], v131 offset:23136
	s_waitcnt lgkmcnt(1)
	v_mfma_f32_32x32x16_bf16 v[34:49], v[142:145], v[154:157], v[34:49]
	s_waitcnt lgkmcnt(0)
	v_mfma_f32_32x32x16_bf16 v[50:65], v[142:145], v[158:161], v[50:65]
	ds_read_b128 v[142:145], v130 offset:4704
	s_waitcnt lgkmcnt(0)
	v_mfma_f32_32x32x16_bf16 v[2:17], v[142:145], v[154:157], v[2:17]
	v_mfma_f32_32x32x16_bf16 v[18:33], v[142:145], v[158:161], v[18:33]
	s_nop 0
	s_waitcnt vmcnt(15)
	v_lshlrev_b32_e32 v141, 16, v90
	v_and_b32_e32 v142, 0xffff0000, v90
	v_fmac_f32_e32 v134, v141, v141
	v_lshlrev_b32_e32 v143, 16, v91
	v_fmac_f32_e32 v134, v142, v142
	v_and_b32_e32 v144, 0xffff0000, v91
	v_fmac_f32_e32 v134, v143, v143
	v_lshlrev_b32_e32 v145, 16, v92
	v_fmac_f32_e32 v134, v144, v144
	v_and_b32_e32 v147, 0xffff0000, v92
	v_fmac_f32_e32 v134, v145, v145
	v_lshlrev_b32_e32 v148, 16, v93
	v_fmac_f32_e32 v134, v147, v147
	v_and_b32_e32 v149, 0xffff0000, v93
	v_fmac_f32_e32 v134, v148, v148
	v_fmac_f32_e32 v134, v149, v149
	ds_write_b128 v138, v[90:93] offset:36864
	s_waitcnt vmcnt(14)
	ds_write_b128 v138, v[94:97] offset:55296
	s_waitcnt vmcnt(13)
	v_lshlrev_b32_e32 v90, 16, v82
	v_and_b32_e32 v91, 0xffff0000, v82
	v_fmac_f32_e32 v135, v90, v90
	v_lshlrev_b32_e32 v92, 16, v83
	v_fmac_f32_e32 v135, v91, v91
	v_and_b32_e32 v93, 0xffff0000, v83
	v_fmac_f32_e32 v135, v92, v92
	v_lshlrev_b32_e32 v94, 16, v84
	v_fmac_f32_e32 v135, v93, v93
	v_and_b32_e32 v95, 0xffff0000, v84
	v_fmac_f32_e32 v135, v94, v94
	v_lshlrev_b32_e32 v96, 16, v85
	v_fmac_f32_e32 v135, v95, v95
	v_and_b32_e32 v97, 0xffff0000, v85
	v_fmac_f32_e32 v135, v96, v96
	v_fmac_f32_e32 v135, v97, v97
	ds_write_b128 v138, v[82:85] offset:41472
	s_waitcnt vmcnt(12)
	ds_write_b128 v138, v[86:89] offset:59904
	s_waitcnt vmcnt(11)
	v_lshlrev_b32_e32 v82, 16, v74
	v_and_b32_e32 v83, 0xffff0000, v74
	v_fmac_f32_e32 v136, v82, v82
	v_lshlrev_b32_e32 v84, 16, v75
	v_fmac_f32_e32 v136, v83, v83
	v_and_b32_e32 v85, 0xffff0000, v75
	v_fmac_f32_e32 v136, v84, v84
	v_lshlrev_b32_e32 v86, 16, v76
	v_fmac_f32_e32 v136, v85, v85
	v_and_b32_e32 v87, 0xffff0000, v76
	v_fmac_f32_e32 v136, v86, v86
	v_lshlrev_b32_e32 v88, 16, v77
	v_fmac_f32_e32 v136, v87, v87
	v_and_b32_e32 v89, 0xffff0000, v77
	v_fmac_f32_e32 v136, v88, v88
	v_fmac_f32_e32 v136, v89, v89
	ds_write_b128 v138, v[74:77] offset:46080
	s_waitcnt vmcnt(10)
	ds_write_b128 v138, v[78:81] offset:64512
	s_waitcnt vmcnt(9)
	v_lshlrev_b32_e32 v74, 16, v66
	v_and_b32_e32 v75, 0xffff0000, v66
	v_fmac_f32_e32 v137, v74, v74
	v_lshlrev_b32_e32 v76, 16, v67
	v_fmac_f32_e32 v137, v75, v75
	v_and_b32_e32 v77, 0xffff0000, v67
	v_fmac_f32_e32 v137, v76, v76
	v_lshlrev_b32_e32 v78, 16, v68
	v_fmac_f32_e32 v137, v77, v77
	v_and_b32_e32 v79, 0xffff0000, v68
	v_fmac_f32_e32 v137, v78, v78
	v_lshlrev_b32_e32 v80, 16, v69
	v_fmac_f32_e32 v137, v79, v79
	v_and_b32_e32 v81, 0xffff0000, v69
	v_fmac_f32_e32 v137, v80, v80
	v_fmac_f32_e32 v137, v81, v81
	ds_write_b128 v138, v[66:69] offset:50688
	s_waitcnt vmcnt(8)
	ds_write_b128 v139, v[70:73] offset:64512
	v_add_u32_e32 v66, 0x4180, v140
	global_load_dwordx4 v[90:93], v140, s[36:37] offset:384
	global_load_dwordx4 v[94:97], v140, vcc offset:384
	global_load_dwordx4 v[82:85], v66, s[36:37]
	global_load_dwordx4 v[86:89], v66, vcc
	v_add_u32_e32 v66, 0x8180, v140
	v_add_u32_e32 v70, 0xc180, v140
	global_load_dwordx4 v[74:77], v66, s[36:37]
	global_load_dwordx4 v[78:81], v66, vcc
	s_nop 0
	global_load_dwordx4 v[66:69], v70, s[36:37]
	s_nop 0
	global_load_dwordx4 v[70:73], v70, vcc
	s_waitcnt lgkmcnt(0)
	s_barrier
; #define BLOAD(A_, B_, kt) do { _Pragma("unroll") for (int i = 0; i < 4; ++i) { \
;     A_[i] = *(const u32x4*)((const char*)Ap + (aoff + (unsigned)(32 * i * lda + (kt) * 64) * 2u)); B_[i] = *(const u32x4*)((const char*)Wt + (woff + (unsigned)(32 * i * K + (kt) * 64) * 2u)); } } while (0)
; #define BLOAD(A_, B_, kt) do { _Pragma("unroll") for (int i = 0; i < 4; ++i) { \
;     A_[i] = *(const u32x4*)((const char*)Ap + (aoff + (unsigned)(32 * i * lda + (kt) * 64) * 2u)); B_[i] = *(const u32x4*)((const char*)Wt + (woff + (unsigned)(32 * i * K + (kt) * 64) * 2u)); } } while (0)
; #define BSTORE(A_, B_, buf) do { _Pragma("unroll") for (int i = 0; i < 4; ++i) { \
;     *(u32x4*)&As[(buf) * GBUF + (srow + 32 * i) * LDT + sc8] = A_[i]; \
;     *(u32x4*)&Bs[(buf) * GBUF + (srow + 32 * i) * LDT + sc8] = B_[i]; } } while (0)
; template <bool ROWNORM, int NK>
; DI void gemm_main_bf(const u16* __restrict__ Ap, int lda, const u16* __restrict__ Wt, f32x16 (&acc)[2][2], char* smem, float* rinv_s) {
;     ...
; #pragma unroll
;   for (int kt = 0; kt < nk; kt += 2) {
;     BCOMP(0);
;     BSTORE(a1, b1, 1);
;     if (kt + 3 < nk) BLOAD(a1, b1, kt + 3);
;     __syncthreads();
;     BCOMP(1);
;     if (kt + 2 < nk) { BSTORE(a0, b0, 0); if (kt + 4 < nk) BLOAD(a0, b0, kt + 4); }
;     __syncthreads();
	s_nop 0
	ds_read_b128 v[140:143], v130 offset:36864
	ds_read_b128 v[154:157], v131 offset:55296
	ds_read_b128 v[158:161], v131 offset:59904
	s_waitcnt lgkmcnt(1)
	v_mfma_f32_32x32x16_bf16 v[34:49], v[140:143], v[154:157], v[34:49]
	s_waitcnt lgkmcnt(0)
	v_mfma_f32_32x32x16_bf16 v[50:65], v[140:143], v[158:161], v[50:65]
	ds_read_b128 v[140:143], v130 offset:41472
	s_waitcnt lgkmcnt(0)
	v_mfma_f32_32x32x16_bf16 v[2:17], v[140:143], v[154:157], v[2:17]
	v_mfma_f32_32x32x16_bf16 v[18:33], v[140:143], v[158:161], v[18:33]
	ds_read_b128 v[140:143], v130 offset:36896
	ds_read_b128 v[154:157], v131 offset:55328
	ds_read_b128 v[158:161], v131 offset:59936
	s_waitcnt lgkmcnt(1)
	v_mfma_f32_32x32x16_bf16 v[34:49], v[140:143], v[154:157], v[34:49]
	s_waitcnt lgkmcnt(0)
	v_mfma_f32_32x32x16_bf16 v[50:65], v[140:143], v[158:161], v[50:65]
	ds_read_b128 v[140:143], v130 offset:41504
	s_waitcnt lgkmcnt(0)
	v_mfma_f32_32x32x16_bf16 v[2:17], v[140:143], v[154:157], v[2:17]
	v_mfma_f32_32x32x16_bf16 v[18:33], v[140:143], v[158:161], v[18:33]
	ds_read_b128 v[140:143], v130 offset:36928
	ds_read_b128 v[154:157], v131 offset:55360
	ds_read_b128 v[158:161], v131 offset:59968
	s_waitcnt lgkmcnt(1)
	v_mfma_f32_32x32x16_bf16 v[34:49], v[140:143], v[154:157], v[34:49]
	s_waitcnt lgkmcnt(0)
	v_mfma_f32_32x32x16_bf16 v[50:65], v[140:143], v[158:161], v[50:65]
	ds_read_b128 v[140:143], v130 offset:41536
	s_waitcnt lgkmcnt(0)
	v_mfma_f32_32x32x16_bf16 v[2:17], v[140:143], v[154:157], v[2:17]
	v_mfma_f32_32x32x16_bf16 v[18:33], v[140:143], v[158:161], v[18:33]
	ds_read_b128 v[140:143], v130 offset:36960
	ds_read_b128 v[154:157], v131 offset:55392
	ds_read_b128 v[158:161], v131 offset:60000
	s_waitcnt lgkmcnt(1)
	v_mfma_f32_32x32x16_bf16 v[34:49], v[140:143], v[154:157], v[34:49]
	s_waitcnt lgkmcnt(0)
	v_mfma_f32_32x32x16_bf16 v[50:65], v[140:143], v[158:161], v[50:65]
	ds_read_b128 v[140:143], v130 offset:41568
	s_waitcnt lgkmcnt(0)
	v_mfma_f32_32x32x16_bf16 v[2:17], v[140:143], v[154:157], v[2:17]
	v_mfma_f32_32x32x16_bf16 v[18:33], v[140:143], v[158:161], v[18:33]
	s_nop 0
	s_waitcnt vmcnt(15)
	v_lshlrev_b32_e32 v140, 16, v122
	v_and_b32_e32 v141, 0xffff0000, v122
	v_fmac_f32_e32 v134, v140, v140
	v_lshlrev_b32_e32 v142, 16, v123
	v_fmac_f32_e32 v134, v141, v141
	v_and_b32_e32 v143, 0xffff0000, v123
	v_fmac_f32_e32 v134, v142, v142
	v_lshlrev_b32_e32 v144, 16, v124
	v_fmac_f32_e32 v134, v143, v143
	v_and_b32_e32 v145, 0xffff0000, v124
	v_fmac_f32_e32 v134, v144, v144
	v_lshlrev_b32_e32 v147, 16, v125
	v_fmac_f32_e32 v134, v145, v145
	v_and_b32_e32 v148, 0xffff0000, v125
	v_fmac_f32_e32 v134, v147, v147
	v_fmac_f32_e32 v134, v148, v148
	ds_write_b128 v138, v[122:125]
	s_waitcnt vmcnt(14)
	ds_write_b128 v138, v[126:129] offset:18432
	s_waitcnt vmcnt(13)
	v_lshlrev_b32_e32 v122, 16, v114
	v_and_b32_e32 v123, 0xffff0000, v114
	v_fmac_f32_e32 v135, v122, v122
	v_lshlrev_b32_e32 v124, 16, v115
	v_fmac_f32_e32 v135, v123, v123
	v_and_b32_e32 v125, 0xffff0000, v115
	v_fmac_f32_e32 v135, v124, v124
	v_lshlrev_b32_e32 v126, 16, v116
	v_fmac_f32_e32 v135, v125, v125
	v_and_b32_e32 v127, 0xffff0000, v116
	v_fmac_f32_e32 v135, v126, v126
	v_lshlrev_b32_e32 v128, 16, v117
	v_fmac_f32_e32 v135, v127, v127
	v_and_b32_e32 v129, 0xffff0000, v117
	v_fmac_f32_e32 v135, v128, v128
	v_fmac_f32_e32 v135, v129, v129
	ds_write_b128 v138, v[114:117] offset:4608
	s_waitcnt vmcnt(12)
	ds_write_b128 v138, v[118:121] offset:23040
	s_waitcnt vmcnt(11)
	v_lshlrev_b32_e32 v114, 16, v106
	v_and_b32_e32 v115, 0xffff0000, v106
	v_fmac_f32_e32 v136, v114, v114
	v_lshlrev_b32_e32 v116, 16, v107
	v_fmac_f32_e32 v136, v115, v115
	v_and_b32_e32 v117, 0xffff0000, v107
	v_fmac_f32_e32 v136, v116, v116
	v_lshlrev_b32_e32 v118, 16, v108
	v_fmac_f32_e32 v136, v117, v117
	v_and_b32_e32 v119, 0xffff0000, v108
	v_fmac_f32_e32 v136, v118, v118
	v_lshlrev_b32_e32 v120, 16, v109
	v_fmac_f32_e32 v136, v119, v119
	v_and_b32_e32 v121, 0xffff0000, v109
	v_fmac_f32_e32 v136, v120, v120
	v_fmac_f32_e32 v136, v121, v121
	ds_write_b128 v138, v[106:109] offset:9216
	s_waitcnt vmcnt(10)
	ds_write_b128 v138, v[110:113] offset:27648
	s_waitcnt vmcnt(9)
	v_lshlrev_b32_e32 v106, 16, v98
	v_and_b32_e32 v107, 0xffff0000, v98
	v_fmac_f32_e32 v137, v106, v106
	v_lshlrev_b32_e32 v108, 16, v99
	v_fmac_f32_e32 v137, v107, v107
	v_and_b32_e32 v109, 0xffff0000, v99
	v_fmac_f32_e32 v137, v108, v108
	v_lshlrev_b32_e32 v110, 16, v100
	v_fmac_f32_e32 v137, v109, v109
	v_and_b32_e32 v111, 0xffff0000, v100
	v_fmac_f32_e32 v137, v110, v110
	v_lshlrev_b32_e32 v112, 16, v101
	v_fmac_f32_e32 v137, v111, v111
	v_and_b32_e32 v113, 0xffff0000, v101
	v_fmac_f32_e32 v137, v112, v112
	v_fmac_f32_e32 v137, v113, v113
	ds_write_b128 v138, v[98:101] offset:13824
	s_waitcnt vmcnt(8)
	ds_write_b128 v138, v[102:105] offset:32256
	s_waitcnt lgkmcnt(0)
	s_barrier
; #define BLOAD(A_, B_, kt) do { _Pragma("unroll") for (int i = 0; i < 4; ++i) { \
;     A_[i] = *(const u32x4*)((const char*)Ap + (aoff + (unsigned)(32 * i * lda + (kt) * 64) * 2u)); B_[i] = *(const u32x4*)((const char*)Wt + (woff + (unsigned)(32 * i * K + (kt) * 64) * 2u)); } } while (0)
; #define BLOAD(A_, B_, kt) do { _Pragma("unroll") for (int i = 0; i < 4; ++i) { \
;     A_[i] = *(const u32x4*)((const char*)Ap + (aoff + (unsigned)(32 * i * lda + (kt) * 64) * 2u)); B_[i] = *(const u32x4*)((const char*)Wt + (woff + (unsigned)(32 * i * K + (kt) * 64) * 2u)); } } while (0)
; #define BSTORE(A_, B_, buf) do { _Pragma("unroll") for (int i = 0; i < 4; ++i) { \
;     *(u32x4*)&As[(buf) * GBUF + (srow + 32 * i) * LDT + sc8] = A_[i]; \
;     *(u32x4*)&Bs[(buf) * GBUF + (srow + 32 * i) * LDT + sc8] = B_[i]; } } while (0)
; template <bool ROWNORM, int NK>
; DI void gemm_main_bf(const u16* __restrict__ Ap, int lda, const u16* __restrict__ Wt, f32x16 (&acc)[2][2], char* smem, float* rinv_s) {
;     ...
;     BCOMP(0);
;     BSTORE(a1, b1, 1);
;     if (kt + 3 < nk) BLOAD(a1, b1, kt + 3);
;     __syncthreads();
	s_nop 0
	ds_read_b128 v[98:101], v130
	ds_read_b128 v[102:105], v131 offset:18432
	ds_read_b128 v[106:109], v131 offset:23040
	s_waitcnt lgkmcnt(1)
	v_mfma_f32_32x32x16_bf16 v[34:49], v[98:101], v[102:105], v[34:49]
	s_waitcnt lgkmcnt(0)
	v_mfma_f32_32x32x16_bf16 v[50:65], v[98:101], v[106:109], v[50:65]
	ds_read_b128 v[98:101], v130 offset:4608
	s_waitcnt lgkmcnt(0)
	v_mfma_f32_32x32x16_bf16 v[2:17], v[98:101], v[102:105], v[2:17]
	v_mfma_f32_32x32x16_bf16 v[18:33], v[98:101], v[106:109], v[18:33]
	ds_read_b128 v[98:101], v130 offset:32
	ds_read_b128 v[102:105], v131 offset:18464
	ds_read_b128 v[106:109], v131 offset:23072
	s_waitcnt lgkmcnt(1)
	v_mfma_f32_32x32x16_bf16 v[34:49], v[98:101], v[102:105], v[34:49]
	s_waitcnt lgkmcnt(0)
	v_mfma_f32_32x32x16_bf16 v[50:65], v[98:101], v[106:109], v[50:65]
	ds_read_b128 v[98:101], v130 offset:4640
	s_waitcnt lgkmcnt(0)
	v_mfma_f32_32x32x16_bf16 v[2:17], v[98:101], v[102:105], v[2:17]
	v_mfma_f32_32x32x16_bf16 v[18:33], v[98:101], v[106:109], v[18:33]
	ds_read_b128 v[98:101], v130 offset:64
	ds_read_b128 v[102:105], v131 offset:18496
	ds_read_b128 v[106:109], v131 offset:23104
	s_waitcnt lgkmcnt(1)
	v_mfma_f32_32x32x16_bf16 v[34:49], v[98:101], v[102:105], v[34:49]
	s_waitcnt lgkmcnt(0)
	v_mfma_f32_32x32x16_bf16 v[50:65], v[98:101], v[106:109], v[50:65]
	ds_read_b128 v[98:101], v130 offset:4672
	s_waitcnt lgkmcnt(0)
	v_mfma_f32_32x32x16_bf16 v[2:17], v[98:101], v[102:105], v[2:17]
	v_mfma_f32_32x32x16_bf16 v[18:33], v[98:101], v[106:109], v[18:33]
	ds_read_b128 v[98:101], v130 offset:96
	ds_read_b128 v[102:105], v131 offset:18528
	ds_read_b128 v[106:109], v131 offset:23136
	s_waitcnt lgkmcnt(1)
	v_mfma_f32_32x32x16_bf16 v[34:49], v[98:101], v[102:105], v[34:49]
	s_waitcnt lgkmcnt(0)
	v_mfma_f32_32x32x16_bf16 v[50:65], v[98:101], v[106:109], v[50:65]
	ds_read_b128 v[98:101], v130 offset:4704
	s_waitcnt lgkmcnt(0)
	v_mfma_f32_32x32x16_bf16 v[2:17], v[98:101], v[102:105], v[2:17]
	v_mfma_f32_32x32x16_bf16 v[18:33], v[98:101], v[106:109], v[18:33]
	s_nop 0
	s_waitcnt vmcnt(7)
	v_lshlrev_b32_e32 v98, 16, v90
	v_and_b32_e32 v99, 0xffff0000, v90
	v_fmac_f32_e32 v134, v98, v98
	v_lshlrev_b32_e32 v100, 16, v91
	v_fmac_f32_e32 v134, v99, v99
	v_and_b32_e32 v101, 0xffff0000, v91
	v_fmac_f32_e32 v134, v100, v100
	v_lshlrev_b32_e32 v102, 16, v92
	v_fmac_f32_e32 v134, v101, v101
	v_and_b32_e32 v103, 0xffff0000, v92
	v_fmac_f32_e32 v134, v102, v102
	v_lshlrev_b32_e32 v104, 16, v93
	v_fmac_f32_e32 v134, v103, v103
	v_and_b32_e32 v105, 0xffff0000, v93
	v_fmac_f32_e32 v134, v104, v104
	v_fmac_f32_e32 v134, v105, v105
	ds_write_b128 v138, v[90:93] offset:36864
	s_waitcnt vmcnt(6)
	ds_write_b128 v138, v[94:97] offset:55296
	s_waitcnt vmcnt(5)
	v_lshlrev_b32_e32 v90, 16, v82
	v_and_b32_e32 v91, 0xffff0000, v82
	v_fmac_f32_e32 v135, v90, v90
	v_lshlrev_b32_e32 v92, 16, v83
	v_fmac_f32_e32 v135, v91, v91
	v_and_b32_e32 v93, 0xffff0000, v83
	v_fmac_f32_e32 v135, v92, v92
	v_lshlrev_b32_e32 v94, 16, v84
	v_fmac_f32_e32 v135, v93, v93
	v_and_b32_e32 v95, 0xffff0000, v84
	v_fmac_f32_e32 v135, v94, v94
	v_lshlrev_b32_e32 v96, 16, v85
	v_fmac_f32_e32 v135, v95, v95
	v_and_b32_e32 v97, 0xffff0000, v85
	v_fmac_f32_e32 v135, v96, v96
	v_fmac_f32_e32 v135, v97, v97
	ds_write_b128 v138, v[82:85] offset:41472
	s_waitcnt vmcnt(4)
	ds_write_b128 v138, v[86:89] offset:59904
	s_waitcnt vmcnt(3)
	v_lshlrev_b32_e32 v82, 16, v74
	v_and_b32_e32 v83, 0xffff0000, v74
	v_fmac_f32_e32 v136, v82, v82
	v_lshlrev_b32_e32 v84, 16, v75
	v_fmac_f32_e32 v136, v83, v83
	v_and_b32_e32 v85, 0xffff0000, v75
	v_fmac_f32_e32 v136, v84, v84
	v_lshlrev_b32_e32 v86, 16, v76
	v_fmac_f32_e32 v136, v85, v85
	v_and_b32_e32 v87, 0xffff0000, v76
	v_fmac_f32_e32 v136, v86, v86
	v_lshlrev_b32_e32 v88, 16, v77
	v_fmac_f32_e32 v136, v87, v87
	v_and_b32_e32 v89, 0xffff0000, v77
	v_fmac_f32_e32 v136, v88, v88
	v_fmac_f32_e32 v136, v89, v89
	ds_write_b128 v138, v[74:77] offset:46080
	s_waitcnt vmcnt(2)
	ds_write_b128 v138, v[78:81] offset:64512
	s_waitcnt vmcnt(1)
	v_lshlrev_b32_e32 v74, 16, v66
	v_and_b32_e32 v75, 0xffff0000, v66
	v_fmac_f32_e32 v137, v74, v74
	v_lshlrev_b32_e32 v76, 16, v67
	v_fmac_f32_e32 v137, v75, v75
	v_and_b32_e32 v77, 0xffff0000, v67
	v_fmac_f32_e32 v137, v76, v76
	v_lshlrev_b32_e32 v78, 16, v68
	v_fmac_f32_e32 v137, v77, v77
	v_and_b32_e32 v79, 0xffff0000, v68
	v_fmac_f32_e32 v137, v78, v78
	v_lshlrev_b32_e32 v80, 16, v69
	v_fmac_f32_e32 v137, v79, v79
	v_and_b32_e32 v81, 0xffff0000, v69
	v_fmac_f32_e32 v137, v80, v80
	v_fmac_f32_e32 v137, v81, v81
	ds_write_b128 v138, v[66:69] offset:50688
	s_waitcnt vmcnt(0)
	ds_write_b128 v139, v[70:73] offset:64512
	s_waitcnt lgkmcnt(0)
	s_barrier
; #define BLOAD(A_, B_, kt) do { _Pragma("unroll") for (int i = 0; i < 4; ++i) { \
;     A_[i] = *(const u32x4*)((const char*)Ap + (aoff + (unsigned)(32 * i * lda + (kt) * 64) * 2u)); B_[i] = *(const u32x4*)((const char*)Wt + (woff + (unsigned)(32 * i * K + (kt) * 64) * 2u)); } } while (0)
; #define BLOAD(A_, B_, kt) do { _Pragma("unroll") for (int i = 0; i < 4; ++i) { \
;     A_[i] = *(const u32x4*)((const char*)Ap + (aoff + (unsigned)(32 * i * lda + (kt) * 64) * 2u)); B_[i] = *(const u32x4*)((const char*)Wt + (woff + (unsigned)(32 * i * K + (kt) * 64) * 2u)); } } while (0)
; #define BSTORE(A_, B_, buf) do { _Pragma("unroll") for (int i = 0; i < 4; ++i) { \
;     *(u32x4*)&As[(buf) * GBUF + (srow + 32 * i) * LDT + sc8] = A_[i]; \
;     *(u32x4*)&Bs[(buf) * GBUF + (srow + 32 * i) * LDT + sc8] = B_[i]; } } while (0)
; template <bool ROWNORM, int NK>
; DI void gemm_main_bf(const u16* __restrict__ Ap, int lda, const u16* __restrict__ Wt, f32x16 (&acc)[2][2], char* smem, float* rinv_s) {
;     ...
;     BCOMP(1);
;     if (kt + 2 < nk) { BSTORE(a0, b0, 0); if (kt + 4 < nk) BLOAD(a0, b0, kt + 4); }
;     __syncthreads();
;   }
;     ...
;   if constexpr (ROWNORM) {
; #pragma unroll
;     for (int i = 0; i < 4; ++i) {
;       float s = ss[i]; s += __shfl_xor(s, 1); s += __shfl_xor(s, 2); s += __shfl_xor(s, 4);
;       if ((tid & 7) == 0) rinv_s[srow + 32 * i] = rsqrtf(s / (float)K + EPS);
;     }
	s_nop 0
	ds_read_b128 v[66:69], v130 offset:36864
	ds_read_b128 v[70:73], v131 offset:55296
	ds_read_b128 v[74:77], v131 offset:59904
	s_waitcnt lgkmcnt(1)
	v_mfma_f32_32x32x16_bf16 v[34:49], v[66:69], v[70:73], v[34:49]
	s_waitcnt lgkmcnt(0)
	v_mfma_f32_32x32x16_bf16 v[50:65], v[66:69], v[74:77], v[50:65]
	ds_read_b128 v[66:69], v130 offset:41472
	s_waitcnt lgkmcnt(0)
	v_mfma_f32_32x32x16_bf16 v[2:17], v[66:69], v[70:73], v[2:17]
	v_mfma_f32_32x32x16_bf16 v[18:33], v[66:69], v[74:77], v[18:33]
	ds_read_b128 v[66:69], v130 offset:36896
	ds_read_b128 v[70:73], v131 offset:55328
	ds_read_b128 v[74:77], v131 offset:59936
	s_waitcnt lgkmcnt(1)
	v_mfma_f32_32x32x16_bf16 v[34:49], v[66:69], v[70:73], v[34:49]
	s_waitcnt lgkmcnt(0)
	v_mfma_f32_32x32x16_bf16 v[50:65], v[66:69], v[74:77], v[50:65]
	ds_read_b128 v[66:69], v130 offset:41504
	s_waitcnt lgkmcnt(0)
	v_mfma_f32_32x32x16_bf16 v[2:17], v[66:69], v[70:73], v[2:17]
	v_mfma_f32_32x32x16_bf16 v[18:33], v[66:69], v[74:77], v[18:33]
	ds_read_b128 v[66:69], v130 offset:36928
	ds_read_b128 v[70:73], v131 offset:55360
	ds_read_b128 v[74:77], v131 offset:59968
	s_waitcnt lgkmcnt(1)
	v_mfma_f32_32x32x16_bf16 v[34:49], v[66:69], v[70:73], v[34:49]
	s_waitcnt lgkmcnt(0)
	v_mfma_f32_32x32x16_bf16 v[50:65], v[66:69], v[74:77], v[50:65]
	ds_read_b128 v[66:69], v130 offset:41536
	s_waitcnt lgkmcnt(0)
	v_mfma_f32_32x32x16_bf16 v[2:17], v[66:69], v[70:73], v[2:17]
	v_mfma_f32_32x32x16_bf16 v[18:33], v[66:69], v[74:77], v[18:33]
	ds_read_b128 v[66:69], v130 offset:36960
	ds_read_b128 v[70:73], v131 offset:55392
	ds_read_b128 v[74:77], v131 offset:60000
	s_waitcnt lgkmcnt(1)
	v_mfma_f32_32x32x16_bf16 v[34:49], v[66:69], v[70:73], v[34:49]
	s_waitcnt lgkmcnt(0)
	v_mfma_f32_32x32x16_bf16 v[50:65], v[66:69], v[74:77], v[50:65]
	ds_read_b128 v[66:69], v130 offset:41568
	s_waitcnt lgkmcnt(0)
	v_mfma_f32_32x32x16_bf16 v[2:17], v[66:69], v[70:73], v[2:17]
	v_mfma_f32_32x32x16_bf16 v[18:33], v[66:69], v[74:77], v[18:33]
	s_nop 0
	v_cmp_lt_i32_e32 vcc, v200, v194
	s_barrier
	s_nop 0
	v_cndmask_b32_e32 v66, v193, v200, vcc
	v_lshlrev_b32_e32 v66, 2, v66
	ds_bpermute_b32 v69, v66, v134
	v_cmp_lt_i32_e32 vcc, v199, v194
	s_waitcnt lgkmcnt(0)
	v_add_f32_e32 v69, v134, v69
	v_cndmask_b32_e32 v67, v193, v199, vcc
	v_lshlrev_b32_e32 v67, 2, v67
	ds_bpermute_b32 v70, v67, v69
	v_cmp_lt_i32_e32 vcc, v198, v194
	s_waitcnt lgkmcnt(0)
	v_add_f32_e32 v69, v69, v70
	v_cndmask_b32_e32 v68, v193, v198, vcc
	v_lshlrev_b32_e32 v68, 2, v68
	ds_bpermute_b32 v70, v68, v69
	v_cmp_eq_u32_e32 vcc, 0, v133
	s_and_saveexec_b64 s[34:35], vcc
	s_cbranch_execz .LBB1_345
	s_waitcnt lgkmcnt(0)
	v_add_f32_e32 v69, v69, v70
	v_fmamk_f32 v69, v69, 0x3b800000, v188
	v_mul_f32_e32 v70, 0x4b800000, v69
	v_cmp_gt_f32_e64 s[36:37], s39, v69
	s_nop 1
	v_cndmask_b32_e64 v69, v69, v70, s[36:37]
	v_rsq_f32_e32 v69, v69
	s_nop 0
	v_mul_f32_e32 v70, 0x45800000, v69
	v_cndmask_b32_e64 v69, v69, v70, s[36:37]
	v_lshl_add_u32 v70, v0, 2, v201
	ds_write_b32 v70, v69

; DI int TID() { int t = (int)__builtin_amdgcn_workitem_id_x(); asm volatile("" : "+v"(t)); return t; }
; DI int crow(int r, int hi) { return (r & 3) + 8 * (r >> 2) + 4 * hi; }
; DI void acc_to_cs(const f32x16 (&acc)[2][2], float* Cs) {
;   __builtin_amdgcn_s_setprio(2);
;   const int tid = TID(), lane = tid & 63, w = tid >> 6, wm = w >> 1, wn = w & 1, r32 = lane & 31, hi = lane >> 5;
; #pragma unroll
;   for (int mt = 0; mt < 2; ++mt)
; #pragma unroll
;     for (int nt = 0; nt < 2; ++nt)
; #pragma unroll
;       for (int r = 0; r < 16; ++r) Cs[(wm * 64 + mt * 32 + crow(r, hi)) * CSL + wn * 64 + nt * 32 + r32] = acc[mt][nt][r];
;   __syncthreads();
; }
; DI void tile_mla_up(const Params& p, int l, const Chunk& ck, int tile, char* smem) {
;     ...
;     const float rinv = rinv_s[row]; const float* gain = (const float*)(p.ws + OFF_GAINS) + GN_MK + l * 96;
;     float ssq = 0.f; float x[32];
;     if (half == 0) {
; #pragma unroll
;       for (int c8 = 0; c8 < 8; ++c8) { cs_ld8(Cs, row, c8 * 8, v);
; #pragma unroll
;         for (int j = 0; j < 8; ++j) ssq += v[j] * v[j]; }
;       ssq *= rinv * rinv;
;     } else {
;       const u16* kr = (const u16*)(p.ws + OFF_KR) + (size_t)lt * 32;
; #pragma unroll
;       for (int c8 = 0; c8 < 4; ++c8) { const u32x4 u = *(const u32x4*)(kr + c8 * 8); unpack8(u, v);
; #pragma unroll
;         for (int j = 0; j < 8; ++j) { x[c8 * 8 + j] = v[j]; ssq += v[j] * v[j]; } }
;     }
;     ssq += __shfl_xor(ssq, 1);
.LBB1_351:
	s_or_b64 exec, exec, s[34:35]
	s_nop 0
	v_mov_b32_e32 v0, v172
	v_cmp_ne_u32_e32 vcc, 0, v152
	v_lshrrev_b32_e32 v67, 1, v0
	v_and_b32_e32 v67, 0xfffffc0, v67
	s_waitcnt lgkmcnt(0)
	v_lshrrev_b32_e32 v68, 3, v0
	v_and_or_b32 v67, v68, 4, v67
	v_and_b32_e32 v0, 0x5f, v0
	v_mul_lo_u32 v67, v67, s5
	v_lshl_add_u32 v0, v0, 2, v67
	ds_write2_b32 v0, v34, v50 offset1:32
	ds_write2_b32 v0, v35, v51 offset0:132 offset1:164
	v_add_u32_e32 v34, 0x400, v0
	ds_write2_b32 v34, v36, v52 offset0:8 offset1:40
	ds_write2_b32 v34, v37, v53 offset0:140 offset1:172
	v_add_u32_e32 v34, 0x1000, v0
	ds_write2_b32 v34, v38, v54 offset0:32 offset1:64
	ds_write2_b32 v34, v39, v55 offset0:164 offset1:196
	v_add_u32_e32 v34, 0x1400, v0
	ds_write2_b32 v34, v40, v56 offset0:40 offset1:72
	ds_write2_b32 v34, v41, v57 offset0:172 offset1:204
	v_add_u32_e32 v34, 0x2000, v0
	ds_write2_b32 v34, v42, v58 offset0:64 offset1:96
	ds_write2_b32 v34, v43, v59 offset0:196 offset1:228
	v_add_u32_e32 v34, 0x2400, v0
	ds_write2_b32 v34, v44, v60 offset0:72 offset1:104
	ds_write2_b32 v34, v45, v61 offset0:204 offset1:236
	v_add_u32_e32 v34, 0x3000, v0
	ds_write2_b32 v34, v46, v62 offset0:96 offset1:128
	v_add_u32_e32 v34, 0x3200, v0
	ds_write2_b32 v34, v47, v63 offset0:100 offset1:132
	v_add_u32_e32 v34, 0x3400, v0
	ds_write2_b32 v34, v48, v64 offset0:104 offset1:136
	v_add_u32_e32 v34, 0x3600, v0
	ds_write2_b32 v34, v49, v65 offset0:108 offset1:140
	v_add_u32_e32 v34, 0x4000, v0
	ds_write2_b32 v34, v2, v18 offset0:128 offset1:160
	v_add_u32_e32 v2, 0x4400, v0
	ds_write2_b32 v2, v3, v19 offset0:4 offset1:36
	ds_write2_b32 v2, v4, v20 offset0:136 offset1:168
	v_add_u32_e32 v2, 0x4800, v0
	ds_write2_b32 v2, v5, v21 offset0:12 offset1:44
	v_add_u32_e32 v2, 0x5000, v0
	ds_write2_b32 v2, v6, v22 offset0:160 offset1:192
	v_add_u32_e32 v2, 0x5400, v0
	ds_write2_b32 v2, v7, v23 offset0:36 offset1:68
	ds_write2_b32 v2, v8, v24 offset0:168 offset1:200
	v_add_u32_e32 v2, 0x5800, v0
	ds_write2_b32 v2, v9, v25 offset0:44 offset1:76
	v_add_u32_e32 v2, 0x6000, v0
	ds_write2_b32 v2, v10, v26 offset0:192 offset1:224
	v_add_u32_e32 v2, 0x6400, v0
	ds_write2_b32 v2, v11, v27 offset0:68 offset1:100
	ds_write2_b32 v2, v12, v28 offset0:200 offset1:232
	v_add_u32_e32 v2, 0x6800, v0
	ds_write2_b32 v2, v13, v29 offset0:76 offset1:108
	v_add_u32_e32 v2, 0x7200, v0
	ds_write2_b32 v2, v14, v30 offset0:96 offset1:128
	v_add_u32_e32 v2, 0x7400, v0
	ds_write2_b32 v2, v15, v31 offset0:100 offset1:132
	v_add_u32_e32 v2, 0x7600, v0
	v_add_u32_e32 v0, 0x7800, v0
	ds_write2_b32 v0, v17, v33 offset0:108 offset1:140
	v_lshl_add_u32 v0, v151, 2, v201
	ds_write2_b32 v2, v16, v32 offset0:104 offset1:136
	s_waitcnt lgkmcnt(0)
	s_barrier
	ds_read_b32 v2, v0
	v_ashrrev_i32_e32 v147, 31, v146
	s_and_saveexec_b64 s[34:35], vcc
	s_xor_b64 s[36:37], exec, s[34:35]
	s_cbranch_execz .LBB1_353
	v_lshlrev_b64 v[4:5], 6, v[146:147]
	v_lshl_add_u64 v[4:5], s[46:47], 0, v[4:5]
	global_load_dwordx4 v[26:29], v[4:5], off offset:16
	global_load_dwordx4 v[12:15], v[4:5], off
	global_load_dwordx4 v[18:21], v[4:5], off offset:32
	global_load_dwordx4 v[40:43], v[4:5], off offset:48
	s_waitcnt vmcnt(3)
	v_lshlrev_b32_e32 v8, 16, v26
	s_waitcnt vmcnt(2)
	v_lshlrev_b32_e32 v4, 16, v12
	v_and_b32_e32 v5, 0xffff0000, v12
	v_lshlrev_b32_e32 v10, 16, v13
	v_and_b32_e32 v11, 0xffff0000, v13
	v_pk_mul_f32 v[30:31], v[4:5], v[4:5]
	s_waitcnt vmcnt(1)
	v_lshlrev_b32_e32 v24, 16, v20
	v_and_b32_e32 v25, 0xffff0000, v20
	s_waitcnt vmcnt(0)
	v_and_b32_e32 v33, 0xffff0000, v40
	v_and_b32_e32 v32, 0xffff0000, v26
	v_lshlrev_b32_e32 v37, 16, v41
	v_lshlrev_b32_e32 v36, 16, v40
	v_and_b32_e32 v20, 0xffff0000, v41
	v_and_b32_e32 v53, 0xffff0000, v42
	v_lshlrev_b32_e32 v41, 16, v43
	v_lshlrev_b32_e32 v40, 16, v42
	v_and_b32_e32 v26, 0xffff0000, v43
	v_pk_mul_f32 v[42:43], v[10:11], v[10:11]
	v_add_f32_e32 v0, v30, v31
	v_lshlrev_b32_e32 v12, 16, v14
	v_and_b32_e32 v13, 0xffff0000, v14
	v_add_f32_e32 v0, v42, v0
	v_pk_mul_f32 v[46:47], v[12:13], v[12:13]
	v_add_f32_e32 v0, v43, v0
	v_lshlrev_b32_e32 v16, 16, v18
	v_and_b32_e32 v17, 0xffff0000, v18
	v_lshlrev_b32_e32 v22, 16, v19
	v_and_b32_e32 v23, 0xffff0000, v19
	v_lshlrev_b32_e32 v18, 16, v15
	v_and_b32_e32 v19, 0xffff0000, v15
	v_add_f32_e32 v0, v46, v0
	v_pk_mul_f32 v[56:57], v[18:19], v[18:19]
	v_add_f32_e32 v0, v47, v0
	v_lshlrev_b32_e32 v9, 16, v27
	v_add_f32_e32 v0, v56, v0
	v_pk_mul_f32 v[14:15], v[8:9], v[8:9]
	v_add_f32_e32 v0, v57, v0
	v_add_f32_e32 v0, v14, v0
	v_fmac_f32_e32 v0, v32, v32
	v_lshlrev_b32_e32 v7, 16, v29
	v_lshlrev_b32_e32 v6, 16, v28
	v_and_b32_e32 v34, 0xffff0000, v27
	v_add_f32_e32 v0, v15, v0
	v_and_b32_e32 v52, 0xffff0000, v28
	v_and_b32_e32 v54, 0xffff0000, v29
	v_pk_mul_f32 v[28:29], v[6:7], v[6:7]
	v_fmac_f32_e32 v0, v34, v34
	v_add_f32_e32 v0, v28, v0
	v_fmac_f32_e32 v0, v52, v52
	v_add_f32_e32 v0, v29, v0
	v_pk_mul_f32 v[38:39], v[16:17], v[16:17]
	v_fmac_f32_e32 v0, v54, v54
	v_add_f32_e32 v0, v38, v0
	v_pk_mul_f32 v[44:45], v[22:23], v[22:23]
	v_add_f32_e32 v0, v39, v0
	v_add_f32_e32 v0, v44, v0
	v_pk_mul_f32 v[48:49], v[24:25], v[24:25]
	v_add_f32_e32 v0, v45, v0
	v_lshlrev_b32_e32 v50, 16, v21
	v_and_b32_e32 v51, 0xffff0000, v21
	v_add_f32_e32 v0, v48, v0
	v_pk_mul_f32 v[58:59], v[50:51], v[50:51]
	v_add_f32_e32 v0, v49, v0
	v_pk_mov_b32 v[60:61], v[32:33], v[36:37] op_sel:[1,0]
	v_add_f32_e32 v0, v58, v0
	v_pk_mul_f32 v[60:61], v[60:61], v[60:61]
	v_add_f32_e32 v0, v59, v0
	v_mov_b32_e32 v21, v37
	v_add_f32_e32 v0, v61, v0
	v_pk_mul_f32 v[64:65], v[20:21], v[20:21]
	v_add_f32_e32 v0, v60, v0
	v_pk_mov_b32 v[62:63], v[52:53], v[40:41] op_sel:[1,0]
	v_add_f32_e32 v0, v65, v0
	v_pk_mul_f32 v[62:63], v[62:63], v[62:63]
	v_add_f32_e32 v0, v64, v0
	v_mov_b32_e32 v27, v41
	v_add_f32_e32 v0, v63, v0
	v_pk_mul_f32 v[68:69], v[26:27], v[26:27]
	v_add_f32_e32 v0, v62, v0
	v_add_f32_e32 v0, v69, v0
	v_add_f32_e32 v0, v68, v0

; DI int TID() { int t = (int)__builtin_amdgcn_workitem_id_x(); asm volatile("" : "+v"(t)); return t; }
; #define BLOAD(A_, B_, kt) do { _Pragma("unroll") for (int i = 0; i < 4; ++i) { \
;     A_[i] = *(const u32x4*)((const char*)Ap + (aoff + (unsigned)(32 * i * lda + (kt) * 64) * 2u)); B_[i] = *(const u32x4*)((const char*)Wt + (woff + (unsigned)(32 * i * K + (kt) * 64) * 2u)); } } while (0)
; #define BLOAD(A_, B_, kt) do { _Pragma("unroll") for (int i = 0; i < 4; ++i) { \
;     A_[i] = *(const u32x4*)((const char*)Ap + (aoff + (unsigned)(32 * i * lda + (kt) * 64) * 2u)); B_[i] = *(const u32x4*)((const char*)Wt + (woff + (unsigned)(32 * i * K + (kt) * 64) * 2u)); } } while (0)
; #define BSTORE(A_, B_, buf) do { _Pragma("unroll") for (int i = 0; i < 4; ++i) { \
;     *(u32x4*)&As[(buf) * GBUF + (srow + 32 * i) * LDT + sc8] = A_[i]; \
;     *(u32x4*)&Bs[(buf) * GBUF + (srow + 32 * i) * LDT + sc8] = B_[i]; } } while (0)
; template <bool ROWNORM, int NK>
; DI void gemm_main_bf(const u16* __restrict__ Ap, int lda, const u16* __restrict__ Wt, f32x16 (&acc)[2][2], char* smem, float* rinv_s) {
;     ...
;   const int tid = TID(), lane = tid & 63, w = tid >> 6, wm = w >> 1, wn = w & 1, r32 = lane & 31, hi = lane >> 5;
;   u16* As = (u16*)smem; u16* Bs = As + 128 * LDT;
;   const int srow = tid >> 3, sc8 = (tid & 7) * 8;
;   float ss[4] = {0.f, 0.f, 0.f, 0.f};
;   u32x4 a0[4], b0[4], a1[4], b1[4];
;   constexpr int nk = NK;
;   const unsigned aoff = (unsigned)(srow * lda + sc8) * 2u, woff = (unsigned)(srow * K + sc8) * 2u;
;     ...
;   __builtin_amdgcn_s_setprio(0);
;   BLOAD(a0, b0, 0); BLOAD(a1, b1, 1);
;   __syncthreads();
;   BSTORE(a0, b0, 0);
;   BLOAD(a0, b0, 2);
;   __syncthreads();
; DI void tile_mla_up(const Params& p, int l, const Chunk& ck, int tile, char* smem) {
;     ...
;   if (ni < 8) {
;     const int h = ni;
;     gemm_main_bf<true, 6>((const u16*)(p.ws + OFF_CQ) + (size_t)m0 * 384, 384, (const u16*)(p.ws + OFF_WQB + l * SZ_WQB) + (size_t)h * 128 * 384, acc, smem, rinv_s);
.LBB1_360:
	s_mulk_i32 s52, 0x300
	s_add_u32 s36, s92, s52
	s_addc_u32 s37, s93, 0
	s_mul_i32 s34, s79, 0x18000
	s_mul_hi_i32 s0, s79, 0x18000
	s_add_u32 s40, s94, s34
	v_mov_b32_e32 v18, v172
	s_addc_u32 s41, s22, s0
	s_movk_i32 s0, 0x180
	v_ashrrev_i32_e32 v0, 3, v18
	v_and_b32_e32 v147, 7, v18
	v_lshlrev_b32_e32 v19, 3, v147
	v_mul_lo_u32 v2, v0, s0
	v_or_b32_e32 v2, v2, v19
	v_lshlrev_b32_e32 v159, 1, v2
	s_nop 0
	global_load_dwordx4 v[20:23], v159, s[36:37]
	global_load_dwordx4 v[24:27], v159, s[40:41]
	v_add_u32_e32 v2, 0x6000, v159
	global_load_dwordx4 v[28:31], v2, s[36:37]
	global_load_dwordx4 v[32:35], v2, s[40:41]
	v_add_u32_e32 v2, 0xc000, v159
	global_load_dwordx4 v[10:13], v2, s[36:37]
	s_waitcnt lgkmcnt(0)
	global_load_dwordx4 v[14:17], v2, s[40:41]
	v_add_u32_e32 v6, 0x12000, v159
	global_load_dwordx4 v[2:5], v6, s[36:37]
	s_nop 0
	global_load_dwordx4 v[6:9], v6, s[40:41]
	v_add_u32_e32 v37, 0x6080, v159
	global_load_dwordx4 v[90:93], v159, s[36:37] offset:128
	global_load_dwordx4 v[94:97], v159, s[40:41] offset:128
	global_load_dwordx4 v[82:85], v37, s[36:37]
	global_load_dwordx4 v[86:89], v37, s[40:41]
	v_add_u32_e32 v37, 0xc080, v159
	global_load_dwordx4 v[74:77], v37, s[36:37]
	global_load_dwordx4 v[78:81], v37, s[40:41]
	v_add_u32_e32 v37, 0x12080, v159
	global_load_dwordx4 v[66:69], v37, s[36:37]
	global_load_dwordx4 v[70:73], v37, s[40:41]
	s_barrier
	v_and_b32_e32 v36, 31, v18
	s_waitcnt vmcnt(15)
	v_and_b32_e32 v38, 0xffff0000, v20
	v_lshlrev_b32_e32 v37, 16, v20
	v_mul_f32_e32 v153, v38, v38
	v_lshlrev_b32_e32 v39, 16, v21
	v_fmac_f32_e32 v153, v37, v37
	v_and_b32_e32 v40, 0xffff0000, v21
	v_fmac_f32_e32 v153, v39, v39
	v_lshlrev_b32_e32 v41, 16, v22
	v_fmac_f32_e32 v153, v40, v40
	v_and_b32_e32 v42, 0xffff0000, v22
	v_fmac_f32_e32 v153, v41, v41
	v_lshlrev_b32_e32 v43, 16, v23
	v_fmac_f32_e32 v153, v42, v42
	v_and_b32_e32 v44, 0xffff0000, v23
	v_fmac_f32_e32 v153, v43, v43
	v_mul_lo_u32 v37, v0, s91
	v_fmac_f32_e32 v153, v44, v44
	v_add_lshl_u32 v157, v37, v19, 1
	ds_write_b128 v157, v[20:23]
	s_waitcnt vmcnt(14)
	ds_write_b128 v157, v[24:27] offset:18432
	s_waitcnt vmcnt(13)
	v_and_b32_e32 v20, 0xffff0000, v28
	v_lshlrev_b32_e32 v19, 16, v28
	v_mul_f32_e32 v154, v20, v20
	s_waitcnt vmcnt(11)
	v_and_b32_e32 v20, 0xffff0000, v10
	v_lshlrev_b32_e32 v21, 16, v29
	v_fmac_f32_e32 v154, v19, v19
	v_lshlrev_b32_e32 v19, 16, v10
	v_mul_f32_e32 v155, v20, v20
	v_and_b32_e32 v22, 0xffff0000, v29
	v_fmac_f32_e32 v154, v21, v21
	v_lshlrev_b32_e32 v21, 16, v11
	v_fmac_f32_e32 v155, v19, v19
	v_lshlrev_b32_e32 v23, 16, v30
	v_fmac_f32_e32 v154, v22, v22
	v_and_b32_e32 v22, 0xffff0000, v11
	v_fmac_f32_e32 v155, v21, v21
	v_and_b32_e32 v24, 0xffff0000, v30
	v_fmac_f32_e32 v154, v23, v23
	v_lshlrev_b32_e32 v23, 16, v12
	v_fmac_f32_e32 v155, v22, v22
	v_lshlrev_b32_e32 v25, 16, v31
	v_fmac_f32_e32 v154, v24, v24
	v_and_b32_e32 v24, 0xffff0000, v12
	v_fmac_f32_e32 v155, v23, v23
	v_and_b32_e32 v26, 0xffff0000, v31
	v_fmac_f32_e32 v154, v25, v25
	v_lshlrev_b32_e32 v25, 16, v13
	v_fmac_f32_e32 v155, v24, v24
	v_fmac_f32_e32 v154, v26, v26
	v_and_b32_e32 v26, 0xffff0000, v13
	v_fmac_f32_e32 v155, v25, v25
	v_fmac_f32_e32 v155, v26, v26
	ds_write_b128 v157, v[28:31] offset:4608
	ds_write_b128 v157, v[32:35] offset:23040
	ds_write_b128 v157, v[10:13] offset:9216
	s_waitcnt vmcnt(10)
	ds_write_b128 v157, v[14:17] offset:27648
	s_waitcnt vmcnt(9)
	v_and_b32_e32 v11, 0xffff0000, v2
	v_lshlrev_b32_e32 v10, 16, v2
	v_mul_f32_e32 v156, v11, v11
	v_lshlrev_b32_e32 v12, 16, v3
	v_fmac_f32_e32 v156, v10, v10
	v_and_b32_e32 v13, 0xffff0000, v3
	v_fmac_f32_e32 v156, v12, v12
	v_lshlrev_b32_e32 v14, 16, v4
	v_fmac_f32_e32 v156, v13, v13
	v_and_b32_e32 v15, 0xffff0000, v4
	v_fmac_f32_e32 v156, v14, v14
	v_lshlrev_b32_e32 v16, 16, v5
	v_fmac_f32_e32 v156, v15, v15
	v_and_b32_e32 v17, 0xffff0000, v5
	v_fmac_f32_e32 v156, v16, v16
	v_fmac_f32_e32 v156, v17, v17
	ds_write_b128 v157, v[2:5] offset:13824
	s_waitcnt vmcnt(8)
	ds_write_b128 v157, v[6:9] offset:32256
	v_add_u32_e32 v2, 0x100, v159
	global_load_dwordx4 v[130:133], v2, s[36:37]
	global_load_dwordx4 v[134:137], v2, s[40:41]
	v_add_u32_e32 v2, 0x6100, v159
	global_load_dwordx4 v[114:117], v2, s[36:37]
	global_load_dwordx4 v[118:121], v2, s[40:41]
	v_add_u32_e32 v2, 0xc100, v159
	global_load_dwordx4 v[106:109], v2, s[36:37]
	global_load_dwordx4 v[110:113], v2, s[40:41]
	v_add_u32_e32 v2, 0x12100, v159
	global_load_dwordx4 v[98:101], v2, s[36:37]
	global_load_dwordx4 v[102:105], v2, s[40:41]
	v_lshrrev_b32_e32 v2, 1, v18
	v_and_b32_e32 v4, 0x5f, v18
	v_and_or_b32 v3, v2, s90, v36
	v_mul_u32_u24_e32 v7, 0x48, v4
	v_add_u32_e32 v158, 0x1200, v157
	s_waitcnt lgkmcnt(0)
	s_barrier
; #define BLOAD(A_, B_, kt) do { _Pragma("unroll") for (int i = 0; i < 4; ++i) { \
;     A_[i] = *(const u32x4*)((const char*)Ap + (aoff + (unsigned)(32 * i * lda + (kt) * 64) * 2u)); B_[i] = *(const u32x4*)((const char*)Wt + (woff + (unsigned)(32 * i * K + (kt) * 64) * 2u)); } } while (0)
; #define BLOAD(A_, B_, kt) do { _Pragma("unroll") for (int i = 0; i < 4; ++i) { \
;     A_[i] = *(const u32x4*)((const char*)Ap + (aoff + (unsigned)(32 * i * lda + (kt) * 64) * 2u)); B_[i] = *(const u32x4*)((const char*)Wt + (woff + (unsigned)(32 * i * K + (kt) * 64) * 2u)); } } while (0)
; #define BSTORE(A_, B_, buf) do { _Pragma("unroll") for (int i = 0; i < 4; ++i) { \
;     *(u32x4*)&As[(buf) * GBUF + (srow + 32 * i) * LDT + sc8] = A_[i]; \
;     *(u32x4*)&Bs[(buf) * GBUF + (srow + 32 * i) * LDT + sc8] = B_[i]; } } while (0)
; template <bool ROWNORM, int NK>
; DI void gemm_main_bf(const u16* __restrict__ Ap, int lda, const u16* __restrict__ Wt, f32x16 (&acc)[2][2], char* smem, float* rinv_s) {
;     ...
; #pragma unroll
;   for (int kt = 0; kt < nk; kt += 2) {
;     BCOMP(0);
;     BSTORE(a1, b1, 1);
;     if (kt + 3 < nk) BLOAD(a1, b1, kt + 3);
;     __syncthreads();
	s_nop 0
	v_and_b32_e32 v6, 16, v2
	v_mad_u64_u32 v[148:149], s[34:35], v3, s4, v[6:7]
	ds_read_b128 v[2:5], v148
	ds_read_b128 v[22:25], v148 offset:4608
	v_lshl_add_u32 v149, v7, 1, v6
	ds_read_b128 v[6:9], v149 offset:18432
	ds_read_b128 v[18:21], v149 offset:23040
	ds_read_b128 v[122:125], v148 offset:32
	ds_read_b128 v[126:129], v149 offset:18464
	ds_read_b128 v[138:141], v149 offset:23072
	s_waitcnt lgkmcnt(4)
	v_mfma_f32_32x32x16_bf16 v[34:49], v[2:5], v[6:9], 0
	s_waitcnt lgkmcnt(3)
	v_mfma_f32_32x32x16_bf16 v[50:65], v[2:5], v[18:21], 0
	s_waitcnt lgkmcnt(1)
	v_mfma_f32_32x32x16_bf16 v[34:49], v[122:125], v[126:129], v[34:49]
	s_waitcnt lgkmcnt(0)
	v_mfma_f32_32x32x16_bf16 v[50:65], v[122:125], v[138:141], v[50:65]
	ds_read_b128 v[122:125], v148 offset:4640
	v_mfma_f32_32x32x16_bf16 v[2:17], v[22:25], v[6:9], 0
	v_mfma_f32_32x32x16_bf16 v[18:33], v[22:25], v[18:21], 0
	s_waitcnt lgkmcnt(0)
	v_mfma_f32_32x32x16_bf16 v[2:17], v[122:125], v[126:129], v[2:17]
	v_mfma_f32_32x32x16_bf16 v[18:33], v[122:125], v[138:141], v[18:33]
	ds_read_b128 v[122:125], v148 offset:64
	ds_read_b128 v[126:129], v149 offset:18496
	ds_read_b128 v[138:141], v149 offset:23104
	s_waitcnt lgkmcnt(1)
	v_mfma_f32_32x32x16_bf16 v[34:49], v[122:125], v[126:129], v[34:49]
	s_waitcnt lgkmcnt(0)
	v_mfma_f32_32x32x16_bf16 v[50:65], v[122:125], v[138:141], v[50:65]
	ds_read_b128 v[122:125], v148 offset:4672
	s_waitcnt lgkmcnt(0)
	v_mfma_f32_32x32x16_bf16 v[2:17], v[122:125], v[126:129], v[2:17]
	v_mfma_f32_32x32x16_bf16 v[18:33], v[122:125], v[138:141], v[18:33]
	ds_read_b128 v[122:125], v148 offset:96
	ds_read_b128 v[126:129], v149 offset:18528
	ds_read_b128 v[138:141], v149 offset:23136
	s_waitcnt lgkmcnt(1)
	v_mfma_f32_32x32x16_bf16 v[34:49], v[122:125], v[126:129], v[34:49]
	s_waitcnt lgkmcnt(0)
	v_mfma_f32_32x32x16_bf16 v[50:65], v[122:125], v[138:141], v[50:65]
	ds_read_b128 v[122:125], v148 offset:4704
	s_waitcnt lgkmcnt(0)
	v_mfma_f32_32x32x16_bf16 v[2:17], v[122:125], v[126:129], v[2:17]
	v_mfma_f32_32x32x16_bf16 v[18:33], v[122:125], v[138:141], v[18:33]
	s_nop 0
	s_waitcnt vmcnt(15)
	v_lshlrev_b32_e32 v122, 16, v90
	v_and_b32_e32 v123, 0xffff0000, v90
	v_fmac_f32_e32 v153, v122, v122
	v_lshlrev_b32_e32 v124, 16, v91
	v_fmac_f32_e32 v153, v123, v123
	v_and_b32_e32 v125, 0xffff0000, v91
	v_fmac_f32_e32 v153, v124, v124
	v_lshlrev_b32_e32 v126, 16, v92
	v_fmac_f32_e32 v153, v125, v125
	v_and_b32_e32 v127, 0xffff0000, v92
	v_fmac_f32_e32 v153, v126, v126
	v_lshlrev_b32_e32 v128, 16, v93
	v_fmac_f32_e32 v153, v127, v127
	v_and_b32_e32 v129, 0xffff0000, v93
	v_fmac_f32_e32 v153, v128, v128
	v_fmac_f32_e32 v153, v129, v129
	ds_write_b128 v157, v[90:93] offset:36864
	s_waitcnt vmcnt(14)
	ds_write_b128 v157, v[94:97] offset:55296
	s_waitcnt vmcnt(13)
	v_lshlrev_b32_e32 v90, 16, v82
	v_and_b32_e32 v91, 0xffff0000, v82
	v_fmac_f32_e32 v154, v90, v90
	v_lshlrev_b32_e32 v92, 16, v83
	v_fmac_f32_e32 v154, v91, v91
	v_and_b32_e32 v93, 0xffff0000, v83
	v_fmac_f32_e32 v154, v92, v92
	v_lshlrev_b32_e32 v94, 16, v84
	v_fmac_f32_e32 v154, v93, v93
	v_and_b32_e32 v95, 0xffff0000, v84
	v_fmac_f32_e32 v154, v94, v94
	v_lshlrev_b32_e32 v96, 16, v85
	v_fmac_f32_e32 v154, v95, v95
	v_and_b32_e32 v97, 0xffff0000, v85
	v_fmac_f32_e32 v154, v96, v96
	v_fmac_f32_e32 v154, v97, v97
	ds_write_b128 v157, v[82:85] offset:41472
	s_waitcnt vmcnt(12)
	ds_write_b128 v157, v[86:89] offset:59904
	s_waitcnt vmcnt(11)
	v_lshlrev_b32_e32 v82, 16, v74
	v_and_b32_e32 v83, 0xffff0000, v74
	v_fmac_f32_e32 v155, v82, v82
	v_lshlrev_b32_e32 v84, 16, v75
	v_fmac_f32_e32 v155, v83, v83
	v_and_b32_e32 v85, 0xffff0000, v75
	v_fmac_f32_e32 v155, v84, v84
	v_lshlrev_b32_e32 v86, 16, v76
	v_fmac_f32_e32 v155, v85, v85
	v_and_b32_e32 v87, 0xffff0000, v76
	v_fmac_f32_e32 v155, v86, v86
	v_lshlrev_b32_e32 v88, 16, v77
	v_fmac_f32_e32 v155, v87, v87
	v_and_b32_e32 v89, 0xffff0000, v77
	v_fmac_f32_e32 v155, v88, v88
	v_fmac_f32_e32 v155, v89, v89
	ds_write_b128 v157, v[74:77] offset:46080
	s_waitcnt vmcnt(10)
	ds_write_b128 v157, v[78:81] offset:64512
	s_waitcnt vmcnt(9)
	v_lshlrev_b32_e32 v74, 16, v66
	v_and_b32_e32 v75, 0xffff0000, v66
	v_fmac_f32_e32 v156, v74, v74
	v_lshlrev_b32_e32 v76, 16, v67
	v_fmac_f32_e32 v156, v75, v75
	v_and_b32_e32 v77, 0xffff0000, v67
	v_fmac_f32_e32 v156, v76, v76
	v_lshlrev_b32_e32 v78, 16, v68
	v_fmac_f32_e32 v156, v77, v77
	v_and_b32_e32 v79, 0xffff0000, v68
	v_fmac_f32_e32 v156, v78, v78
	v_lshlrev_b32_e32 v80, 16, v69
	v_fmac_f32_e32 v156, v79, v79
	v_and_b32_e32 v81, 0xffff0000, v69
	v_fmac_f32_e32 v156, v80, v80
	v_fmac_f32_e32 v156, v81, v81
	ds_write_b128 v157, v[66:69] offset:50688
	s_waitcnt vmcnt(8)
	ds_write_b128 v158, v[70:73] offset:64512
	v_add_u32_e32 v66, 0x180, v159
	global_load_dwordx4 v[138:141], v66, s[36:37]
	global_load_dwordx4 v[142:145], v66, s[40:41]
	v_add_u32_e32 v66, 0x6180, v159
	global_load_dwordx4 v[122:125], v66, s[36:37]
	global_load_dwordx4 v[126:129], v66, s[40:41]
	v_add_u32_e32 v66, 0xc180, v159
	v_add_u32_e32 v70, 0x12180, v159
	global_load_dwordx4 v[82:85], v66, s[36:37]
	global_load_dwordx4 v[86:89], v66, s[40:41]
	s_nop 0
	global_load_dwordx4 v[66:69], v70, s[36:37]
	s_nop 0
	global_load_dwordx4 v[70:73], v70, s[40:41]
	s_waitcnt lgkmcnt(0)
	s_barrier
; #define BLOAD(A_, B_, kt) do { _Pragma("unroll") for (int i = 0; i < 4; ++i) { \
;     A_[i] = *(const u32x4*)((const char*)Ap + (aoff + (unsigned)(32 * i * lda + (kt) * 64) * 2u)); B_[i] = *(const u32x4*)((const char*)Wt + (woff + (unsigned)(32 * i * K + (kt) * 64) * 2u)); } } while (0)
; #define BLOAD(A_, B_, kt) do { _Pragma("unroll") for (int i = 0; i < 4; ++i) { \
;     A_[i] = *(const u32x4*)((const char*)Ap + (aoff + (unsigned)(32 * i * lda + (kt) * 64) * 2u)); B_[i] = *(const u32x4*)((const char*)Wt + (woff + (unsigned)(32 * i * K + (kt) * 64) * 2u)); } } while (0)
; #define BSTORE(A_, B_, buf) do { _Pragma("unroll") for (int i = 0; i < 4; ++i) { \
;     *(u32x4*)&As[(buf) * GBUF + (srow + 32 * i) * LDT + sc8] = A_[i]; \
;     *(u32x4*)&Bs[(buf) * GBUF + (srow + 32 * i) * LDT + sc8] = B_[i]; } } while (0)
; template <bool ROWNORM, int NK>
; DI void gemm_main_bf(const u16* __restrict__ Ap, int lda, const u16* __restrict__ Wt, f32x16 (&acc)[2][2], char* smem, float* rinv_s) {
;     ...
;     BCOMP(1);
;     if (kt + 2 < nk) { BSTORE(a0, b0, 0); if (kt + 4 < nk) BLOAD(a0, b0, kt + 4); }
;     __syncthreads();
	s_nop 0
	ds_read_b128 v[74:77], v148 offset:36864
	ds_read_b128 v[78:81], v149 offset:55296
	ds_read_b128 v[90:93], v149 offset:59904
	s_waitcnt lgkmcnt(1)
	v_mfma_f32_32x32x16_bf16 v[34:49], v[74:77], v[78:81], v[34:49]
	s_waitcnt lgkmcnt(0)
	v_mfma_f32_32x32x16_bf16 v[50:65], v[74:77], v[90:93], v[50:65]
	ds_read_b128 v[74:77], v148 offset:41472
	s_waitcnt lgkmcnt(0)
	v_mfma_f32_32x32x16_bf16 v[2:17], v[74:77], v[78:81], v[2:17]
	v_mfma_f32_32x32x16_bf16 v[18:33], v[74:77], v[90:93], v[18:33]
	ds_read_b128 v[74:77], v148 offset:36896
	ds_read_b128 v[78:81], v149 offset:55328
	ds_read_b128 v[90:93], v149 offset:59936
	s_waitcnt lgkmcnt(1)
	v_mfma_f32_32x32x16_bf16 v[34:49], v[74:77], v[78:81], v[34:49]
	s_waitcnt lgkmcnt(0)
	v_mfma_f32_32x32x16_bf16 v[50:65], v[74:77], v[90:93], v[50:65]
	ds_read_b128 v[74:77], v148 offset:41504
	s_waitcnt lgkmcnt(0)
	v_mfma_f32_32x32x16_bf16 v[2:17], v[74:77], v[78:81], v[2:17]
	v_mfma_f32_32x32x16_bf16 v[18:33], v[74:77], v[90:93], v[18:33]
	ds_read_b128 v[74:77], v148 offset:36928
	ds_read_b128 v[78:81], v149 offset:55360
	ds_read_b128 v[90:93], v149 offset:59968
	s_waitcnt lgkmcnt(1)
	v_mfma_f32_32x32x16_bf16 v[34:49], v[74:77], v[78:81], v[34:49]
	s_waitcnt lgkmcnt(0)
	v_mfma_f32_32x32x16_bf16 v[50:65], v[74:77], v[90:93], v[50:65]
	ds_read_b128 v[74:77], v148 offset:41536
	s_waitcnt lgkmcnt(0)
	v_mfma_f32_32x32x16_bf16 v[2:17], v[74:77], v[78:81], v[2:17]
	v_mfma_f32_32x32x16_bf16 v[18:33], v[74:77], v[90:93], v[18:33]
	ds_read_b128 v[74:77], v148 offset:36960
	ds_read_b128 v[78:81], v149 offset:55392
	ds_read_b128 v[90:93], v149 offset:60000
	s_waitcnt lgkmcnt(1)
	v_mfma_f32_32x32x16_bf16 v[34:49], v[74:77], v[78:81], v[34:49]
	s_waitcnt lgkmcnt(0)
	v_mfma_f32_32x32x16_bf16 v[50:65], v[74:77], v[90:93], v[50:65]
	ds_read_b128 v[74:77], v148 offset:41568
	s_waitcnt lgkmcnt(0)
	v_mfma_f32_32x32x16_bf16 v[2:17], v[74:77], v[78:81], v[2:17]
	v_mfma_f32_32x32x16_bf16 v[18:33], v[74:77], v[90:93], v[18:33]
	s_nop 0
	s_waitcnt vmcnt(15)
	v_lshlrev_b32_e32 v74, 16, v130
	v_and_b32_e32 v75, 0xffff0000, v130
	v_fmac_f32_e32 v153, v74, v74
	s_waitcnt vmcnt(13)
	v_lshlrev_b32_e32 v74, 16, v114
	v_lshlrev_b32_e32 v76, 16, v131
	v_fmac_f32_e32 v153, v75, v75
	v_and_b32_e32 v75, 0xffff0000, v114
	v_fmac_f32_e32 v154, v74, v74
	s_waitcnt vmcnt(11)
	v_lshlrev_b32_e32 v74, 16, v106
	v_and_b32_e32 v77, 0xffff0000, v131
	v_fmac_f32_e32 v153, v76, v76
	v_lshlrev_b32_e32 v76, 16, v115
	v_fmac_f32_e32 v154, v75, v75
	v_and_b32_e32 v75, 0xffff0000, v106
	v_fmac_f32_e32 v155, v74, v74
	s_waitcnt vmcnt(9)
	v_lshlrev_b32_e32 v74, 16, v98
	v_lshlrev_b32_e32 v78, 16, v132
	v_fmac_f32_e32 v153, v77, v77
	v_and_b32_e32 v77, 0xffff0000, v115
	v_fmac_f32_e32 v154, v76, v76
	v_lshlrev_b32_e32 v76, 16, v107
	v_fmac_f32_e32 v155, v75, v75
	v_and_b32_e32 v75, 0xffff0000, v98
	v_fmac_f32_e32 v156, v74, v74
	v_and_b32_e32 v79, 0xffff0000, v132
	v_fmac_f32_e32 v153, v78, v78
	v_lshlrev_b32_e32 v78, 16, v116
	v_fmac_f32_e32 v154, v77, v77
	v_and_b32_e32 v77, 0xffff0000, v107
	v_fmac_f32_e32 v155, v76, v76
	v_lshlrev_b32_e32 v76, 16, v99
	v_fmac_f32_e32 v156, v75, v75
	v_lshlrev_b32_e32 v80, 16, v133
	v_fmac_f32_e32 v153, v79, v79
	v_and_b32_e32 v79, 0xffff0000, v116
	v_fmac_f32_e32 v154, v78, v78
	v_lshlrev_b32_e32 v78, 16, v108
	v_fmac_f32_e32 v155, v77, v77
	v_and_b32_e32 v77, 0xffff0000, v99
	v_fmac_f32_e32 v156, v76, v76
	v_and_b32_e32 v81, 0xffff0000, v133
	v_fmac_f32_e32 v153, v80, v80
	v_lshlrev_b32_e32 v80, 16, v117
	v_fmac_f32_e32 v154, v79, v79
	v_and_b32_e32 v79, 0xffff0000, v108
	v_fmac_f32_e32 v155, v78, v78
	v_lshlrev_b32_e32 v78, 16, v100
	v_fmac_f32_e32 v156, v77, v77
	v_fmac_f32_e32 v153, v81, v81
	v_and_b32_e32 v81, 0xffff0000, v117
	v_fmac_f32_e32 v154, v80, v80
	v_lshlrev_b32_e32 v80, 16, v109
	v_fmac_f32_e32 v155, v79, v79
	v_and_b32_e32 v79, 0xffff0000, v100
	v_fmac_f32_e32 v156, v78, v78
	v_fmac_f32_e32 v154, v81, v81
	v_and_b32_e32 v81, 0xffff0000, v109
	v_fmac_f32_e32 v155, v80, v80
	v_lshlrev_b32_e32 v80, 16, v101
	v_fmac_f32_e32 v156, v79, v79
	v_fmac_f32_e32 v155, v81, v81
	v_and_b32_e32 v81, 0xffff0000, v101
	v_fmac_f32_e32 v156, v80, v80
	v_fmac_f32_e32 v156, v81, v81
	ds_write_b128 v157, v[130:133]
	ds_write_b128 v157, v[134:137] offset:18432
	ds_write_b128 v157, v[114:117] offset:4608
	ds_write_b128 v157, v[118:121] offset:23040
	ds_write_b128 v157, v[106:109] offset:9216
	ds_write_b128 v157, v[110:113] offset:27648
	ds_write_b128 v157, v[98:101] offset:13824
	s_waitcnt vmcnt(8)
	ds_write_b128 v157, v[102:105] offset:32256
	v_add_u32_e32 v74, 0x200, v159
	global_load_dwordx4 v[114:117], v74, s[36:37]
	global_load_dwordx4 v[118:121], v74, s[40:41]
	v_add_u32_e32 v74, 0x6200, v159
	global_load_dwordx4 v[98:101], v74, s[36:37]
	global_load_dwordx4 v[102:105], v74, s[40:41]
	v_add_u32_e32 v74, 0xc200, v159
	v_add_u32_e32 v78, 0x12200, v159
	global_load_dwordx4 v[90:93], v74, s[36:37]
	global_load_dwordx4 v[94:97], v74, s[40:41]
	s_nop 0
	global_load_dwordx4 v[74:77], v78, s[36:37]
	s_nop 0
	global_load_dwordx4 v[78:81], v78, s[40:41]
	s_waitcnt lgkmcnt(0)
	s_barrier
; #define BLOAD(A_, B_, kt) do { _Pragma("unroll") for (int i = 0; i < 4; ++i) { \
;     A_[i] = *(const u32x4*)((const char*)Ap + (aoff + (unsigned)(32 * i * lda + (kt) * 64) * 2u)); B_[i] = *(const u32x4*)((const char*)Wt + (woff + (unsigned)(32 * i * K + (kt) * 64) * 2u)); } } while (0)
; #define BLOAD(A_, B_, kt) do { _Pragma("unroll") for (int i = 0; i < 4; ++i) { \
;     A_[i] = *(const u32x4*)((const char*)Ap + (aoff + (unsigned)(32 * i * lda + (kt) * 64) * 2u)); B_[i] = *(const u32x4*)((const char*)Wt + (woff + (unsigned)(32 * i * K + (kt) * 64) * 2u)); } } while (0)
; #define BSTORE(A_, B_, buf) do { _Pragma("unroll") for (int i = 0; i < 4; ++i) { \
;     *(u32x4*)&As[(buf) * GBUF + (srow + 32 * i) * LDT + sc8] = A_[i]; \
;     *(u32x4*)&Bs[(buf) * GBUF + (srow + 32 * i) * LDT + sc8] = B_[i]; } } while (0)
; template <bool ROWNORM, int NK>
; DI void gemm_main_bf(const u16* __restrict__ Ap, int lda, const u16* __restrict__ Wt, f32x16 (&acc)[2][2], char* smem, float* rinv_s) {
;     ...
;     BCOMP(0);
;     BSTORE(a1, b1, 1);
;     if (kt + 3 < nk) BLOAD(a1, b1, kt + 3);
;     __syncthreads();
	s_nop 0
	ds_read_b128 v[106:109], v148
	ds_read_b128 v[110:113], v149 offset:18432
	ds_read_b128 v[130:133], v149 offset:23040
	s_waitcnt lgkmcnt(1)
	v_mfma_f32_32x32x16_bf16 v[34:49], v[106:109], v[110:113], v[34:49]
	s_waitcnt lgkmcnt(0)
	v_mfma_f32_32x32x16_bf16 v[50:65], v[106:109], v[130:133], v[50:65]
	ds_read_b128 v[106:109], v148 offset:4608
	s_waitcnt lgkmcnt(0)
	v_mfma_f32_32x32x16_bf16 v[2:17], v[106:109], v[110:113], v[2:17]
	v_mfma_f32_32x32x16_bf16 v[18:33], v[106:109], v[130:133], v[18:33]
	ds_read_b128 v[106:109], v148 offset:32
	ds_read_b128 v[110:113], v149 offset:18464
	ds_read_b128 v[130:133], v149 offset:23072
	s_waitcnt lgkmcnt(1)
	v_mfma_f32_32x32x16_bf16 v[34:49], v[106:109], v[110:113], v[34:49]
	s_waitcnt lgkmcnt(0)
	v_mfma_f32_32x32x16_bf16 v[50:65], v[106:109], v[130:133], v[50:65]
	ds_read_b128 v[106:109], v148 offset:4640
	s_waitcnt lgkmcnt(0)
	v_mfma_f32_32x32x16_bf16 v[2:17], v[106:109], v[110:113], v[2:17]
	v_mfma_f32_32x32x16_bf16 v[18:33], v[106:109], v[130:133], v[18:33]
	ds_read_b128 v[106:109], v148 offset:64
	ds_read_b128 v[110:113], v149 offset:18496
	ds_read_b128 v[130:133], v149 offset:23104
	s_waitcnt lgkmcnt(1)
	v_mfma_f32_32x32x16_bf16 v[34:49], v[106:109], v[110:113], v[34:49]
	s_waitcnt lgkmcnt(0)
	v_mfma_f32_32x32x16_bf16 v[50:65], v[106:109], v[130:133], v[50:65]
	ds_read_b128 v[106:109], v148 offset:4672
	s_waitcnt lgkmcnt(0)
	v_mfma_f32_32x32x16_bf16 v[2:17], v[106:109], v[110:113], v[2:17]
	v_mfma_f32_32x32x16_bf16 v[18:33], v[106:109], v[130:133], v[18:33]
	ds_read_b128 v[106:109], v148 offset:96
	ds_read_b128 v[110:113], v149 offset:18528
	ds_read_b128 v[130:133], v149 offset:23136
	s_waitcnt lgkmcnt(1)
	v_mfma_f32_32x32x16_bf16 v[34:49], v[106:109], v[110:113], v[34:49]
	s_waitcnt lgkmcnt(0)
	v_mfma_f32_32x32x16_bf16 v[50:65], v[106:109], v[130:133], v[50:65]
	ds_read_b128 v[106:109], v148 offset:4704
	s_waitcnt lgkmcnt(0)
	v_mfma_f32_32x32x16_bf16 v[2:17], v[106:109], v[110:113], v[2:17]
	v_mfma_f32_32x32x16_bf16 v[18:33], v[106:109], v[130:133], v[18:33]
	s_nop 0
	s_waitcnt vmcnt(15)
	v_lshlrev_b32_e32 v106, 16, v138
	v_and_b32_e32 v107, 0xffff0000, v138
	v_fmac_f32_e32 v153, v106, v106
	s_waitcnt vmcnt(13)
	v_lshlrev_b32_e32 v106, 16, v122
	v_lshlrev_b32_e32 v108, 16, v139
	v_fmac_f32_e32 v153, v107, v107
	v_and_b32_e32 v107, 0xffff0000, v122
	v_fmac_f32_e32 v154, v106, v106
	s_waitcnt vmcnt(11)
	v_lshlrev_b32_e32 v106, 16, v82
	v_and_b32_e32 v109, 0xffff0000, v139
	v_fmac_f32_e32 v153, v108, v108
	v_lshlrev_b32_e32 v108, 16, v123
	v_fmac_f32_e32 v154, v107, v107
	v_and_b32_e32 v107, 0xffff0000, v82
	v_fmac_f32_e32 v155, v106, v106
	v_lshlrev_b32_e32 v110, 16, v140
	v_fmac_f32_e32 v153, v109, v109
	v_and_b32_e32 v109, 0xffff0000, v123
	v_fmac_f32_e32 v154, v108, v108
	v_lshlrev_b32_e32 v108, 16, v83
	v_fmac_f32_e32 v155, v107, v107
	v_and_b32_e32 v111, 0xffff0000, v140
	v_fmac_f32_e32 v153, v110, v110
	v_lshlrev_b32_e32 v110, 16, v124
	v_fmac_f32_e32 v154, v109, v109
	v_and_b32_e32 v109, 0xffff0000, v83
	v_fmac_f32_e32 v155, v108, v108
	v_lshlrev_b32_e32 v112, 16, v141
	v_fmac_f32_e32 v153, v111, v111
	v_and_b32_e32 v111, 0xffff0000, v124
	v_fmac_f32_e32 v154, v110, v110
	v_lshlrev_b32_e32 v110, 16, v84
	v_fmac_f32_e32 v155, v109, v109
	v_and_b32_e32 v113, 0xffff0000, v141
	v_fmac_f32_e32 v153, v112, v112
	v_lshlrev_b32_e32 v112, 16, v125
	v_fmac_f32_e32 v154, v111, v111
	v_and_b32_e32 v111, 0xffff0000, v84
	v_fmac_f32_e32 v155, v110, v110
	v_fmac_f32_e32 v153, v113, v113
	v_and_b32_e32 v113, 0xffff0000, v125
	v_fmac_f32_e32 v154, v112, v112
	v_lshlrev_b32_e32 v112, 16, v85
	v_fmac_f32_e32 v155, v111, v111
	v_fmac_f32_e32 v154, v113, v113
	v_and_b32_e32 v113, 0xffff0000, v85
	v_fmac_f32_e32 v155, v112, v112
	v_fmac_f32_e32 v155, v113, v113
	ds_write_b128 v157, v[138:141] offset:36864
	ds_write_b128 v157, v[142:145] offset:55296
	ds_write_b128 v157, v[122:125] offset:41472
	ds_write_b128 v157, v[126:129] offset:59904
	ds_write_b128 v157, v[82:85] offset:46080
	s_waitcnt vmcnt(10)
	ds_write_b128 v157, v[86:89] offset:64512
	s_waitcnt vmcnt(9)
	v_lshlrev_b32_e32 v82, 16, v66
	v_and_b32_e32 v83, 0xffff0000, v66
	v_fmac_f32_e32 v156, v82, v82
	v_lshlrev_b32_e32 v84, 16, v67
	v_fmac_f32_e32 v156, v83, v83
	v_and_b32_e32 v85, 0xffff0000, v67
	v_fmac_f32_e32 v156, v84, v84
	v_lshlrev_b32_e32 v86, 16, v68
	v_fmac_f32_e32 v156, v85, v85
	v_and_b32_e32 v87, 0xffff0000, v68
	v_fmac_f32_e32 v156, v86, v86
	v_lshlrev_b32_e32 v88, 16, v69
	v_fmac_f32_e32 v156, v87, v87
	v_and_b32_e32 v89, 0xffff0000, v69
	v_fmac_f32_e32 v156, v88, v88
	v_fmac_f32_e32 v156, v89, v89
	ds_write_b128 v157, v[66:69] offset:50688
	s_waitcnt vmcnt(8)
	ds_write_b128 v158, v[70:73] offset:64512
	v_add_u32_e32 v66, 0x280, v159
	global_load_dwordx4 v[122:125], v66, s[36:37]
	global_load_dwordx4 v[126:129], v66, s[40:41]
	v_add_u32_e32 v66, 0x6280, v159
	global_load_dwordx4 v[106:109], v66, s[36:37]
	global_load_dwordx4 v[110:113], v66, s[40:41]
	v_add_u32_e32 v66, 0xc280, v159
	v_add_u32_e32 v70, 0x12280, v159
	global_load_dwordx4 v[82:85], v66, s[36:37]
	global_load_dwordx4 v[86:89], v66, s[40:41]
	s_nop 0
	global_load_dwordx4 v[66:69], v70, s[36:37]
	s_nop 0
	global_load_dwordx4 v[70:73], v70, s[40:41]
	s_waitcnt lgkmcnt(0)
	s_barrier
; #define BLOAD(A_, B_, kt) do { _Pragma("unroll") for (int i = 0; i < 4; ++i) { \
;     A_[i] = *(const u32x4*)((const char*)Ap + (aoff + (unsigned)(32 * i * lda + (kt) * 64) * 2u)); B_[i] = *(const u32x4*)((const char*)Wt + (woff + (unsigned)(32 * i * K + (kt) * 64) * 2u)); } } while (0)
; #define BLOAD(A_, B_, kt) do { _Pragma("unroll") for (int i = 0; i < 4; ++i) { \
;     A_[i] = *(const u32x4*)((const char*)Ap + (aoff + (unsigned)(32 * i * lda + (kt) * 64) * 2u)); B_[i] = *(const u32x4*)((const char*)Wt + (woff + (unsigned)(32 * i * K + (kt) * 64) * 2u)); } } while (0)
; #define BSTORE(A_, B_, buf) do { _Pragma("unroll") for (int i = 0; i < 4; ++i) { \
;     *(u32x4*)&As[(buf) * GBUF + (srow + 32 * i) * LDT + sc8] = A_[i]; \
;     *(u32x4*)&Bs[(buf) * GBUF + (srow + 32 * i) * LDT + sc8] = B_[i]; } } while (0)
; template <bool ROWNORM, int NK>
; DI void gemm_main_bf(const u16* __restrict__ Ap, int lda, const u16* __restrict__ Wt, f32x16 (&acc)[2][2], char* smem, float* rinv_s) {
;     ...
;     BCOMP(1);
;     if (kt + 2 < nk) { BSTORE(a0, b0, 0); if (kt + 4 < nk) BLOAD(a0, b0, kt + 4); }
;     __syncthreads();
	s_nop 0
	ds_read_b128 v[130:133], v148 offset:36864
	ds_read_b128 v[134:137], v149 offset:55296
	ds_read_b128 v[138:141], v149 offset:59904
	s_waitcnt lgkmcnt(1)
	v_mfma_f32_32x32x16_bf16 v[34:49], v[130:133], v[134:137], v[34:49]
	s_waitcnt lgkmcnt(0)
	v_mfma_f32_32x32x16_bf16 v[50:65], v[130:133], v[138:141], v[50:65]
	ds_read_b128 v[130:133], v148 offset:41472
	s_waitcnt lgkmcnt(0)
	v_mfma_f32_32x32x16_bf16 v[2:17], v[130:133], v[134:137], v[2:17]
	v_mfma_f32_32x32x16_bf16 v[18:33], v[130:133], v[138:141], v[18:33]
	ds_read_b128 v[130:133], v148 offset:36896
	ds_read_b128 v[134:137], v149 offset:55328
	ds_read_b128 v[138:141], v149 offset:59936
	s_waitcnt lgkmcnt(1)
	v_mfma_f32_32x32x16_bf16 v[34:49], v[130:133], v[134:137], v[34:49]
	s_waitcnt lgkmcnt(0)
	v_mfma_f32_32x32x16_bf16 v[50:65], v[130:133], v[138:141], v[50:65]
	ds_read_b128 v[130:133], v148 offset:41504
	s_waitcnt lgkmcnt(0)
	v_mfma_f32_32x32x16_bf16 v[2:17], v[130:133], v[134:137], v[2:17]
	v_mfma_f32_32x32x16_bf16 v[18:33], v[130:133], v[138:141], v[18:33]
	ds_read_b128 v[130:133], v148 offset:36928
	ds_read_b128 v[134:137], v149 offset:55360
	ds_read_b128 v[138:141], v149 offset:59968
	s_waitcnt lgkmcnt(1)
	v_mfma_f32_32x32x16_bf16 v[34:49], v[130:133], v[134:137], v[34:49]
	s_waitcnt lgkmcnt(0)
	v_mfma_f32_32x32x16_bf16 v[50:65], v[130:133], v[138:141], v[50:65]
	ds_read_b128 v[130:133], v148 offset:41536
	s_waitcnt lgkmcnt(0)
	v_mfma_f32_32x32x16_bf16 v[2:17], v[130:133], v[134:137], v[2:17]
	v_mfma_f32_32x32x16_bf16 v[18:33], v[130:133], v[138:141], v[18:33]
	ds_read_b128 v[130:133], v148 offset:36960
	ds_read_b128 v[134:137], v149 offset:55392
	ds_read_b128 v[138:141], v149 offset:60000
	s_waitcnt lgkmcnt(1)
	v_mfma_f32_32x32x16_bf16 v[34:49], v[130:133], v[134:137], v[34:49]
	s_waitcnt lgkmcnt(0)
	v_mfma_f32_32x32x16_bf16 v[50:65], v[130:133], v[138:141], v[50:65]
	ds_read_b128 v[130:133], v148 offset:41568
	s_waitcnt lgkmcnt(0)
	v_mfma_f32_32x32x16_bf16 v[2:17], v[130:133], v[134:137], v[2:17]
	v_mfma_f32_32x32x16_bf16 v[18:33], v[130:133], v[138:141], v[18:33]
	s_nop 0
	s_waitcnt vmcnt(15)
	v_lshlrev_b32_e32 v130, 16, v114
	v_and_b32_e32 v131, 0xffff0000, v114
	v_fmac_f32_e32 v153, v130, v130
	v_lshlrev_b32_e32 v132, 16, v115
	v_fmac_f32_e32 v153, v131, v131
	v_and_b32_e32 v133, 0xffff0000, v115
	v_fmac_f32_e32 v153, v132, v132
	v_lshlrev_b32_e32 v134, 16, v116
	v_fmac_f32_e32 v153, v133, v133
	v_and_b32_e32 v135, 0xffff0000, v116
	v_fmac_f32_e32 v153, v134, v134
	v_lshlrev_b32_e32 v136, 16, v117
	v_fmac_f32_e32 v153, v135, v135
	v_and_b32_e32 v137, 0xffff0000, v117
	v_fmac_f32_e32 v153, v136, v136
	v_fmac_f32_e32 v153, v137, v137
	ds_write_b128 v157, v[114:117]
	s_waitcnt vmcnt(14)
	ds_write_b128 v157, v[118:121] offset:18432
	s_waitcnt vmcnt(13)
	v_lshlrev_b32_e32 v114, 16, v98
	v_and_b32_e32 v115, 0xffff0000, v98
	v_fmac_f32_e32 v154, v114, v114
	v_lshlrev_b32_e32 v116, 16, v99
	v_fmac_f32_e32 v154, v115, v115
	v_and_b32_e32 v117, 0xffff0000, v99
	v_fmac_f32_e32 v154, v116, v116
	v_lshlrev_b32_e32 v118, 16, v100
	v_fmac_f32_e32 v154, v117, v117
	v_and_b32_e32 v119, 0xffff0000, v100
	v_fmac_f32_e32 v154, v118, v118
	v_lshlrev_b32_e32 v120, 16, v101
	v_fmac_f32_e32 v154, v119, v119
	v_and_b32_e32 v121, 0xffff0000, v101
	v_fmac_f32_e32 v154, v120, v120
	v_fmac_f32_e32 v154, v121, v121
	ds_write_b128 v157, v[98:101] offset:4608
	s_waitcnt vmcnt(12)
	ds_write_b128 v157, v[102:105] offset:23040
	s_waitcnt vmcnt(11)
	v_lshlrev_b32_e32 v98, 16, v90
	v_and_b32_e32 v99, 0xffff0000, v90
	v_fmac_f32_e32 v155, v98, v98
	v_lshlrev_b32_e32 v100, 16, v91
	v_fmac_f32_e32 v155, v99, v99
	v_and_b32_e32 v101, 0xffff0000, v91
	v_fmac_f32_e32 v155, v100, v100
	v_lshlrev_b32_e32 v102, 16, v92
	v_fmac_f32_e32 v155, v101, v101
	v_and_b32_e32 v103, 0xffff0000, v92
	v_fmac_f32_e32 v155, v102, v102
	v_lshlrev_b32_e32 v104, 16, v93
	v_fmac_f32_e32 v155, v103, v103
	v_and_b32_e32 v105, 0xffff0000, v93
	v_fmac_f32_e32 v155, v104, v104
	v_fmac_f32_e32 v155, v105, v105
	ds_write_b128 v157, v[90:93] offset:9216
	s_waitcnt vmcnt(10)
	ds_write_b128 v157, v[94:97] offset:27648
	s_waitcnt vmcnt(9)
	v_lshlrev_b32_e32 v90, 16, v74
	v_and_b32_e32 v91, 0xffff0000, v74
	v_fmac_f32_e32 v156, v90, v90
	v_lshlrev_b32_e32 v92, 16, v75
	v_fmac_f32_e32 v156, v91, v91
	v_and_b32_e32 v93, 0xffff0000, v75
	v_fmac_f32_e32 v156, v92, v92
	v_lshlrev_b32_e32 v94, 16, v76
	v_fmac_f32_e32 v156, v93, v93
	v_and_b32_e32 v95, 0xffff0000, v76
	v_fmac_f32_e32 v156, v94, v94
	v_lshlrev_b32_e32 v96, 16, v77
	v_fmac_f32_e32 v156, v95, v95
	v_and_b32_e32 v97, 0xffff0000, v77
	v_fmac_f32_e32 v156, v96, v96
	v_fmac_f32_e32 v156, v97, v97
	ds_write_b128 v157, v[74:77] offset:13824
	s_waitcnt vmcnt(8)
	ds_write_b128 v157, v[78:81] offset:32256
	s_waitcnt lgkmcnt(0)
	s_barrier
; #define BLOAD(A_, B_, kt) do { _Pragma("unroll") for (int i = 0; i < 4; ++i) { \
;     A_[i] = *(const u32x4*)((const char*)Ap + (aoff + (unsigned)(32 * i * lda + (kt) * 64) * 2u)); B_[i] = *(const u32x4*)((const char*)Wt + (woff + (unsigned)(32 * i * K + (kt) * 64) * 2u)); } } while (0)
; #define BLOAD(A_, B_, kt) do { _Pragma("unroll") for (int i = 0; i < 4; ++i) { \
;     A_[i] = *(const u32x4*)((const char*)Ap + (aoff + (unsigned)(32 * i * lda + (kt) * 64) * 2u)); B_[i] = *(const u32x4*)((const char*)Wt + (woff + (unsigned)(32 * i * K + (kt) * 64) * 2u)); } } while (0)
; #define BSTORE(A_, B_, buf) do { _Pragma("unroll") for (int i = 0; i < 4; ++i) { \
;     *(u32x4*)&As[(buf) * GBUF + (srow + 32 * i) * LDT + sc8] = A_[i]; \
;     *(u32x4*)&Bs[(buf) * GBUF + (srow + 32 * i) * LDT + sc8] = B_[i]; } } while (0)
; template <bool ROWNORM, int NK>
; DI void gemm_main_bf(const u16* __restrict__ Ap, int lda, const u16* __restrict__ Wt, f32x16 (&acc)[2][2], char* smem, float* rinv_s) {
;     ...
;     BCOMP(0);
;     BSTORE(a1, b1, 1);
;     if (kt + 3 < nk) BLOAD(a1, b1, kt + 3);
;     __syncthreads();
	s_nop 0
	ds_read_b128 v[74:77], v148
	ds_read_b128 v[78:81], v149 offset:18432
	ds_read_b128 v[90:93], v149 offset:23040
	s_waitcnt lgkmcnt(1)
	v_mfma_f32_32x32x16_bf16 v[34:49], v[74:77], v[78:81], v[34:49]
	s_waitcnt lgkmcnt(0)
	v_mfma_f32_32x32x16_bf16 v[50:65], v[74:77], v[90:93], v[50:65]
	ds_read_b128 v[74:77], v148 offset:4608
	s_waitcnt lgkmcnt(0)
	v_mfma_f32_32x32x16_bf16 v[2:17], v[74:77], v[78:81], v[2:17]
	v_mfma_f32_32x32x16_bf16 v[18:33], v[74:77], v[90:93], v[18:33]
	ds_read_b128 v[74:77], v148 offset:32
	ds_read_b128 v[78:81], v149 offset:18464
	ds_read_b128 v[90:93], v149 offset:23072
	s_waitcnt lgkmcnt(1)
	v_mfma_f32_32x32x16_bf16 v[34:49], v[74:77], v[78:81], v[34:49]
	s_waitcnt lgkmcnt(0)
	v_mfma_f32_32x32x16_bf16 v[50:65], v[74:77], v[90:93], v[50:65]
	ds_read_b128 v[74:77], v148 offset:4640
	s_waitcnt lgkmcnt(0)
	v_mfma_f32_32x32x16_bf16 v[2:17], v[74:77], v[78:81], v[2:17]
	v_mfma_f32_32x32x16_bf16 v[18:33], v[74:77], v[90:93], v[18:33]
	ds_read_b128 v[74:77], v148 offset:64
	ds_read_b128 v[78:81], v149 offset:18496
	ds_read_b128 v[90:93], v149 offset:23104
	s_waitcnt lgkmcnt(1)
	v_mfma_f32_32x32x16_bf16 v[34:49], v[74:77], v[78:81], v[34:49]
	s_waitcnt lgkmcnt(0)
	v_mfma_f32_32x32x16_bf16 v[50:65], v[74:77], v[90:93], v[50:65]
	ds_read_b128 v[74:77], v148 offset:4672
	s_waitcnt lgkmcnt(0)
	v_mfma_f32_32x32x16_bf16 v[2:17], v[74:77], v[78:81], v[2:17]
	v_mfma_f32_32x32x16_bf16 v[18:33], v[74:77], v[90:93], v[18:33]
	ds_read_b128 v[74:77], v148 offset:96
	ds_read_b128 v[78:81], v149 offset:18528
	ds_read_b128 v[90:93], v149 offset:23136
	s_waitcnt lgkmcnt(1)
	v_mfma_f32_32x32x16_bf16 v[34:49], v[74:77], v[78:81], v[34:49]
	s_waitcnt lgkmcnt(0)
	v_mfma_f32_32x32x16_bf16 v[50:65], v[74:77], v[90:93], v[50:65]
	ds_read_b128 v[74:77], v148 offset:4704
	s_waitcnt lgkmcnt(0)
	v_mfma_f32_32x32x16_bf16 v[2:17], v[74:77], v[78:81], v[2:17]
	v_mfma_f32_32x32x16_bf16 v[18:33], v[74:77], v[90:93], v[18:33]
	s_nop 0
	s_waitcnt vmcnt(7)
	v_lshlrev_b32_e32 v74, 16, v122
	v_and_b32_e32 v75, 0xffff0000, v122
	v_fmac_f32_e32 v153, v74, v74
	s_waitcnt vmcnt(5)
	v_lshlrev_b32_e32 v74, 16, v106
	v_lshlrev_b32_e32 v76, 16, v123
	v_fmac_f32_e32 v153, v75, v75
	v_and_b32_e32 v75, 0xffff0000, v106
	v_fmac_f32_e32 v154, v74, v74
	s_waitcnt vmcnt(3)
	v_lshlrev_b32_e32 v74, 16, v82
	v_and_b32_e32 v77, 0xffff0000, v123
	v_fmac_f32_e32 v153, v76, v76
	v_lshlrev_b32_e32 v76, 16, v107
	v_fmac_f32_e32 v154, v75, v75
	v_and_b32_e32 v75, 0xffff0000, v82
	v_fmac_f32_e32 v155, v74, v74
	s_waitcnt vmcnt(1)
	v_lshlrev_b32_e32 v74, 16, v66
	v_lshlrev_b32_e32 v78, 16, v124
	v_fmac_f32_e32 v153, v77, v77
	v_and_b32_e32 v77, 0xffff0000, v107
	v_fmac_f32_e32 v154, v76, v76
	v_lshlrev_b32_e32 v76, 16, v83
	v_fmac_f32_e32 v155, v75, v75
	v_and_b32_e32 v75, 0xffff0000, v66
	v_fmac_f32_e32 v156, v74, v74
	v_and_b32_e32 v79, 0xffff0000, v124
	v_fmac_f32_e32 v153, v78, v78
	v_lshlrev_b32_e32 v78, 16, v108
	v_fmac_f32_e32 v154, v77, v77
	v_and_b32_e32 v77, 0xffff0000, v83
	v_fmac_f32_e32 v155, v76, v76
	v_lshlrev_b32_e32 v76, 16, v67
	v_fmac_f32_e32 v156, v75, v75
	v_lshlrev_b32_e32 v80, 16, v125
	v_fmac_f32_e32 v153, v79, v79
	v_and_b32_e32 v79, 0xffff0000, v108
	v_fmac_f32_e32 v154, v78, v78
	v_lshlrev_b32_e32 v78, 16, v84
	v_fmac_f32_e32 v155, v77, v77
	v_and_b32_e32 v77, 0xffff0000, v67
	v_fmac_f32_e32 v156, v76, v76
	v_and_b32_e32 v81, 0xffff0000, v125
	v_fmac_f32_e32 v153, v80, v80
	v_lshlrev_b32_e32 v80, 16, v109
	v_fmac_f32_e32 v154, v79, v79
	v_and_b32_e32 v79, 0xffff0000, v84
	v_fmac_f32_e32 v155, v78, v78
	v_lshlrev_b32_e32 v78, 16, v68
	v_fmac_f32_e32 v156, v77, v77
	v_fmac_f32_e32 v153, v81, v81
	v_and_b32_e32 v81, 0xffff0000, v109
	v_fmac_f32_e32 v154, v80, v80
	v_lshlrev_b32_e32 v80, 16, v85
	v_fmac_f32_e32 v155, v79, v79
	v_and_b32_e32 v79, 0xffff0000, v68
	v_fmac_f32_e32 v156, v78, v78
	v_fmac_f32_e32 v154, v81, v81
	v_and_b32_e32 v81, 0xffff0000, v85
	v_fmac_f32_e32 v155, v80, v80
	v_lshlrev_b32_e32 v80, 16, v69
	v_fmac_f32_e32 v156, v79, v79
	v_fmac_f32_e32 v155, v81, v81
	v_and_b32_e32 v81, 0xffff0000, v69
	v_fmac_f32_e32 v156, v80, v80
	v_fmac_f32_e32 v156, v81, v81
	ds_write_b128 v157, v[122:125] offset:36864
	ds_write_b128 v157, v[126:129] offset:55296
	ds_write_b128 v157, v[106:109] offset:41472
	ds_write_b128 v157, v[110:113] offset:59904
	ds_write_b128 v157, v[82:85] offset:46080
	ds_write_b128 v157, v[86:89] offset:64512
	ds_write_b128 v157, v[66:69] offset:50688
	s_waitcnt vmcnt(0)
	ds_write_b128 v158, v[70:73] offset:64512
	s_waitcnt lgkmcnt(0)
	s_barrier
; #define BLOAD(A_, B_, kt) do { _Pragma("unroll") for (int i = 0; i < 4; ++i) { \
;     A_[i] = *(const u32x4*)((const char*)Ap + (aoff + (unsigned)(32 * i * lda + (kt) * 64) * 2u)); B_[i] = *(const u32x4*)((const char*)Wt + (woff + (unsigned)(32 * i * K + (kt) * 64) * 2u)); } } while (0)
; #define BLOAD(A_, B_, kt) do { _Pragma("unroll") for (int i = 0; i < 4; ++i) { \
;     A_[i] = *(const u32x4*)((const char*)Ap + (aoff + (unsigned)(32 * i * lda + (kt) * 64) * 2u)); B_[i] = *(const u32x4*)((const char*)Wt + (woff + (unsigned)(32 * i * K + (kt) * 64) * 2u)); } } while (0)
; #define BSTORE(A_, B_, buf) do { _Pragma("unroll") for (int i = 0; i < 4; ++i) { \
;     *(u32x4*)&As[(buf) * GBUF + (srow + 32 * i) * LDT + sc8] = A_[i]; \
;     *(u32x4*)&Bs[(buf) * GBUF + (srow + 32 * i) * LDT + sc8] = B_[i]; } } while (0)
; template <bool ROWNORM, int NK>
; DI void gemm_main_bf(const u16* __restrict__ Ap, int lda, const u16* __restrict__ Wt, f32x16 (&acc)[2][2], char* smem, float* rinv_s) {
;     ...
;     BCOMP(1);
;     if (kt + 2 < nk) { BSTORE(a0, b0, 0); if (kt + 4 < nk) BLOAD(a0, b0, kt + 4); }
;     __syncthreads();
;   }
;     ...
;   if constexpr (ROWNORM) {
; #pragma unroll
;     for (int i = 0; i < 4; ++i) {
;       float s = ss[i]; s += __shfl_xor(s, 1); s += __shfl_xor(s, 2); s += __shfl_xor(s, 4);
;       if ((tid & 7) == 0) rinv_s[srow + 32 * i] = rsqrtf(s / (float)K + EPS);
;     }
	s_nop 0
	ds_read_b128 v[66:69], v148 offset:36864
	ds_read_b128 v[70:73], v149 offset:55296
	ds_read_b128 v[74:77], v149 offset:59904
	s_waitcnt lgkmcnt(1)
	v_mfma_f32_32x32x16_bf16 v[34:49], v[66:69], v[70:73], v[34:49]
	s_waitcnt lgkmcnt(0)
	v_mfma_f32_32x32x16_bf16 v[50:65], v[66:69], v[74:77], v[50:65]
	ds_read_b128 v[66:69], v148 offset:41472
	s_waitcnt lgkmcnt(0)
	v_mfma_f32_32x32x16_bf16 v[2:17], v[66:69], v[70:73], v[2:17]
	v_mfma_f32_32x32x16_bf16 v[18:33], v[66:69], v[74:77], v[18:33]
	ds_read_b128 v[66:69], v148 offset:36896
	ds_read_b128 v[70:73], v149 offset:55328
	ds_read_b128 v[74:77], v149 offset:59936
	s_waitcnt lgkmcnt(1)
	v_mfma_f32_32x32x16_bf16 v[34:49], v[66:69], v[70:73], v[34:49]
	s_waitcnt lgkmcnt(0)
	v_mfma_f32_32x32x16_bf16 v[50:65], v[66:69], v[74:77], v[50:65]
	ds_read_b128 v[66:69], v148 offset:41504
	s_waitcnt lgkmcnt(0)
	v_mfma_f32_32x32x16_bf16 v[2:17], v[66:69], v[70:73], v[2:17]
	v_mfma_f32_32x32x16_bf16 v[18:33], v[66:69], v[74:77], v[18:33]
	ds_read_b128 v[66:69], v148 offset:36928
	ds_read_b128 v[70:73], v149 offset:55360
	ds_read_b128 v[74:77], v149 offset:59968
	s_waitcnt lgkmcnt(1)
	v_mfma_f32_32x32x16_bf16 v[34:49], v[66:69], v[70:73], v[34:49]
	s_waitcnt lgkmcnt(0)
	v_mfma_f32_32x32x16_bf16 v[50:65], v[66:69], v[74:77], v[50:65]
	ds_read_b128 v[66:69], v148 offset:41536
	s_waitcnt lgkmcnt(0)
	v_mfma_f32_32x32x16_bf16 v[2:17], v[66:69], v[70:73], v[2:17]
	v_mfma_f32_32x32x16_bf16 v[18:33], v[66:69], v[74:77], v[18:33]
	ds_read_b128 v[66:69], v148 offset:36960
	ds_read_b128 v[70:73], v149 offset:55392
	ds_read_b128 v[74:77], v149 offset:60000
	s_waitcnt lgkmcnt(1)
	v_mfma_f32_32x32x16_bf16 v[34:49], v[66:69], v[70:73], v[34:49]
	s_waitcnt lgkmcnt(0)
	v_mfma_f32_32x32x16_bf16 v[50:65], v[66:69], v[74:77], v[50:65]
	ds_read_b128 v[66:69], v148 offset:41568
	s_waitcnt lgkmcnt(0)
	v_mfma_f32_32x32x16_bf16 v[2:17], v[66:69], v[70:73], v[2:17]
	v_mfma_f32_32x32x16_bf16 v[18:33], v[66:69], v[74:77], v[18:33]
	s_nop 0
	v_cmp_lt_i32_e32 vcc, v200, v194
	v_cmp_eq_u32_e64 s[36:37], 0, v147
	s_nop 0
	v_cndmask_b32_e32 v66, v193, v200, vcc
	v_lshlrev_b32_e32 v66, 2, v66
	ds_bpermute_b32 v69, v66, v153
	v_cmp_lt_i32_e32 vcc, v199, v194
	s_barrier
	s_waitcnt lgkmcnt(0)
	v_cndmask_b32_e32 v67, v193, v199, vcc
	v_lshlrev_b32_e32 v67, 2, v67
	v_add_f32_e32 v69, v153, v69
	ds_bpermute_b32 v70, v67, v69
	v_cmp_lt_i32_e32 vcc, v198, v194
	s_waitcnt lgkmcnt(0)
	v_add_f32_e32 v69, v69, v70
	v_cndmask_b32_e32 v68, v193, v198, vcc
	v_lshlrev_b32_e32 v68, 2, v68
	ds_bpermute_b32 v70, v68, v69
	s_and_saveexec_b64 s[40:41], s[36:37]
	s_cbranch_execz .LBB1_362
	s_waitcnt lgkmcnt(0)
	v_add_f32_e32 v69, v69, v70
	s_mov_b32 s0, 0x43c00000
	v_div_scale_f32 v70, s[34:35], s0, s0, v69
	v_rcp_f32_e32 v71, v70
	v_div_scale_f32 v72, vcc, v69, s0, v69
	v_fma_f32 v73, -v70, v71, 1.0
	v_fmac_f32_e32 v71, v73, v71
	v_mul_f32_e32 v73, v72, v71
	v_fma_f32 v74, -v70, v73, v72
	v_fmac_f32_e32 v73, v74, v71
	v_fma_f32 v70, -v70, v73, v72
	v_div_fmas_f32 v70, v70, v71, v73
	v_div_fixup_f32 v69, v70, s0, v69
	v_add_f32_e32 v69, 0x358637bd, v69
	v_mul_f32_e32 v70, 0x4b800000, v69
	v_cmp_gt_f32_e32 vcc, s39, v69
	s_nop 1
	v_cndmask_b32_e32 v69, v69, v70, vcc
	v_rsq_f32_e32 v69, v69
	s_nop 0
	v_mul_f32_e32 v70, 0x45800000, v69
	v_cndmask_b32_e32 v69, v69, v70, vcc
	v_lshl_add_u32 v70, v0, 2, v201
	ds_write_b32 v70, v69

; DI int TID() { int t = (int)__builtin_amdgcn_workitem_id_x(); asm volatile("" : "+v"(t)); return t; }
; DI int crow(int r, int hi) { return (r & 3) + 8 * (r >> 2) + 4 * hi; }
; DI void acc_to_cs(const f32x16 (&acc)[2][2], float* Cs) {
;   __builtin_amdgcn_s_setprio(2);
;   const int tid = TID(), lane = tid & 63, w = tid >> 6, wm = w >> 1, wn = w & 1, r32 = lane & 31, hi = lane >> 5;
; #pragma unroll
;   for (int mt = 0; mt < 2; ++mt)
; #pragma unroll
;     for (int nt = 0; nt < 2; ++nt)
; #pragma unroll
;       for (int r = 0; r < 16; ++r) Cs[(wm * 64 + mt * 32 + crow(r, hi)) * CSL + wn * 64 + nt * 32 + r32] = acc[mt][nt][r];
;   __syncthreads();
; }
; DI void tile_mla_up(const Params& p, int l, const Chunk& ck, int tile, char* smem) {
;     ...
;     const float rinv = rinv_s[row]; const float* gain = (const float*)(p.ws + OFF_GAINS) + GN_MQ + l * 96;
;     float ssq = 0.f;
;     if (half == 0) {
; #pragma unroll
;       for (int c8 = 0; c8 < 8; ++c8) { cs_ld8(Cs, row, c8 * 8, v);
; #pragma unroll
;         for (int j = 0; j < 8; ++j) ssq += v[j] * v[j]; }
;     } else {
; #pragma unroll
;       for (int c8 = 0; c8 < 4; ++c8) { cs_ld8(Cs, row, 64 + c8 * 8, v);
; #pragma unroll
;         for (int j = 0; j < 8; ++j) ssq += v[j] * v[j]; }
;     }
.LBB1_368:
	s_or_b64 exec, exec, s[40:41]
	s_nop 0
	v_mov_b32_e32 v0, v172
	v_cmp_ne_u32_e32 vcc, 0, v152
	v_lshrrev_b32_e32 v67, 1, v0
	v_and_b32_e32 v67, 0xfffffc0, v67
	s_waitcnt lgkmcnt(0)
	v_lshrrev_b32_e32 v68, 3, v0
	v_and_or_b32 v67, v68, 4, v67
	v_and_b32_e32 v0, 0x5f, v0
	v_mul_lo_u32 v67, v67, s5
	v_lshl_add_u32 v0, v0, 2, v67
	ds_write2_b32 v0, v34, v50 offset1:32
	ds_write2_b32 v0, v35, v51 offset0:132 offset1:164
	v_add_u32_e32 v34, 0x400, v0
	ds_write2_b32 v34, v36, v52 offset0:8 offset1:40
	ds_write2_b32 v34, v37, v53 offset0:140 offset1:172
	v_add_u32_e32 v34, 0x1000, v0
	ds_write2_b32 v34, v38, v54 offset0:32 offset1:64
	ds_write2_b32 v34, v39, v55 offset0:164 offset1:196
	v_add_u32_e32 v34, 0x1400, v0
	ds_write2_b32 v34, v40, v56 offset0:40 offset1:72
	ds_write2_b32 v34, v41, v57 offset0:172 offset1:204
	v_add_u32_e32 v34, 0x2000, v0
	ds_write2_b32 v34, v42, v58 offset0:64 offset1:96
	ds_write2_b32 v34, v43, v59 offset0:196 offset1:228
	v_add_u32_e32 v34, 0x2400, v0
	ds_write2_b32 v34, v44, v60 offset0:72 offset1:104
	ds_write2_b32 v34, v45, v61 offset0:204 offset1:236
	v_add_u32_e32 v34, 0x3000, v0
	ds_write2_b32 v34, v46, v62 offset0:96 offset1:128
	v_add_u32_e32 v34, 0x3200, v0
	ds_write2_b32 v34, v47, v63 offset0:100 offset1:132
	v_add_u32_e32 v34, 0x3400, v0
	ds_write2_b32 v34, v48, v64 offset0:104 offset1:136
	v_add_u32_e32 v34, 0x3600, v0
	ds_write2_b32 v34, v49, v65 offset0:108 offset1:140
	v_add_u32_e32 v34, 0x4000, v0
	ds_write2_b32 v34, v2, v18 offset0:128 offset1:160
	v_add_u32_e32 v2, 0x4400, v0
	ds_write2_b32 v2, v3, v19 offset0:4 offset1:36
	ds_write2_b32 v2, v4, v20 offset0:136 offset1:168
	v_add_u32_e32 v2, 0x4800, v0
	ds_write2_b32 v2, v5, v21 offset0:12 offset1:44
	v_add_u32_e32 v2, 0x5000, v0
	ds_write2_b32 v2, v6, v22 offset0:160 offset1:192
	v_add_u32_e32 v2, 0x5400, v0
	ds_write2_b32 v2, v7, v23 offset0:36 offset1:68
	ds_write2_b32 v2, v8, v24 offset0:168 offset1:200
	v_add_u32_e32 v2, 0x5800, v0
	ds_write2_b32 v2, v9, v25 offset0:44 offset1:76
	v_add_u32_e32 v2, 0x6000, v0
	ds_write2_b32 v2, v10, v26 offset0:192 offset1:224
	v_add_u32_e32 v2, 0x6400, v0
	ds_write2_b32 v2, v11, v27 offset0:68 offset1:100
	ds_write2_b32 v2, v12, v28 offset0:200 offset1:232
	v_add_u32_e32 v2, 0x6800, v0
	ds_write2_b32 v2, v13, v29 offset0:76 offset1:108
	v_add_u32_e32 v2, 0x7200, v0
	ds_write2_b32 v2, v14, v30 offset0:96 offset1:128
	v_add_u32_e32 v2, 0x7400, v0
	ds_write2_b32 v2, v15, v31 offset0:100 offset1:132
	v_add_u32_e32 v2, 0x7600, v0
	v_add_u32_e32 v0, 0x7800, v0
	ds_write2_b32 v0, v17, v33 offset0:108 offset1:140
	v_lshl_add_u32 v0, v151, 2, v201
	ds_write2_b32 v2, v16, v32 offset0:104 offset1:136
	s_waitcnt lgkmcnt(0)
	s_barrier
	ds_read_b32 v6, v0
	v_mul_lo_u32 v8, v151, s5
	v_add_u32_e32 v0, 0x90, v8
	s_and_saveexec_b64 s[34:35], vcc
	s_xor_b64 s[34:35], exec, s[34:35]
	s_cbranch_execz .LBB1_370
	ds_read_b128 v[2:5], v8 offset:256
	v_add_u32_e32 v0, 0x110, v8
	s_waitcnt lgkmcnt(0)
	v_pk_mul_f32 v[2:3], v[2:3], v[2:3]
	s_nop 0
	v_add_f32_e32 v7, v2, v3

; DI RowSS rowss_load(const float* ps, int m0) { const int tid = TID(); const float* q = ps + (size_t)(m0 + (tid >> 1)) * 16 + (tid & 1) * 8; RowSS r; r.a = *(const f32x4*)q; r.b = *(const f32x4*)(q + 4); return r; }
; DI void tile_inproj(const Params& p, int l, const Chunk& ck, int tile, int next, PF& pf, char* smem) {
;   float* Cs = (float*)smem; float* rinv_s = (float*)(smem + SMEM_CS);
;   const int mi = tile & (MTN - 1), nj = tile >> MTS; const int ni = (nj < 45) ? nj : 69; const int m0 = mi * 128;
;   const u16* Ap; const u16* Wt; inproj_ptrs(p, l, tile, Ap, Wt);
;   f32x16 acc[2][2]; zero_acc(acc);
;   const RowSS rss = rowss_load((const float*)(p.ws + OFF_PSIN), m0);
;   gemm_run<16>(pf, Ap, 1024, Wt, acc, smem);
;   if (next >= 0) { const u16* An; const u16* Wn; inproj_ptrs(p, l, next, An, Wn); gemm_issue(pf, An, 1024, Wn, 1024); }
.LBB1_384:
	s_mov_b32 s0, s16
	s_add_i32 s16, s16, s78
	s_cmpk_gt_i32 s16, 0x16ff
	s_cselect_b64 s[28:29], -1, 0
	s_cmpk_lt_i32 s16, 0x1700
	s_cselect_b32 s34, s16, -1
	s_ashr_i32 s0, s0, 7
	s_cmp_lt_i32 s0, 45
	s_cselect_b64 s[36:37], -1, 0
	s_and_b64 s[30:31], s[36:37], exec
	v_mov_b32_e32 v0, v172
	s_cselect_b32 s30, s0, 0x45
	s_and_b32 s79, s75, 0x3f80
	s_and_b32 s0, s43, 0xfe0000
	s_waitcnt lgkmcnt(0)
	v_ashrrev_i32_e32 v2, 1, v0
	v_add_u32_e32 v2, s79, v2
	v_ashrrev_i32_e32 v3, 31, v2
	v_lshlrev_b64 v[2:3], 6, v[2:3]
	v_lshlrev_b32_e32 v0, 5, v0
	v_lshl_add_u64 v[2:3], s[20:21], 0, v[2:3]
	v_and_b32_e32 v0, 32, v0
	v_lshl_add_u64 v[2:3], v[2:3], 0, v[0:1]
	global_load_dwordx4 v[130:133], v[2:3], off offset:16
	global_load_dwordx4 v[134:137], v[2:3], off
	s_lshr_b32 s0, s0, 4
	s_add_u32 s40, s17, s0
	s_addc_u32 s41, s42, 0
	s_ashr_i32 s31, s30, 31
	s_lshl_b64 s[56:57], s[30:31], 18
	s_add_u32 vcc_lo, s52, s56
	s_addc_u32 vcc_hi, s53, s57
	s_nop 0
	s_waitcnt lgkmcnt(0)
	s_cmp_lg_u32 s14, 0
	s_cbranch_scc1 .Linp_pass1
	s_mov_b64 s[48:49], s[40:41]
	s_lshl_b32 s15, s30, 13
	s_add_u32 s50, s52, s15
	s_addc_u32 s51, s53, 0
	s_mov_b32 s13, 0x5a000
	v_and_b32_e32 v144, 63, v172
	v_lshrrev_b32_e32 v145, 6, v172
	v_bfe_u32 v146, v144, 4, 2
	v_lshrrev_b32_e32 v147, 1, v146
	v_xor_b32_e32 v146, v146, v147
	v_and_b32_e32 v146, 1, v146
	v_lshl_or_b32 v146, v146, 1, v147
	v_xor_b32_e32 v146, v146, v144
	v_and_b32_e32 v146, 3, v146
	v_lshlrev_b32_e32 v146, 4, v146
	v_lshrrev_b32_e32 v147, 2, v144
	v_lshl_add_u32 v138, v145, 5, v147
	v_lshl_add_u32 v138, v138, 6, v146
	v_mov_b32_e32 v139, v138
	v_lshl_add_u32 v140, v145, 6, v147
	v_lshl_add_u32 v140, v140, 6, v146
	v_mov_b32_e32 v141, v140
	v_mov_b32_e32 v142, v140
	v_mov_b32_e32 v143, v140
	v_readfirstlane_b32 s46, v145
	s_lshl_b32 s47, s46, 12
	s_lshl_b32 s46, s46, 11
	s_add_u32 s47, s47, 0x2000
	v_bfe_u32 v146, v144, 2, 2
	v_lshrrev_b32_e32 v147, 1, v146
	v_xor_b32_e32 v146, v146, v147
	v_and_b32_e32 v146, 1, v146
	v_lshl_or_b32 v146, v146, 1, v147
	v_lshrrev_b32_e32 v147, 4, v144
	v_xor_b32_e32 v146, v146, v147
	v_lshlrev_b32_e32 v146, 4, v146
	v_and_b32_e32 v144, 15, v144
	v_lshl_add_u32 v144, v144, 6, v146
	v_lshrrev_b32_e32 v146, 1, v145
	v_and_b32_e32 v147, 1, v145
	v_lshl_add_u32 v126, v146, 12, v144
	v_lshl_add_u32 v128, v147, 12, v144
	v_add_u32_e32 v128, 0x2000, v128
	s_cmp_eq_u32 s30, 44
	s_cselect_b32 s15, 1, 0
	s_cmp_ge_u32 s46, 0x1000
	s_cselect_b32 s15, s15, 0
	s_cmp_lg_u32 s15, 0
	s_cbranch_scc0 .Linp_nokr
	s_add_u32 s50, s52, 0x113e000
	s_addc_u32 s51, s53, 0
	s_mov_b32 s13, 0x2000

; DI int TID() { int t = (int)__builtin_amdgcn_workitem_id_x(); asm volatile("" : "+v"(t)); return t; }
; DI void tile_inproj(const Params& p, int l, const Chunk& ck, int tile, int next, PF& pf, char* smem) {
;     ...
;   rowss_finish(rss, rinv_s);
;   acc_to_cs(acc, Cs);
;   const int tid = TID(), row = tid >> 1, half = tid & 1;
;   const int lt = m0 + row; const int S = ck.S; const int bl = lt >> ck.sshift, t = lt & (S - 1);
;   const float rinv = rinv_s[row];
;   float v[8];
;   if (ni < 24 || (ni >= 41 && ni < 45)) {
.Linp_wd:
	s_nop 0
	v_mov_b32_e32 v0, v172
	s_cmp_gt_i32 s30, 23
	v_lshrrev_b32_e32 v131, 1, v0
	v_and_b32_e32 v131, 0xfffffc0, v131
	s_waitcnt lgkmcnt(0)
	v_lshrrev_b32_e32 v132, 3, v0
	v_and_or_b32 v131, v132, 4, v131
	v_and_b32_e32 v0, 0x5f, v0
	v_mul_lo_u32 v131, v131, s5
	v_lshl_add_u32 v0, v0, 2, v131
	v_add_u32_e32 v34, 0x400, v0
	v_add_u32_e32 v34, 0x1000, v0
	v_add_u32_e32 v34, 0x1400, v0
	v_add_u32_e32 v34, 0x2000, v0
	v_add_u32_e32 v34, 0x2400, v0
	v_add_u32_e32 v34, 0x3000, v0
	v_add_u32_e32 v34, 0x3200, v0
	v_add_u32_e32 v34, 0x3400, v0
	v_add_u32_e32 v34, 0x3600, v0
	v_add_u32_e32 v34, 0x4000, v0
	v_add_u32_e32 v2, 0x4400, v0
	v_add_u32_e32 v2, 0x4800, v0
	v_add_u32_e32 v2, 0x5000, v0
	v_add_u32_e32 v2, 0x5400, v0
	v_add_u32_e32 v2, 0x5800, v0
	v_add_u32_e32 v2, 0x6000, v0
	v_add_u32_e32 v2, 0x6400, v0
	v_add_u32_e32 v2, 0x6800, v0
	v_add_u32_e32 v2, 0x7200, v0
	v_add_u32_e32 v2, 0x7400, v0
	v_add_u32_e32 v2, 0x7600, v0
	v_add_u32_e32 v0, 0x7800, v0
	v_mov_b32_e32 v8, v172
	s_waitcnt lgkmcnt(0)
	s_barrier
	s_cselect_b64 s[40:41], -1, 0
	v_ashrrev_i32_e32 v3, 1, v8
	v_lshl_add_u32 v0, v3, 2, v201
	s_cmp_lt_i32 s30, 24
	ds_read_b32 v2, v0
	s_cselect_b64 s[34:35], -1, 0
	s_cmp_gt_i32 s30, 40
	s_cselect_b64 s[56:57], -1, 0
	s_and_b64 s[36:37], s[36:37], s[56:57]
	s_or_b64 s[34:35], s[34:35], s[36:37]
	v_and_b32_e32 v13, 1, v8
	v_add_u32_e32 v4, s79, v3
	s_andn2_b64 vcc, exec, s[34:35]
	s_mov_b64 s[34:35], -1
	s_cbranch_vccnz .LBB1_390
	s_andn2_b64 vcc, exec, s[34:35]
	s_cbranch_vccnz .LBB1_383
	s_branch .LBB1_405

; DI int TID() { int t = (int)__builtin_amdgcn_workitem_id_x(); asm volatile("" : "+v"(t)); return t; }
; DI int crow(int r, int hi) { return (r & 3) + 8 * (r >> 2) + 4 * hi; }
; DI void acc_to_cs(const f32x16 (&acc)[2][2], float* Cs) {
;   __builtin_amdgcn_s_setprio(2);
;   const int tid = TID(), lane = tid & 63, w = tid >> 6, wm = w >> 1, wn = w & 1, r32 = lane & 31, hi = lane >> 5;
; #pragma unroll
;   for (int mt = 0; mt < 2; ++mt)
; #pragma unroll
;     for (int nt = 0; nt < 2; ++nt)
; #pragma unroll
;       for (int r = 0; r < 16; ++r) Cs[(wm * 64 + mt * 32 + crow(r, hi)) * CSL + wn * 64 + nt * 32 + r32] = acc[mt][nt][r];
;   __syncthreads();
; }
; DI void tile_memkv(const Params& p, int l, int tile, char* smem) {
;     ...
;   f32x16 acc[2][2]; zero_acc(acc);
;   gemm_main<true, true>(A, 1024, Wt, 1024, acc, smem, rinv_s);
;   acc_to_cs(acc, Cs);
;   const int tid = TID();
;   if (ni < 4) {
.LBB1_424:
	s_or_b64 exec, exec, s[24:25]
	s_nop 0
	v_mov_b32_e32 v0, v172
	s_cmpk_gt_i32 s2, 0xbf
	s_waitcnt lgkmcnt(0)
	v_lshrrev_b32_e32 v67, 1, v0
	v_and_b32_e32 v67, 0xfffffc0, v67
	v_lshrrev_b32_e32 v68, 3, v0
	v_and_or_b32 v67, v68, 4, v67
	v_and_b32_e32 v0, 0x5f, v0
	v_mul_lo_u32 v67, v67, s5
	v_lshl_add_u32 v0, v0, 2, v67
	ds_write2_b32 v0, v50, v34 offset1:32
	ds_write2_b32 v0, v51, v35 offset0:132 offset1:164
	v_add_u32_e32 v34, 0x400, v0
	ds_write2_b32 v34, v52, v36 offset0:8 offset1:40
	ds_write2_b32 v34, v53, v37 offset0:140 offset1:172
	v_add_u32_e32 v34, 0x1000, v0
	ds_write2_b32 v34, v54, v38 offset0:32 offset1:64
	ds_write2_b32 v34, v55, v39 offset0:164 offset1:196
	v_add_u32_e32 v34, 0x1400, v0
	ds_write2_b32 v34, v56, v40 offset0:40 offset1:72
	ds_write2_b32 v34, v57, v41 offset0:172 offset1:204
	v_add_u32_e32 v34, 0x2000, v0
	ds_write2_b32 v34, v58, v42 offset0:64 offset1:96
	ds_write2_b32 v34, v59, v43 offset0:196 offset1:228
	v_add_u32_e32 v34, 0x2400, v0
	ds_write2_b32 v34, v60, v44 offset0:72 offset1:104
	ds_write2_b32 v34, v61, v45 offset0:204 offset1:236
	v_add_u32_e32 v34, 0x3000, v0
	ds_write2_b32 v34, v62, v46 offset0:96 offset1:128
	v_add_u32_e32 v34, 0x3200, v0
	ds_write2_b32 v34, v63, v47 offset0:100 offset1:132
	v_add_u32_e32 v34, 0x3400, v0
	ds_write2_b32 v34, v64, v48 offset0:104 offset1:136
	v_add_u32_e32 v34, 0x3600, v0
	ds_write2_b32 v34, v65, v49 offset0:108 offset1:140
	v_add_u32_e32 v34, 0x4000, v0
	ds_write2_b32 v34, v18, v2 offset0:128 offset1:160
	v_add_u32_e32 v2, 0x4400, v0
	ds_write2_b32 v2, v19, v3 offset0:4 offset1:36
	ds_write2_b32 v2, v20, v4 offset0:136 offset1:168
	v_add_u32_e32 v2, 0x4800, v0
	ds_write2_b32 v2, v21, v5 offset0:12 offset1:44
	v_add_u32_e32 v2, 0x5000, v0
	ds_write2_b32 v2, v22, v6 offset0:160 offset1:192
	v_add_u32_e32 v2, 0x5400, v0
	ds_write2_b32 v2, v23, v7 offset0:36 offset1:68
	ds_write2_b32 v2, v24, v8 offset0:168 offset1:200
	v_add_u32_e32 v2, 0x5800, v0
	ds_write2_b32 v2, v25, v9 offset0:44 offset1:76
	v_add_u32_e32 v2, 0x6000, v0
	ds_write2_b32 v2, v26, v10 offset0:192 offset1:224
	v_add_u32_e32 v2, 0x6400, v0
	ds_write2_b32 v2, v27, v11 offset0:68 offset1:100
	ds_write2_b32 v2, v28, v12 offset0:200 offset1:232
	v_add_u32_e32 v2, 0x6800, v0
	ds_write2_b32 v2, v29, v13 offset0:76 offset1:108
	v_add_u32_e32 v2, 0x7200, v0
	ds_write2_b32 v2, v30, v14 offset0:96 offset1:128
	v_add_u32_e32 v2, 0x7400, v0
	ds_write2_b32 v2, v31, v15 offset0:100 offset1:132
	v_add_u32_e32 v2, 0x7600, v0
	ds_write2_b32 v2, v32, v16 offset0:104 offset1:136
	v_add_u32_e32 v0, 0x7800, v0
	v_mov_b32_e32 v16, v172
	s_mov_b64 s[24:25], -1
	ds_write2_b32 v0, v33, v17 offset0:108 offset1:140
	s_waitcnt lgkmcnt(0)
	s_barrier
	s_cbranch_scc1 .LBB1_426
	s_andn2_b64 vcc, exec, s[24:25]
	s_cbranch_vccnz .LBB1_413
	s_branch .LBB1_427
